# P11 body rewritten by hand like P9 (one work grab per workgroup, 32-bit offsets, 32 gathers in flight, ids/acts prefetched, permlane-swap cross-group reduction); same f32 FMA order as baseline
# speedup vs baseline: 1.0552x; 1.0233x over previous
; DI unsigned xb_xcc_id() { return (unsigned)__builtin_amdgcn_s_getreg((3 << 11) | 20) & 0xFu; }
; template <class F>
; DI void xcd_queue(unsigned* ctrs, int nchunks, char* smem, F&& f) {
;   const int x0 = (int)(xb_xcc_id() & 7u);
; #pragma unroll 1
;   for (int k = 0; k < 8; ++k) {
;     const int s = (x0 + k) & 7;
;     for (;;) { const int c = grab(ctrs + 64 * s, smem); if (c >= nchunks) break; f(s, c); }
;   }
; DI void phase11(const Params& p, char* smem, int rep) {
;   const unsigned char* V8 = (const unsigned char*)(p.ws + WS_V);
;   const int* IDS = (const int*)(p.ws + WS_IDS); const float* ACT = (const float*)(p.ws + WS_ACT); u16* OUTP = (u16*)(p.ws + WS_OUTP);
;   const int lane = threadIdx.x & 63, w = threadIdx.x >> 6, g = lane >> 4, l15 = lane & 15;
;   const int b5 = (lane >> 5) & 1, b4 = (lane >> 4) & 1;
;   int* lw = (int*)(smem + 16) + w * 256;
;   float* lf = (float*)(lw + 128);
;   xcd_queue((unsigned*)(p.ws + WS_BAR) + CTR_VQ + rep * 8, 512, smem, [&](int s, int c) __attribute__((always_inline)) {
; #pragma unroll 1
;     for (int t = 0; t < 4; ++t) {
;       const int tok = __builtin_amdgcn_readfirstlane(c * 16 + w * 4 + t);
.LBB0_1253:
	s_waitcnt lgkmcnt(0)
	v_and_b32_e32 v1, 63, v0
	v_and_b32_e32 v2, 15, v0
	v_lshlrev_b32_e32 v2, 4, v2
	v_bfe_u32 v3, v0, 4, 2
	v_lshl_add_u32 v4, v3, 2, v2
	v_lshlrev_b32_e32 v4, 1, v4
	v_lshrrev_b32_e32 v6, 6, v0
	v_lshlrev_b32_e32 v6, 10, v6
	v_lshlrev_b32_e32 v5, 7, v0
	v_and_b32_e32 v5, 0x180, v5
	v_and_b32_e32 v7, 60, v0
	v_add3_u32 v5, v6, v5, v7
	v_lshl_add_u32 v6, v3, 7, v6
	v_lshlrev_b32_e32 v3, 2, v1
	v_and_b32_e32 v241, 7, v0
	v_lshlrev_b32_e32 v241, 8, v241
	v_mov_b32_e32 v7, 0
	s_add_u32 s6, s82, 0x16638000
	s_addc_u32 s7, s83, 0
	s_add_u32 s8, s82, 0x16f18000
	s_addc_u32 s9, s83, 0
	s_add_u32 s10, s82, 0x4538000
	s_addc_u32 s11, s83, 0
	s_add_u32 s14, s82, 0xc638000
	s_addc_u32 s15, s83, 0
	s_add_u32 s16, s82, 0x4800
	s_addc_u32 s17, s83, 0
	s_getreg_b32 s13, hwreg(HW_REG_XCC_ID, 0, 4)
	s_and_b32 s13, s13, 7
	s_mov_b32 s18, 0
	s_mov_b32 s50, 8
	s_mov_b32 s52, 0
	s_lshl_b32 s35, s13, 8
	s_add_u32 s26, s16, s35
	s_addc_u32 s27, s17, 0
	v_lshrrev_b32_e32 v9, 6, v0
	v_mov_b32_e32 v240, 8
	v_readfirstlane_b32 s53, v9
	s_cmp_eq_u32 s53, 0
	s_cbranch_scc0 .Lp11_wg_wait
	v_mov_b32_e32 v8, 128
	s_mov_b64 s[28:29], exec
	s_mov_b64 exec, 1
	global_atomic_add v9, v7, v8, s[26:27] sc0
	s_waitcnt vmcnt(0)
	ds_write_b32 v240, v9
	s_mov_b64 exec, s[28:29]
	s_waitcnt lgkmcnt(0)
.Lp11_wg_wait:
	s_barrier
	ds_read_b32 v9, v240
	s_waitcnt lgkmcnt(0)
	v_readfirstlane_b32 s34, v9
	s_nop 1
	s_mul_i32 s35, s53, 32
	s_add_i32 s34, s34, s35
	s_mov_b32 s49, 8
	s_mov_b32 s19, s13
	s_lshl_b32 s35, s19, 8
	s_add_u32 s20, s10, s35
	s_addc_u32 s21, s11, 0
	s_add_u32 s26, s16, s35
	s_addc_u32 s27, s17, 0
	s_lshl_b32 s24, s19, 9
	s_cmp_ge_u32 s34, 8192
	s_cbranch_scc1 .Lp11_peek
	s_branch .Lp11_fill
.Lp11_slice:
	s_add_i32 s19, s13, s18
	s_and_b32 s19, s19, 7
	s_nop 3
	v_readlane_b32 s47, v242, s19
	s_cmp_ge_u32 s47, 8192
	s_cbranch_scc1 .Lp11_slice_next
	s_lshl_b32 s35, s19, 8
	s_add_u32 s20, s10, s35
	s_addc_u32 s21, s11, 0
	s_add_u32 s26, s16, s35
	s_addc_u32 s27, s17, 0
	s_lshl_b32 s24, s19, 9

; DI f2_t cvt8lo(unsigned w) { return __builtin_amdgcn_cvt_pk_f32_fp8(w, false); }
; DI f2_t cvt8hi(unsigned w) { return __builtin_amdgcn_cvt_pk_f32_fp8(w, true); }
; DI void wave_lds_sync() { asm volatile("s_waitcnt lgkmcnt(0)" ::: "memory"); __builtin_amdgcn_wave_barrier(); }
; DI void phase11(const Params& p, char* smem, int rep) {
;     ...
;       const int i0 = IDS[(size_t)tok * 128 + lane], i1 = IDS[(size_t)tok * 128 + 64 + lane];
;       const float a0 = ACT[(size_t)tok * 128 + lane], a1 = ACT[(size_t)tok * 128 + 64 + lane];
;       wave_lds_sync();
;       lw[(lane & 3) * 32 + (lane >> 2)] = i0; lw[(lane & 3) * 32 + 16 + (lane >> 2)] = i1;
;       lf[(lane & 3) * 32 + (lane >> 2)] = a0; lf[(lane & 3) * 32 + 16 + (lane >> 2)] = a1;
;       wave_lds_sync();
;       f2_t o[8];
; #pragma unroll
;       for (int i = 0; i < 8; ++i) o[i] = f2_t{0.f, 0.f};
;       const unsigned char* vb = V8 + s * 256 + l15 * 16;
; #pragma unroll
;       for (int batch = 0; batch < 2; ++batch) {
;         int ida[16]; float aa[16];
; #pragma unroll
;         for (int q = 0; q < 4; ++q) {
;           const int4 v = *(const int4*)(lw + g * 32 + batch * 16 + q * 4); ida[q * 4] = v.x; ida[q * 4 + 1] = v.y; ida[q * 4 + 2] = v.z; ida[q * 4 + 3] = v.w;
;           const float4 f = *(const float4*)(lf + g * 32 + batch * 16 + q * 4); aa[q * 4] = f.x; aa[q * 4 + 1] = f.y; aa[q * 4 + 2] = f.z; aa[q * 4 + 3] = f.w;
;         }
;         u32x4 rows[16];
; #pragma unroll
;         for (int k = 0; k < 16; ++k) rows[k] = *(const u32x4*)(vb + (size_t)ida[k] * 2048);
; #pragma unroll
;         for (int k = 0; k < 16; ++k) {
;           const f2_t a2 = {aa[k], aa[k]};
; #pragma unroll
;           for (int d = 0; d < 4; ++d) { const unsigned ww = rows[k][d]; o[2 * d] += a2 * cvt8lo(ww); o[2 * d + 1] += a2 * cvt8hi(ww); }
.Lp11_fill:
	s_lshl_b32 s47, s34, 9
	s_add_u32 s42, s6, s47
	s_addc_u32 s43, s7, 0
	s_add_u32 s44, s8, s47
	s_addc_u32 s45, s9, 0
	global_load_dword v10, v3, s[42:43]
	global_load_dword v11, v3, s[42:43] offset:256
	global_load_dword v12, v3, s[44:45]
	global_load_dword v13, v3, s[44:45] offset:256
	s_waitcnt vmcnt(0)
	ds_write2_b32 v5, v10, v11 offset0:4 offset1:20
	ds_write2_b32 v5, v12, v13 offset0:132 offset1:148
	s_waitcnt lgkmcnt(0)
	ds_read_b128 v[20:23], v6 offset:16
	ds_read_b128 v[24:27], v6 offset:32
	ds_read_b128 v[28:31], v6 offset:48
	ds_read_b128 v[32:35], v6 offset:64
	ds_read_b128 v[36:39], v6 offset:80
	ds_read_b128 v[40:43], v6 offset:96
	ds_read_b128 v[44:47], v6 offset:112
	ds_read_b128 v[48:51], v6 offset:128
	ds_read_b128 v[52:55], v6 offset:528
	ds_read_b128 v[56:59], v6 offset:544
	ds_read_b128 v[60:63], v6 offset:560
	ds_read_b128 v[64:67], v6 offset:576
	ds_read_b128 v[68:71], v6 offset:592
	ds_read_b128 v[72:75], v6 offset:608
	ds_read_b128 v[76:79], v6 offset:624
	ds_read_b128 v[80:83], v6 offset:640
	s_mov_b32 s48, 0
.Lp11_body:
	s_add_i32 s36, s34, 0
	s_lshl_b32 s46, s36, 12
	s_add_i32 s46, s46, s24
	s_add_i32 s37, s34, 1
	s_lshl_b32 s47, s37, 9
	s_add_u32 s42, s6, s47
	s_addc_u32 s43, s7, 0
	s_add_u32 s44, s8, s47
	s_addc_u32 s45, s9, 0
	global_load_dword v10, v3, s[42:43]
	global_load_dword v11, v3, s[42:43] offset:256
	global_load_dword v12, v3, s[44:45]
	global_load_dword v13, v3, s[44:45] offset:256
	s_waitcnt lgkmcnt(0)
	v_lshl_add_u32 v20, v20, 11, v2
	v_lshl_add_u32 v21, v21, 11, v2
	v_lshl_add_u32 v22, v22, 11, v2
	v_lshl_add_u32 v23, v23, 11, v2
	v_lshl_add_u32 v24, v24, 11, v2
	v_lshl_add_u32 v25, v25, 11, v2
	v_lshl_add_u32 v26, v26, 11, v2
	v_lshl_add_u32 v27, v27, 11, v2
	v_lshl_add_u32 v28, v28, 11, v2
	v_lshl_add_u32 v29, v29, 11, v2
	v_lshl_add_u32 v30, v30, 11, v2
	v_lshl_add_u32 v31, v31, 11, v2
	v_lshl_add_u32 v32, v32, 11, v2
	v_lshl_add_u32 v33, v33, 11, v2
	v_lshl_add_u32 v34, v34, 11, v2
	v_lshl_add_u32 v35, v35, 11, v2
	v_lshl_add_u32 v36, v36, 11, v2
	v_lshl_add_u32 v37, v37, 11, v2
	v_lshl_add_u32 v38, v38, 11, v2
	v_lshl_add_u32 v39, v39, 11, v2
	v_lshl_add_u32 v40, v40, 11, v2
	v_lshl_add_u32 v41, v41, 11, v2
	v_lshl_add_u32 v42, v42, 11, v2
	v_lshl_add_u32 v43, v43, 11, v2
	v_lshl_add_u32 v44, v44, 11, v2
	v_lshl_add_u32 v45, v45, 11, v2
	v_lshl_add_u32 v46, v46, 11, v2
	v_lshl_add_u32 v47, v47, 11, v2
	v_lshl_add_u32 v48, v48, 11, v2
	v_lshl_add_u32 v49, v49, 11, v2
	v_lshl_add_u32 v50, v50, 11, v2
	v_lshl_add_u32 v51, v51, 11, v2
	global_load_dwordx4 v[84:87], v20, s[20:21]
	global_load_dwordx4 v[88:91], v21, s[20:21]
	global_load_dwordx4 v[92:95], v22, s[20:21]
	global_load_dwordx4 v[96:99], v23, s[20:21]
	global_load_dwordx4 v[100:103], v24, s[20:21]
	global_load_dwordx4 v[104:107], v25, s[20:21]
	global_load_dwordx4 v[108:111], v26, s[20:21]
	global_load_dwordx4 v[112:115], v27, s[20:21]
	global_load_dwordx4 v[116:119], v28, s[20:21]
	global_load_dwordx4 v[120:123], v29, s[20:21]
	global_load_dwordx4 v[124:127], v30, s[20:21]
	global_load_dwordx4 v[128:131], v31, s[20:21]
	global_load_dwordx4 v[132:135], v32, s[20:21]
	global_load_dwordx4 v[136:139], v33, s[20:21]
	global_load_dwordx4 v[140:143], v34, s[20:21]
	global_load_dwordx4 v[144:147], v35, s[20:21]
	global_load_dwordx4 v[148:151], v36, s[20:21]
	global_load_dwordx4 v[152:155], v37, s[20:21]
	global_load_dwordx4 v[156:159], v38, s[20:21]
	global_load_dwordx4 v[160:163], v39, s[20:21]
	global_load_dwordx4 v[164:167], v40, s[20:21]
	global_load_dwordx4 v[168:171], v41, s[20:21]
	global_load_dwordx4 v[172:175], v42, s[20:21]
	global_load_dwordx4 v[176:179], v43, s[20:21]
	global_load_dwordx4 v[180:183], v44, s[20:21]
	global_load_dwordx4 v[184:187], v45, s[20:21]
	global_load_dwordx4 v[190:193], v46, s[20:21]
	global_load_dwordx4 v[194:197], v47, s[20:21]
	global_load_dwordx4 v[198:201], v48, s[20:21]
	global_load_dwordx4 v[202:205], v49, s[20:21]
	global_load_dwordx4 v[206:209], v50, s[20:21]
	global_load_dwordx4 v[210:213], v51, s[20:21]
	s_waitcnt vmcnt(31)
	v_cvt_pk_f32_fp8_e32 v[232:233], v84
	v_cvt_pk_f32_fp8_sdwa v[234:235], v84 src0_sel:WORD_1
	v_pk_fma_f32 v[216:217], v[52:53], v[232:233], 0 op_sel_hi:[0,1,0]
	v_pk_fma_f32 v[218:219], v[52:53], v[234:235], 0 op_sel_hi:[0,1,0]
	v_cvt_pk_f32_fp8_e32 v[236:237], v85
	v_cvt_pk_f32_fp8_sdwa v[238:239], v85 src0_sel:WORD_1
	v_pk_fma_f32 v[220:221], v[52:53], v[236:237], 0 op_sel_hi:[0,1,0]
	v_pk_fma_f32 v[222:223], v[52:53], v[238:239], 0 op_sel_hi:[0,1,0]
	v_cvt_pk_f32_fp8_e32 v[232:233], v86
	v_cvt_pk_f32_fp8_sdwa v[234:235], v86 src0_sel:WORD_1
	v_pk_fma_f32 v[224:225], v[52:53], v[232:233], 0 op_sel_hi:[0,1,0]
	v_pk_fma_f32 v[226:227], v[52:53], v[234:235], 0 op_sel_hi:[0,1,0]
	v_cvt_pk_f32_fp8_e32 v[236:237], v87
	v_cvt_pk_f32_fp8_sdwa v[238:239], v87 src0_sel:WORD_1
	v_pk_fma_f32 v[228:229], v[52:53], v[236:237], 0 op_sel_hi:[0,1,0]
	v_pk_fma_f32 v[230:231], v[52:53], v[238:239], 0 op_sel_hi:[0,1,0]
	s_waitcnt vmcnt(30)
	v_cvt_pk_f32_fp8_e32 v[232:233], v88
	v_cvt_pk_f32_fp8_sdwa v[234:235], v88 src0_sel:WORD_1
	v_pk_fma_f32 v[216:217], v[52:53], v[232:233], v[216:217] op_sel:[1,0,0]
	v_pk_fma_f32 v[218:219], v[52:53], v[234:235], v[218:219] op_sel:[1,0,0]
	v_cvt_pk_f32_fp8_e32 v[236:237], v89
	v_cvt_pk_f32_fp8_sdwa v[238:239], v89 src0_sel:WORD_1
	v_pk_fma_f32 v[220:221], v[52:53], v[236:237], v[220:221] op_sel:[1,0,0]
	v_pk_fma_f32 v[222:223], v[52:53], v[238:239], v[222:223] op_sel:[1,0,0]
	v_cvt_pk_f32_fp8_e32 v[232:233], v90
	v_cvt_pk_f32_fp8_sdwa v[234:235], v90 src0_sel:WORD_1
	v_pk_fma_f32 v[224:225], v[52:53], v[232:233], v[224:225] op_sel:[1,0,0]
	v_pk_fma_f32 v[226:227], v[52:53], v[234:235], v[226:227] op_sel:[1,0,0]
	v_cvt_pk_f32_fp8_e32 v[236:237], v91
	v_cvt_pk_f32_fp8_sdwa v[238:239], v91 src0_sel:WORD_1
	v_pk_fma_f32 v[228:229], v[52:53], v[236:237], v[228:229] op_sel:[1,0,0]
	v_pk_fma_f32 v[230:231], v[52:53], v[238:239], v[230:231] op_sel:[1,0,0]
	s_waitcnt vmcnt(29)
; DI f2_t cvt8lo(unsigned w) { return __builtin_amdgcn_cvt_pk_f32_fp8(w, false); }
; DI f2_t cvt8hi(unsigned w) { return __builtin_amdgcn_cvt_pk_f32_fp8(w, true); }
; DI void phase11(const Params& p, char* smem, int rep) {
;     ...
;         for (int k = 0; k < 16; ++k) rows[k] = *(const u32x4*)(vb + (size_t)ida[k] * 2048);
; #pragma unroll
;         for (int k = 0; k < 16; ++k) {
;           const f2_t a2 = {aa[k], aa[k]};
; #pragma unroll
;           for (int d = 0; d < 4; ++d) { const unsigned ww = rows[k][d]; o[2 * d] += a2 * cvt8lo(ww); o[2 * d + 1] += a2 * cvt8hi(ww); }
	v_cvt_pk_f32_fp8_e32 v[232:233], v92
	v_cvt_pk_f32_fp8_sdwa v[234:235], v92 src0_sel:WORD_1
	v_pk_fma_f32 v[216:217], v[54:55], v[232:233], v[216:217] op_sel_hi:[0,1,1]
	v_pk_fma_f32 v[218:219], v[54:55], v[234:235], v[218:219] op_sel_hi:[0,1,1]
	v_cvt_pk_f32_fp8_e32 v[236:237], v93
	v_cvt_pk_f32_fp8_sdwa v[238:239], v93 src0_sel:WORD_1
	v_pk_fma_f32 v[220:221], v[54:55], v[236:237], v[220:221] op_sel_hi:[0,1,1]
	v_pk_fma_f32 v[222:223], v[54:55], v[238:239], v[222:223] op_sel_hi:[0,1,1]
	v_cvt_pk_f32_fp8_e32 v[232:233], v94
	v_cvt_pk_f32_fp8_sdwa v[234:235], v94 src0_sel:WORD_1
	v_pk_fma_f32 v[224:225], v[54:55], v[232:233], v[224:225] op_sel_hi:[0,1,1]
	v_pk_fma_f32 v[226:227], v[54:55], v[234:235], v[226:227] op_sel_hi:[0,1,1]
	v_cvt_pk_f32_fp8_e32 v[236:237], v95
	v_cvt_pk_f32_fp8_sdwa v[238:239], v95 src0_sel:WORD_1
	v_pk_fma_f32 v[228:229], v[54:55], v[236:237], v[228:229] op_sel_hi:[0,1,1]
	v_pk_fma_f32 v[230:231], v[54:55], v[238:239], v[230:231] op_sel_hi:[0,1,1]
	s_waitcnt vmcnt(28)
	v_cvt_pk_f32_fp8_e32 v[232:233], v96
	v_cvt_pk_f32_fp8_sdwa v[234:235], v96 src0_sel:WORD_1
	v_pk_fma_f32 v[216:217], v[54:55], v[232:233], v[216:217] op_sel:[1,0,0]
	v_pk_fma_f32 v[218:219], v[54:55], v[234:235], v[218:219] op_sel:[1,0,0]
	v_cvt_pk_f32_fp8_e32 v[236:237], v97
	v_cvt_pk_f32_fp8_sdwa v[238:239], v97 src0_sel:WORD_1
	v_pk_fma_f32 v[220:221], v[54:55], v[236:237], v[220:221] op_sel:[1,0,0]
	v_pk_fma_f32 v[222:223], v[54:55], v[238:239], v[222:223] op_sel:[1,0,0]
	v_cvt_pk_f32_fp8_e32 v[232:233], v98
	v_cvt_pk_f32_fp8_sdwa v[234:235], v98 src0_sel:WORD_1
	v_pk_fma_f32 v[224:225], v[54:55], v[232:233], v[224:225] op_sel:[1,0,0]
	v_pk_fma_f32 v[226:227], v[54:55], v[234:235], v[226:227] op_sel:[1,0,0]
	v_cvt_pk_f32_fp8_e32 v[236:237], v99
	v_cvt_pk_f32_fp8_sdwa v[238:239], v99 src0_sel:WORD_1
	v_pk_fma_f32 v[228:229], v[54:55], v[236:237], v[228:229] op_sel:[1,0,0]
	v_pk_fma_f32 v[230:231], v[54:55], v[238:239], v[230:231] op_sel:[1,0,0]
	s_waitcnt vmcnt(27)
	v_cvt_pk_f32_fp8_e32 v[232:233], v100
	v_cvt_pk_f32_fp8_sdwa v[234:235], v100 src0_sel:WORD_1
	v_pk_fma_f32 v[216:217], v[56:57], v[232:233], v[216:217] op_sel_hi:[0,1,1]
	v_pk_fma_f32 v[218:219], v[56:57], v[234:235], v[218:219] op_sel_hi:[0,1,1]
	v_cvt_pk_f32_fp8_e32 v[236:237], v101
	v_cvt_pk_f32_fp8_sdwa v[238:239], v101 src0_sel:WORD_1
	v_pk_fma_f32 v[220:221], v[56:57], v[236:237], v[220:221] op_sel_hi:[0,1,1]
	v_pk_fma_f32 v[222:223], v[56:57], v[238:239], v[222:223] op_sel_hi:[0,1,1]
	v_cvt_pk_f32_fp8_e32 v[232:233], v102
	v_cvt_pk_f32_fp8_sdwa v[234:235], v102 src0_sel:WORD_1
	v_pk_fma_f32 v[224:225], v[56:57], v[232:233], v[224:225] op_sel_hi:[0,1,1]
	v_pk_fma_f32 v[226:227], v[56:57], v[234:235], v[226:227] op_sel_hi:[0,1,1]
	v_cvt_pk_f32_fp8_e32 v[236:237], v103
	v_cvt_pk_f32_fp8_sdwa v[238:239], v103 src0_sel:WORD_1
	v_pk_fma_f32 v[228:229], v[56:57], v[236:237], v[228:229] op_sel_hi:[0,1,1]
	v_pk_fma_f32 v[230:231], v[56:57], v[238:239], v[230:231] op_sel_hi:[0,1,1]
	s_waitcnt vmcnt(26)
	v_cvt_pk_f32_fp8_e32 v[232:233], v104
	v_cvt_pk_f32_fp8_sdwa v[234:235], v104 src0_sel:WORD_1
	v_pk_fma_f32 v[216:217], v[56:57], v[232:233], v[216:217] op_sel:[1,0,0]
	v_pk_fma_f32 v[218:219], v[56:57], v[234:235], v[218:219] op_sel:[1,0,0]
	v_cvt_pk_f32_fp8_e32 v[236:237], v105
	v_cvt_pk_f32_fp8_sdwa v[238:239], v105 src0_sel:WORD_1
	v_pk_fma_f32 v[220:221], v[56:57], v[236:237], v[220:221] op_sel:[1,0,0]
	v_pk_fma_f32 v[222:223], v[56:57], v[238:239], v[222:223] op_sel:[1,0,0]
	v_cvt_pk_f32_fp8_e32 v[232:233], v106
	v_cvt_pk_f32_fp8_sdwa v[234:235], v106 src0_sel:WORD_1
	v_pk_fma_f32 v[224:225], v[56:57], v[232:233], v[224:225] op_sel:[1,0,0]
	v_pk_fma_f32 v[226:227], v[56:57], v[234:235], v[226:227] op_sel:[1,0,0]
	v_cvt_pk_f32_fp8_e32 v[236:237], v107
	v_cvt_pk_f32_fp8_sdwa v[238:239], v107 src0_sel:WORD_1
	v_pk_fma_f32 v[228:229], v[56:57], v[236:237], v[228:229] op_sel:[1,0,0]
	v_pk_fma_f32 v[230:231], v[56:57], v[238:239], v[230:231] op_sel:[1,0,0]
	s_waitcnt vmcnt(25)
	v_cvt_pk_f32_fp8_e32 v[232:233], v108
	v_cvt_pk_f32_fp8_sdwa v[234:235], v108 src0_sel:WORD_1
	v_pk_fma_f32 v[216:217], v[58:59], v[232:233], v[216:217] op_sel_hi:[0,1,1]
	v_pk_fma_f32 v[218:219], v[58:59], v[234:235], v[218:219] op_sel_hi:[0,1,1]
	v_cvt_pk_f32_fp8_e32 v[236:237], v109
	v_cvt_pk_f32_fp8_sdwa v[238:239], v109 src0_sel:WORD_1
	v_pk_fma_f32 v[220:221], v[58:59], v[236:237], v[220:221] op_sel_hi:[0,1,1]
	v_pk_fma_f32 v[222:223], v[58:59], v[238:239], v[222:223] op_sel_hi:[0,1,1]
	v_cvt_pk_f32_fp8_e32 v[232:233], v110
	v_cvt_pk_f32_fp8_sdwa v[234:235], v110 src0_sel:WORD_1
	v_pk_fma_f32 v[224:225], v[58:59], v[232:233], v[224:225] op_sel_hi:[0,1,1]
	v_pk_fma_f32 v[226:227], v[58:59], v[234:235], v[226:227] op_sel_hi:[0,1,1]
	v_cvt_pk_f32_fp8_e32 v[236:237], v111
	v_cvt_pk_f32_fp8_sdwa v[238:239], v111 src0_sel:WORD_1
	v_pk_fma_f32 v[228:229], v[58:59], v[236:237], v[228:229] op_sel_hi:[0,1,1]
	v_pk_fma_f32 v[230:231], v[58:59], v[238:239], v[230:231] op_sel_hi:[0,1,1]
	s_waitcnt vmcnt(24)
	v_cvt_pk_f32_fp8_e32 v[232:233], v112
	v_cvt_pk_f32_fp8_sdwa v[234:235], v112 src0_sel:WORD_1
	v_pk_fma_f32 v[216:217], v[58:59], v[232:233], v[216:217] op_sel:[1,0,0]
	v_pk_fma_f32 v[218:219], v[58:59], v[234:235], v[218:219] op_sel:[1,0,0]
	v_cvt_pk_f32_fp8_e32 v[236:237], v113
	v_cvt_pk_f32_fp8_sdwa v[238:239], v113 src0_sel:WORD_1
	v_pk_fma_f32 v[220:221], v[58:59], v[236:237], v[220:221] op_sel:[1,0,0]
	v_pk_fma_f32 v[222:223], v[58:59], v[238:239], v[222:223] op_sel:[1,0,0]
	v_cvt_pk_f32_fp8_e32 v[232:233], v114
	v_cvt_pk_f32_fp8_sdwa v[234:235], v114 src0_sel:WORD_1
	v_pk_fma_f32 v[224:225], v[58:59], v[232:233], v[224:225] op_sel:[1,0,0]
	v_pk_fma_f32 v[226:227], v[58:59], v[234:235], v[226:227] op_sel:[1,0,0]
	v_cvt_pk_f32_fp8_e32 v[236:237], v115
	v_cvt_pk_f32_fp8_sdwa v[238:239], v115 src0_sel:WORD_1
	v_pk_fma_f32 v[228:229], v[58:59], v[236:237], v[228:229] op_sel:[1,0,0]
	v_pk_fma_f32 v[230:231], v[58:59], v[238:239], v[230:231] op_sel:[1,0,0]
	s_waitcnt vmcnt(23)
; DI f2_t cvt8lo(unsigned w) { return __builtin_amdgcn_cvt_pk_f32_fp8(w, false); }
; DI f2_t cvt8hi(unsigned w) { return __builtin_amdgcn_cvt_pk_f32_fp8(w, true); }
; DI void phase11(const Params& p, char* smem, int rep) {
;     ...
;         for (int k = 0; k < 16; ++k) rows[k] = *(const u32x4*)(vb + (size_t)ida[k] * 2048);
; #pragma unroll
;         for (int k = 0; k < 16; ++k) {
;           const f2_t a2 = {aa[k], aa[k]};
; #pragma unroll
;           for (int d = 0; d < 4; ++d) { const unsigned ww = rows[k][d]; o[2 * d] += a2 * cvt8lo(ww); o[2 * d + 1] += a2 * cvt8hi(ww); }
	v_cvt_pk_f32_fp8_e32 v[232:233], v116
	v_cvt_pk_f32_fp8_sdwa v[234:235], v116 src0_sel:WORD_1
	v_pk_fma_f32 v[216:217], v[60:61], v[232:233], v[216:217] op_sel_hi:[0,1,1]
	v_pk_fma_f32 v[218:219], v[60:61], v[234:235], v[218:219] op_sel_hi:[0,1,1]
	v_cvt_pk_f32_fp8_e32 v[236:237], v117
	v_cvt_pk_f32_fp8_sdwa v[238:239], v117 src0_sel:WORD_1
	v_pk_fma_f32 v[220:221], v[60:61], v[236:237], v[220:221] op_sel_hi:[0,1,1]
	v_pk_fma_f32 v[222:223], v[60:61], v[238:239], v[222:223] op_sel_hi:[0,1,1]
	v_cvt_pk_f32_fp8_e32 v[232:233], v118
	v_cvt_pk_f32_fp8_sdwa v[234:235], v118 src0_sel:WORD_1
	v_pk_fma_f32 v[224:225], v[60:61], v[232:233], v[224:225] op_sel_hi:[0,1,1]
	v_pk_fma_f32 v[226:227], v[60:61], v[234:235], v[226:227] op_sel_hi:[0,1,1]
	v_cvt_pk_f32_fp8_e32 v[236:237], v119
	v_cvt_pk_f32_fp8_sdwa v[238:239], v119 src0_sel:WORD_1
	v_pk_fma_f32 v[228:229], v[60:61], v[236:237], v[228:229] op_sel_hi:[0,1,1]
	v_pk_fma_f32 v[230:231], v[60:61], v[238:239], v[230:231] op_sel_hi:[0,1,1]
	s_waitcnt vmcnt(22)
	v_cvt_pk_f32_fp8_e32 v[232:233], v120
	v_cvt_pk_f32_fp8_sdwa v[234:235], v120 src0_sel:WORD_1
	v_pk_fma_f32 v[216:217], v[60:61], v[232:233], v[216:217] op_sel:[1,0,0]
	v_pk_fma_f32 v[218:219], v[60:61], v[234:235], v[218:219] op_sel:[1,0,0]
	v_cvt_pk_f32_fp8_e32 v[236:237], v121
	v_cvt_pk_f32_fp8_sdwa v[238:239], v121 src0_sel:WORD_1
	v_pk_fma_f32 v[220:221], v[60:61], v[236:237], v[220:221] op_sel:[1,0,0]
	v_pk_fma_f32 v[222:223], v[60:61], v[238:239], v[222:223] op_sel:[1,0,0]
	v_cvt_pk_f32_fp8_e32 v[232:233], v122
	v_cvt_pk_f32_fp8_sdwa v[234:235], v122 src0_sel:WORD_1
	v_pk_fma_f32 v[224:225], v[60:61], v[232:233], v[224:225] op_sel:[1,0,0]
	v_pk_fma_f32 v[226:227], v[60:61], v[234:235], v[226:227] op_sel:[1,0,0]
	v_cvt_pk_f32_fp8_e32 v[236:237], v123
	v_cvt_pk_f32_fp8_sdwa v[238:239], v123 src0_sel:WORD_1
	v_pk_fma_f32 v[228:229], v[60:61], v[236:237], v[228:229] op_sel:[1,0,0]
	v_pk_fma_f32 v[230:231], v[60:61], v[238:239], v[230:231] op_sel:[1,0,0]
	s_waitcnt vmcnt(21)
	v_cvt_pk_f32_fp8_e32 v[232:233], v124
	v_cvt_pk_f32_fp8_sdwa v[234:235], v124 src0_sel:WORD_1
	v_pk_fma_f32 v[216:217], v[62:63], v[232:233], v[216:217] op_sel_hi:[0,1,1]
	v_pk_fma_f32 v[218:219], v[62:63], v[234:235], v[218:219] op_sel_hi:[0,1,1]
	v_cvt_pk_f32_fp8_e32 v[236:237], v125
	v_cvt_pk_f32_fp8_sdwa v[238:239], v125 src0_sel:WORD_1
	v_pk_fma_f32 v[220:221], v[62:63], v[236:237], v[220:221] op_sel_hi:[0,1,1]
	v_pk_fma_f32 v[222:223], v[62:63], v[238:239], v[222:223] op_sel_hi:[0,1,1]
	v_cvt_pk_f32_fp8_e32 v[232:233], v126
	v_cvt_pk_f32_fp8_sdwa v[234:235], v126 src0_sel:WORD_1
	v_pk_fma_f32 v[224:225], v[62:63], v[232:233], v[224:225] op_sel_hi:[0,1,1]
	v_pk_fma_f32 v[226:227], v[62:63], v[234:235], v[226:227] op_sel_hi:[0,1,1]
	v_cvt_pk_f32_fp8_e32 v[236:237], v127
	v_cvt_pk_f32_fp8_sdwa v[238:239], v127 src0_sel:WORD_1
	v_pk_fma_f32 v[228:229], v[62:63], v[236:237], v[228:229] op_sel_hi:[0,1,1]
	v_pk_fma_f32 v[230:231], v[62:63], v[238:239], v[230:231] op_sel_hi:[0,1,1]
	s_waitcnt vmcnt(20)
	v_cvt_pk_f32_fp8_e32 v[232:233], v128
	v_cvt_pk_f32_fp8_sdwa v[234:235], v128 src0_sel:WORD_1
	v_pk_fma_f32 v[216:217], v[62:63], v[232:233], v[216:217] op_sel:[1,0,0]
	v_pk_fma_f32 v[218:219], v[62:63], v[234:235], v[218:219] op_sel:[1,0,0]
	v_cvt_pk_f32_fp8_e32 v[236:237], v129
	v_cvt_pk_f32_fp8_sdwa v[238:239], v129 src0_sel:WORD_1
	v_pk_fma_f32 v[220:221], v[62:63], v[236:237], v[220:221] op_sel:[1,0,0]
	v_pk_fma_f32 v[222:223], v[62:63], v[238:239], v[222:223] op_sel:[1,0,0]
	v_cvt_pk_f32_fp8_e32 v[232:233], v130
	v_cvt_pk_f32_fp8_sdwa v[234:235], v130 src0_sel:WORD_1
	v_pk_fma_f32 v[224:225], v[62:63], v[232:233], v[224:225] op_sel:[1,0,0]
	v_pk_fma_f32 v[226:227], v[62:63], v[234:235], v[226:227] op_sel:[1,0,0]
	v_cvt_pk_f32_fp8_e32 v[236:237], v131
	v_cvt_pk_f32_fp8_sdwa v[238:239], v131 src0_sel:WORD_1
	v_pk_fma_f32 v[228:229], v[62:63], v[236:237], v[228:229] op_sel:[1,0,0]
	v_pk_fma_f32 v[230:231], v[62:63], v[238:239], v[230:231] op_sel:[1,0,0]
	s_waitcnt vmcnt(19)
	v_cvt_pk_f32_fp8_e32 v[232:233], v132
	v_cvt_pk_f32_fp8_sdwa v[234:235], v132 src0_sel:WORD_1
	v_pk_fma_f32 v[216:217], v[64:65], v[232:233], v[216:217] op_sel_hi:[0,1,1]
	v_pk_fma_f32 v[218:219], v[64:65], v[234:235], v[218:219] op_sel_hi:[0,1,1]
	v_cvt_pk_f32_fp8_e32 v[236:237], v133
	v_cvt_pk_f32_fp8_sdwa v[238:239], v133 src0_sel:WORD_1
	v_pk_fma_f32 v[220:221], v[64:65], v[236:237], v[220:221] op_sel_hi:[0,1,1]
	v_pk_fma_f32 v[222:223], v[64:65], v[238:239], v[222:223] op_sel_hi:[0,1,1]
	v_cvt_pk_f32_fp8_e32 v[232:233], v134
	v_cvt_pk_f32_fp8_sdwa v[234:235], v134 src0_sel:WORD_1
	v_pk_fma_f32 v[224:225], v[64:65], v[232:233], v[224:225] op_sel_hi:[0,1,1]
	v_pk_fma_f32 v[226:227], v[64:65], v[234:235], v[226:227] op_sel_hi:[0,1,1]
	v_cvt_pk_f32_fp8_e32 v[236:237], v135
	v_cvt_pk_f32_fp8_sdwa v[238:239], v135 src0_sel:WORD_1
	v_pk_fma_f32 v[228:229], v[64:65], v[236:237], v[228:229] op_sel_hi:[0,1,1]
	v_pk_fma_f32 v[230:231], v[64:65], v[238:239], v[230:231] op_sel_hi:[0,1,1]
	s_waitcnt vmcnt(18)
	v_cvt_pk_f32_fp8_e32 v[232:233], v136
	v_cvt_pk_f32_fp8_sdwa v[234:235], v136 src0_sel:WORD_1
	v_pk_fma_f32 v[216:217], v[64:65], v[232:233], v[216:217] op_sel:[1,0,0]
	v_pk_fma_f32 v[218:219], v[64:65], v[234:235], v[218:219] op_sel:[1,0,0]
	v_cvt_pk_f32_fp8_e32 v[236:237], v137
	v_cvt_pk_f32_fp8_sdwa v[238:239], v137 src0_sel:WORD_1
	v_pk_fma_f32 v[220:221], v[64:65], v[236:237], v[220:221] op_sel:[1,0,0]
	v_pk_fma_f32 v[222:223], v[64:65], v[238:239], v[222:223] op_sel:[1,0,0]
	v_cvt_pk_f32_fp8_e32 v[232:233], v138
	v_cvt_pk_f32_fp8_sdwa v[234:235], v138 src0_sel:WORD_1
	v_pk_fma_f32 v[224:225], v[64:65], v[232:233], v[224:225] op_sel:[1,0,0]
	v_pk_fma_f32 v[226:227], v[64:65], v[234:235], v[226:227] op_sel:[1,0,0]
	v_cvt_pk_f32_fp8_e32 v[236:237], v139
	v_cvt_pk_f32_fp8_sdwa v[238:239], v139 src0_sel:WORD_1
	v_pk_fma_f32 v[228:229], v[64:65], v[236:237], v[228:229] op_sel:[1,0,0]
	v_pk_fma_f32 v[230:231], v[64:65], v[238:239], v[230:231] op_sel:[1,0,0]
	s_waitcnt vmcnt(17)
; DI f2_t cvt8lo(unsigned w) { return __builtin_amdgcn_cvt_pk_f32_fp8(w, false); }
; DI f2_t cvt8hi(unsigned w) { return __builtin_amdgcn_cvt_pk_f32_fp8(w, true); }
; DI void wave_lds_sync() { asm volatile("s_waitcnt lgkmcnt(0)" ::: "memory"); __builtin_amdgcn_wave_barrier(); }
; DI void phase11(const Params& p, char* smem, int rep) {
;     ...
;       wave_lds_sync();
;       lw[(lane & 3) * 32 + (lane >> 2)] = i0; lw[(lane & 3) * 32 + 16 + (lane >> 2)] = i1;
;       lf[(lane & 3) * 32 + (lane >> 2)] = a0; lf[(lane & 3) * 32 + 16 + (lane >> 2)] = a1;
;       wave_lds_sync();
;     ...
;         for (int k = 0; k < 16; ++k) rows[k] = *(const u32x4*)(vb + (size_t)ida[k] * 2048);
; #pragma unroll
;         for (int k = 0; k < 16; ++k) {
;           const f2_t a2 = {aa[k], aa[k]};
; #pragma unroll
;           for (int d = 0; d < 4; ++d) { const unsigned ww = rows[k][d]; o[2 * d] += a2 * cvt8lo(ww); o[2 * d + 1] += a2 * cvt8hi(ww); }
	v_cvt_pk_f32_fp8_e32 v[232:233], v140
	v_cvt_pk_f32_fp8_sdwa v[234:235], v140 src0_sel:WORD_1
	v_pk_fma_f32 v[216:217], v[66:67], v[232:233], v[216:217] op_sel_hi:[0,1,1]
	v_pk_fma_f32 v[218:219], v[66:67], v[234:235], v[218:219] op_sel_hi:[0,1,1]
	v_cvt_pk_f32_fp8_e32 v[236:237], v141
	v_cvt_pk_f32_fp8_sdwa v[238:239], v141 src0_sel:WORD_1
	v_pk_fma_f32 v[220:221], v[66:67], v[236:237], v[220:221] op_sel_hi:[0,1,1]
	v_pk_fma_f32 v[222:223], v[66:67], v[238:239], v[222:223] op_sel_hi:[0,1,1]
	v_cvt_pk_f32_fp8_e32 v[232:233], v142
	v_cvt_pk_f32_fp8_sdwa v[234:235], v142 src0_sel:WORD_1
	v_pk_fma_f32 v[224:225], v[66:67], v[232:233], v[224:225] op_sel_hi:[0,1,1]
	v_pk_fma_f32 v[226:227], v[66:67], v[234:235], v[226:227] op_sel_hi:[0,1,1]
	v_cvt_pk_f32_fp8_e32 v[236:237], v143
	v_cvt_pk_f32_fp8_sdwa v[238:239], v143 src0_sel:WORD_1
	v_pk_fma_f32 v[228:229], v[66:67], v[236:237], v[228:229] op_sel_hi:[0,1,1]
	v_pk_fma_f32 v[230:231], v[66:67], v[238:239], v[230:231] op_sel_hi:[0,1,1]
	s_waitcnt vmcnt(16)
	v_cvt_pk_f32_fp8_e32 v[232:233], v144
	v_cvt_pk_f32_fp8_sdwa v[234:235], v144 src0_sel:WORD_1
	v_pk_fma_f32 v[216:217], v[66:67], v[232:233], v[216:217] op_sel:[1,0,0]
	v_pk_fma_f32 v[218:219], v[66:67], v[234:235], v[218:219] op_sel:[1,0,0]
	v_cvt_pk_f32_fp8_e32 v[236:237], v145
	v_cvt_pk_f32_fp8_sdwa v[238:239], v145 src0_sel:WORD_1
	v_pk_fma_f32 v[220:221], v[66:67], v[236:237], v[220:221] op_sel:[1,0,0]
	v_pk_fma_f32 v[222:223], v[66:67], v[238:239], v[222:223] op_sel:[1,0,0]
	v_cvt_pk_f32_fp8_e32 v[232:233], v146
	v_cvt_pk_f32_fp8_sdwa v[234:235], v146 src0_sel:WORD_1
	v_pk_fma_f32 v[224:225], v[66:67], v[232:233], v[224:225] op_sel:[1,0,0]
	v_pk_fma_f32 v[226:227], v[66:67], v[234:235], v[226:227] op_sel:[1,0,0]
	v_cvt_pk_f32_fp8_e32 v[236:237], v147
	v_cvt_pk_f32_fp8_sdwa v[238:239], v147 src0_sel:WORD_1
	v_pk_fma_f32 v[228:229], v[66:67], v[236:237], v[228:229] op_sel:[1,0,0]
	v_pk_fma_f32 v[230:231], v[66:67], v[238:239], v[230:231] op_sel:[1,0,0]
	ds_write2_b32 v5, v10, v11 offset0:4 offset1:20
	ds_write2_b32 v5, v12, v13 offset0:132 offset1:148
	s_waitcnt lgkmcnt(0)
	ds_read_b128 v[20:23], v6 offset:16
	ds_read_b128 v[24:27], v6 offset:32
	ds_read_b128 v[28:31], v6 offset:48
	ds_read_b128 v[32:35], v6 offset:64
	ds_read_b128 v[36:39], v6 offset:80
	ds_read_b128 v[40:43], v6 offset:96
	ds_read_b128 v[44:47], v6 offset:112
	ds_read_b128 v[48:51], v6 offset:128
	s_waitcnt vmcnt(15)
	v_cvt_pk_f32_fp8_e32 v[232:233], v148
	v_cvt_pk_f32_fp8_sdwa v[234:235], v148 src0_sel:WORD_1
	v_pk_fma_f32 v[216:217], v[68:69], v[232:233], v[216:217] op_sel_hi:[0,1,1]
	v_pk_fma_f32 v[218:219], v[68:69], v[234:235], v[218:219] op_sel_hi:[0,1,1]
	v_cvt_pk_f32_fp8_e32 v[236:237], v149
	v_cvt_pk_f32_fp8_sdwa v[238:239], v149 src0_sel:WORD_1
	v_pk_fma_f32 v[220:221], v[68:69], v[236:237], v[220:221] op_sel_hi:[0,1,1]
	v_pk_fma_f32 v[222:223], v[68:69], v[238:239], v[222:223] op_sel_hi:[0,1,1]
	v_cvt_pk_f32_fp8_e32 v[232:233], v150
	v_cvt_pk_f32_fp8_sdwa v[234:235], v150 src0_sel:WORD_1
	v_pk_fma_f32 v[224:225], v[68:69], v[232:233], v[224:225] op_sel_hi:[0,1,1]
	v_pk_fma_f32 v[226:227], v[68:69], v[234:235], v[226:227] op_sel_hi:[0,1,1]
	v_cvt_pk_f32_fp8_e32 v[236:237], v151
	v_cvt_pk_f32_fp8_sdwa v[238:239], v151 src0_sel:WORD_1
	v_pk_fma_f32 v[228:229], v[68:69], v[236:237], v[228:229] op_sel_hi:[0,1,1]
	v_pk_fma_f32 v[230:231], v[68:69], v[238:239], v[230:231] op_sel_hi:[0,1,1]
	s_waitcnt vmcnt(14)
	v_cvt_pk_f32_fp8_e32 v[232:233], v152
	v_cvt_pk_f32_fp8_sdwa v[234:235], v152 src0_sel:WORD_1
	v_pk_fma_f32 v[216:217], v[68:69], v[232:233], v[216:217] op_sel:[1,0,0]
	v_pk_fma_f32 v[218:219], v[68:69], v[234:235], v[218:219] op_sel:[1,0,0]
	v_cvt_pk_f32_fp8_e32 v[236:237], v153
	v_cvt_pk_f32_fp8_sdwa v[238:239], v153 src0_sel:WORD_1
	v_pk_fma_f32 v[220:221], v[68:69], v[236:237], v[220:221] op_sel:[1,0,0]
	v_pk_fma_f32 v[222:223], v[68:69], v[238:239], v[222:223] op_sel:[1,0,0]
	v_cvt_pk_f32_fp8_e32 v[232:233], v154
	v_cvt_pk_f32_fp8_sdwa v[234:235], v154 src0_sel:WORD_1
	v_pk_fma_f32 v[224:225], v[68:69], v[232:233], v[224:225] op_sel:[1,0,0]
	v_pk_fma_f32 v[226:227], v[68:69], v[234:235], v[226:227] op_sel:[1,0,0]
	v_cvt_pk_f32_fp8_e32 v[236:237], v155
	v_cvt_pk_f32_fp8_sdwa v[238:239], v155 src0_sel:WORD_1
	v_pk_fma_f32 v[228:229], v[68:69], v[236:237], v[228:229] op_sel:[1,0,0]
	v_pk_fma_f32 v[230:231], v[68:69], v[238:239], v[230:231] op_sel:[1,0,0]
	s_waitcnt vmcnt(13)
	v_cvt_pk_f32_fp8_e32 v[232:233], v156
	v_cvt_pk_f32_fp8_sdwa v[234:235], v156 src0_sel:WORD_1
	v_pk_fma_f32 v[216:217], v[70:71], v[232:233], v[216:217] op_sel_hi:[0,1,1]
	v_pk_fma_f32 v[218:219], v[70:71], v[234:235], v[218:219] op_sel_hi:[0,1,1]
	v_cvt_pk_f32_fp8_e32 v[236:237], v157
	v_cvt_pk_f32_fp8_sdwa v[238:239], v157 src0_sel:WORD_1
	v_pk_fma_f32 v[220:221], v[70:71], v[236:237], v[220:221] op_sel_hi:[0,1,1]
	v_pk_fma_f32 v[222:223], v[70:71], v[238:239], v[222:223] op_sel_hi:[0,1,1]
	v_cvt_pk_f32_fp8_e32 v[232:233], v158
	v_cvt_pk_f32_fp8_sdwa v[234:235], v158 src0_sel:WORD_1
	v_pk_fma_f32 v[224:225], v[70:71], v[232:233], v[224:225] op_sel_hi:[0,1,1]
	v_pk_fma_f32 v[226:227], v[70:71], v[234:235], v[226:227] op_sel_hi:[0,1,1]
	v_cvt_pk_f32_fp8_e32 v[236:237], v159
	v_cvt_pk_f32_fp8_sdwa v[238:239], v159 src0_sel:WORD_1
	v_pk_fma_f32 v[228:229], v[70:71], v[236:237], v[228:229] op_sel_hi:[0,1,1]
	v_pk_fma_f32 v[230:231], v[70:71], v[238:239], v[230:231] op_sel_hi:[0,1,1]
	s_waitcnt vmcnt(12)
; DI f2_t cvt8lo(unsigned w) { return __builtin_amdgcn_cvt_pk_f32_fp8(w, false); }
; DI f2_t cvt8hi(unsigned w) { return __builtin_amdgcn_cvt_pk_f32_fp8(w, true); }
; DI void phase11(const Params& p, char* smem, int rep) {
;     ...
;         for (int k = 0; k < 16; ++k) rows[k] = *(const u32x4*)(vb + (size_t)ida[k] * 2048);
; #pragma unroll
;         for (int k = 0; k < 16; ++k) {
;           const f2_t a2 = {aa[k], aa[k]};
; #pragma unroll
;           for (int d = 0; d < 4; ++d) { const unsigned ww = rows[k][d]; o[2 * d] += a2 * cvt8lo(ww); o[2 * d + 1] += a2 * cvt8hi(ww); }
	v_cvt_pk_f32_fp8_e32 v[232:233], v160
	v_cvt_pk_f32_fp8_sdwa v[234:235], v160 src0_sel:WORD_1
	v_pk_fma_f32 v[216:217], v[70:71], v[232:233], v[216:217] op_sel:[1,0,0]
	v_pk_fma_f32 v[218:219], v[70:71], v[234:235], v[218:219] op_sel:[1,0,0]
	v_cvt_pk_f32_fp8_e32 v[236:237], v161
	v_cvt_pk_f32_fp8_sdwa v[238:239], v161 src0_sel:WORD_1
	v_pk_fma_f32 v[220:221], v[70:71], v[236:237], v[220:221] op_sel:[1,0,0]
	v_pk_fma_f32 v[222:223], v[70:71], v[238:239], v[222:223] op_sel:[1,0,0]
	v_cvt_pk_f32_fp8_e32 v[232:233], v162
	v_cvt_pk_f32_fp8_sdwa v[234:235], v162 src0_sel:WORD_1
	v_pk_fma_f32 v[224:225], v[70:71], v[232:233], v[224:225] op_sel:[1,0,0]
	v_pk_fma_f32 v[226:227], v[70:71], v[234:235], v[226:227] op_sel:[1,0,0]
	v_cvt_pk_f32_fp8_e32 v[236:237], v163
	v_cvt_pk_f32_fp8_sdwa v[238:239], v163 src0_sel:WORD_1
	v_pk_fma_f32 v[228:229], v[70:71], v[236:237], v[228:229] op_sel:[1,0,0]
	v_pk_fma_f32 v[230:231], v[70:71], v[238:239], v[230:231] op_sel:[1,0,0]
	s_waitcnt vmcnt(11)
	v_cvt_pk_f32_fp8_e32 v[232:233], v164
	v_cvt_pk_f32_fp8_sdwa v[234:235], v164 src0_sel:WORD_1
	v_pk_fma_f32 v[216:217], v[72:73], v[232:233], v[216:217] op_sel_hi:[0,1,1]
	v_pk_fma_f32 v[218:219], v[72:73], v[234:235], v[218:219] op_sel_hi:[0,1,1]
	v_cvt_pk_f32_fp8_e32 v[236:237], v165
	v_cvt_pk_f32_fp8_sdwa v[238:239], v165 src0_sel:WORD_1
	v_pk_fma_f32 v[220:221], v[72:73], v[236:237], v[220:221] op_sel_hi:[0,1,1]
	v_pk_fma_f32 v[222:223], v[72:73], v[238:239], v[222:223] op_sel_hi:[0,1,1]
	v_cvt_pk_f32_fp8_e32 v[232:233], v166
	v_cvt_pk_f32_fp8_sdwa v[234:235], v166 src0_sel:WORD_1
	v_pk_fma_f32 v[224:225], v[72:73], v[232:233], v[224:225] op_sel_hi:[0,1,1]
	v_pk_fma_f32 v[226:227], v[72:73], v[234:235], v[226:227] op_sel_hi:[0,1,1]
	v_cvt_pk_f32_fp8_e32 v[236:237], v167
	v_cvt_pk_f32_fp8_sdwa v[238:239], v167 src0_sel:WORD_1
	v_pk_fma_f32 v[228:229], v[72:73], v[236:237], v[228:229] op_sel_hi:[0,1,1]
	v_pk_fma_f32 v[230:231], v[72:73], v[238:239], v[230:231] op_sel_hi:[0,1,1]
	s_waitcnt vmcnt(10)
	v_cvt_pk_f32_fp8_e32 v[232:233], v168
	v_cvt_pk_f32_fp8_sdwa v[234:235], v168 src0_sel:WORD_1
	v_pk_fma_f32 v[216:217], v[72:73], v[232:233], v[216:217] op_sel:[1,0,0]
	v_pk_fma_f32 v[218:219], v[72:73], v[234:235], v[218:219] op_sel:[1,0,0]
	v_cvt_pk_f32_fp8_e32 v[236:237], v169
	v_cvt_pk_f32_fp8_sdwa v[238:239], v169 src0_sel:WORD_1
	v_pk_fma_f32 v[220:221], v[72:73], v[236:237], v[220:221] op_sel:[1,0,0]
	v_pk_fma_f32 v[222:223], v[72:73], v[238:239], v[222:223] op_sel:[1,0,0]
	v_cvt_pk_f32_fp8_e32 v[232:233], v170
	v_cvt_pk_f32_fp8_sdwa v[234:235], v170 src0_sel:WORD_1
	v_pk_fma_f32 v[224:225], v[72:73], v[232:233], v[224:225] op_sel:[1,0,0]
	v_pk_fma_f32 v[226:227], v[72:73], v[234:235], v[226:227] op_sel:[1,0,0]
	v_cvt_pk_f32_fp8_e32 v[236:237], v171
	v_cvt_pk_f32_fp8_sdwa v[238:239], v171 src0_sel:WORD_1
	v_pk_fma_f32 v[228:229], v[72:73], v[236:237], v[228:229] op_sel:[1,0,0]
	v_pk_fma_f32 v[230:231], v[72:73], v[238:239], v[230:231] op_sel:[1,0,0]
	s_waitcnt vmcnt(9)
	v_cvt_pk_f32_fp8_e32 v[232:233], v172
	v_cvt_pk_f32_fp8_sdwa v[234:235], v172 src0_sel:WORD_1
	v_pk_fma_f32 v[216:217], v[74:75], v[232:233], v[216:217] op_sel_hi:[0,1,1]
	v_pk_fma_f32 v[218:219], v[74:75], v[234:235], v[218:219] op_sel_hi:[0,1,1]
	v_cvt_pk_f32_fp8_e32 v[236:237], v173
	v_cvt_pk_f32_fp8_sdwa v[238:239], v173 src0_sel:WORD_1
	v_pk_fma_f32 v[220:221], v[74:75], v[236:237], v[220:221] op_sel_hi:[0,1,1]
	v_pk_fma_f32 v[222:223], v[74:75], v[238:239], v[222:223] op_sel_hi:[0,1,1]
	v_cvt_pk_f32_fp8_e32 v[232:233], v174
	v_cvt_pk_f32_fp8_sdwa v[234:235], v174 src0_sel:WORD_1
	v_pk_fma_f32 v[224:225], v[74:75], v[232:233], v[224:225] op_sel_hi:[0,1,1]
	v_pk_fma_f32 v[226:227], v[74:75], v[234:235], v[226:227] op_sel_hi:[0,1,1]
	v_cvt_pk_f32_fp8_e32 v[236:237], v175
	v_cvt_pk_f32_fp8_sdwa v[238:239], v175 src0_sel:WORD_1
	v_pk_fma_f32 v[228:229], v[74:75], v[236:237], v[228:229] op_sel_hi:[0,1,1]
	v_pk_fma_f32 v[230:231], v[74:75], v[238:239], v[230:231] op_sel_hi:[0,1,1]
	s_waitcnt vmcnt(8)
	v_cvt_pk_f32_fp8_e32 v[232:233], v176
	v_cvt_pk_f32_fp8_sdwa v[234:235], v176 src0_sel:WORD_1
	v_pk_fma_f32 v[216:217], v[74:75], v[232:233], v[216:217] op_sel:[1,0,0]
	v_pk_fma_f32 v[218:219], v[74:75], v[234:235], v[218:219] op_sel:[1,0,0]
	v_cvt_pk_f32_fp8_e32 v[236:237], v177
	v_cvt_pk_f32_fp8_sdwa v[238:239], v177 src0_sel:WORD_1
	v_pk_fma_f32 v[220:221], v[74:75], v[236:237], v[220:221] op_sel:[1,0,0]
	v_pk_fma_f32 v[222:223], v[74:75], v[238:239], v[222:223] op_sel:[1,0,0]
	v_cvt_pk_f32_fp8_e32 v[232:233], v178
	v_cvt_pk_f32_fp8_sdwa v[234:235], v178 src0_sel:WORD_1
	v_pk_fma_f32 v[224:225], v[74:75], v[232:233], v[224:225] op_sel:[1,0,0]
	v_pk_fma_f32 v[226:227], v[74:75], v[234:235], v[226:227] op_sel:[1,0,0]
	v_cvt_pk_f32_fp8_e32 v[236:237], v179
	v_cvt_pk_f32_fp8_sdwa v[238:239], v179 src0_sel:WORD_1
	v_pk_fma_f32 v[228:229], v[74:75], v[236:237], v[228:229] op_sel:[1,0,0]
	v_pk_fma_f32 v[230:231], v[74:75], v[238:239], v[230:231] op_sel:[1,0,0]
	s_waitcnt vmcnt(7)
	v_cvt_pk_f32_fp8_e32 v[232:233], v180
	v_cvt_pk_f32_fp8_sdwa v[234:235], v180 src0_sel:WORD_1
	v_pk_fma_f32 v[216:217], v[76:77], v[232:233], v[216:217] op_sel_hi:[0,1,1]
	v_pk_fma_f32 v[218:219], v[76:77], v[234:235], v[218:219] op_sel_hi:[0,1,1]
	v_cvt_pk_f32_fp8_e32 v[236:237], v181
	v_cvt_pk_f32_fp8_sdwa v[238:239], v181 src0_sel:WORD_1
	v_pk_fma_f32 v[220:221], v[76:77], v[236:237], v[220:221] op_sel_hi:[0,1,1]
	v_pk_fma_f32 v[222:223], v[76:77], v[238:239], v[222:223] op_sel_hi:[0,1,1]
	v_cvt_pk_f32_fp8_e32 v[232:233], v182
	v_cvt_pk_f32_fp8_sdwa v[234:235], v182 src0_sel:WORD_1
	v_pk_fma_f32 v[224:225], v[76:77], v[232:233], v[224:225] op_sel_hi:[0,1,1]
	v_pk_fma_f32 v[226:227], v[76:77], v[234:235], v[226:227] op_sel_hi:[0,1,1]
	v_cvt_pk_f32_fp8_e32 v[236:237], v183
	v_cvt_pk_f32_fp8_sdwa v[238:239], v183 src0_sel:WORD_1
	v_pk_fma_f32 v[228:229], v[76:77], v[236:237], v[228:229] op_sel_hi:[0,1,1]
	v_pk_fma_f32 v[230:231], v[76:77], v[238:239], v[230:231] op_sel_hi:[0,1,1]
	s_waitcnt vmcnt(6)
; DI f2_t cvt8lo(unsigned w) { return __builtin_amdgcn_cvt_pk_f32_fp8(w, false); }
; DI f2_t cvt8hi(unsigned w) { return __builtin_amdgcn_cvt_pk_f32_fp8(w, true); }
; DI void phase11(const Params& p, char* smem, int rep) {
;     ...
;         for (int k = 0; k < 16; ++k) rows[k] = *(const u32x4*)(vb + (size_t)ida[k] * 2048);
; #pragma unroll
;         for (int k = 0; k < 16; ++k) {
;           const f2_t a2 = {aa[k], aa[k]};
; #pragma unroll
;           for (int d = 0; d < 4; ++d) { const unsigned ww = rows[k][d]; o[2 * d] += a2 * cvt8lo(ww); o[2 * d + 1] += a2 * cvt8hi(ww); }
	v_cvt_pk_f32_fp8_e32 v[232:233], v184
	v_cvt_pk_f32_fp8_sdwa v[234:235], v184 src0_sel:WORD_1
	v_pk_fma_f32 v[216:217], v[76:77], v[232:233], v[216:217] op_sel:[1,0,0]
	v_pk_fma_f32 v[218:219], v[76:77], v[234:235], v[218:219] op_sel:[1,0,0]
	v_cvt_pk_f32_fp8_e32 v[236:237], v185
	v_cvt_pk_f32_fp8_sdwa v[238:239], v185 src0_sel:WORD_1
	v_pk_fma_f32 v[220:221], v[76:77], v[236:237], v[220:221] op_sel:[1,0,0]
	v_pk_fma_f32 v[222:223], v[76:77], v[238:239], v[222:223] op_sel:[1,0,0]
	v_cvt_pk_f32_fp8_e32 v[232:233], v186
	v_cvt_pk_f32_fp8_sdwa v[234:235], v186 src0_sel:WORD_1
	v_pk_fma_f32 v[224:225], v[76:77], v[232:233], v[224:225] op_sel:[1,0,0]
	v_pk_fma_f32 v[226:227], v[76:77], v[234:235], v[226:227] op_sel:[1,0,0]
	v_cvt_pk_f32_fp8_e32 v[236:237], v187
	v_cvt_pk_f32_fp8_sdwa v[238:239], v187 src0_sel:WORD_1
	v_pk_fma_f32 v[228:229], v[76:77], v[236:237], v[228:229] op_sel:[1,0,0]
	v_pk_fma_f32 v[230:231], v[76:77], v[238:239], v[230:231] op_sel:[1,0,0]
	s_waitcnt vmcnt(5)
	v_cvt_pk_f32_fp8_e32 v[232:233], v190
	v_cvt_pk_f32_fp8_sdwa v[234:235], v190 src0_sel:WORD_1
	v_pk_fma_f32 v[216:217], v[78:79], v[232:233], v[216:217] op_sel_hi:[0,1,1]
	v_pk_fma_f32 v[218:219], v[78:79], v[234:235], v[218:219] op_sel_hi:[0,1,1]
	v_cvt_pk_f32_fp8_e32 v[236:237], v191
	v_cvt_pk_f32_fp8_sdwa v[238:239], v191 src0_sel:WORD_1
	v_pk_fma_f32 v[220:221], v[78:79], v[236:237], v[220:221] op_sel_hi:[0,1,1]
	v_pk_fma_f32 v[222:223], v[78:79], v[238:239], v[222:223] op_sel_hi:[0,1,1]
	v_cvt_pk_f32_fp8_e32 v[232:233], v192
	v_cvt_pk_f32_fp8_sdwa v[234:235], v192 src0_sel:WORD_1
	v_pk_fma_f32 v[224:225], v[78:79], v[232:233], v[224:225] op_sel_hi:[0,1,1]
	v_pk_fma_f32 v[226:227], v[78:79], v[234:235], v[226:227] op_sel_hi:[0,1,1]
	v_cvt_pk_f32_fp8_e32 v[236:237], v193
	v_cvt_pk_f32_fp8_sdwa v[238:239], v193 src0_sel:WORD_1
	v_pk_fma_f32 v[228:229], v[78:79], v[236:237], v[228:229] op_sel_hi:[0,1,1]
	v_pk_fma_f32 v[230:231], v[78:79], v[238:239], v[230:231] op_sel_hi:[0,1,1]
	s_waitcnt vmcnt(4)
	v_cvt_pk_f32_fp8_e32 v[232:233], v194
	v_cvt_pk_f32_fp8_sdwa v[234:235], v194 src0_sel:WORD_1
	v_pk_fma_f32 v[216:217], v[78:79], v[232:233], v[216:217] op_sel:[1,0,0]
	v_pk_fma_f32 v[218:219], v[78:79], v[234:235], v[218:219] op_sel:[1,0,0]
	v_cvt_pk_f32_fp8_e32 v[236:237], v195
	v_cvt_pk_f32_fp8_sdwa v[238:239], v195 src0_sel:WORD_1
	v_pk_fma_f32 v[220:221], v[78:79], v[236:237], v[220:221] op_sel:[1,0,0]
	v_pk_fma_f32 v[222:223], v[78:79], v[238:239], v[222:223] op_sel:[1,0,0]
	v_cvt_pk_f32_fp8_e32 v[232:233], v196
	v_cvt_pk_f32_fp8_sdwa v[234:235], v196 src0_sel:WORD_1
	v_pk_fma_f32 v[224:225], v[78:79], v[232:233], v[224:225] op_sel:[1,0,0]
	v_pk_fma_f32 v[226:227], v[78:79], v[234:235], v[226:227] op_sel:[1,0,0]
	v_cvt_pk_f32_fp8_e32 v[236:237], v197
	v_cvt_pk_f32_fp8_sdwa v[238:239], v197 src0_sel:WORD_1
	v_pk_fma_f32 v[228:229], v[78:79], v[236:237], v[228:229] op_sel:[1,0,0]
	v_pk_fma_f32 v[230:231], v[78:79], v[238:239], v[230:231] op_sel:[1,0,0]
	s_waitcnt vmcnt(3)
	v_cvt_pk_f32_fp8_e32 v[232:233], v198
	v_cvt_pk_f32_fp8_sdwa v[234:235], v198 src0_sel:WORD_1
	v_pk_fma_f32 v[216:217], v[80:81], v[232:233], v[216:217] op_sel_hi:[0,1,1]
	v_pk_fma_f32 v[218:219], v[80:81], v[234:235], v[218:219] op_sel_hi:[0,1,1]
	v_cvt_pk_f32_fp8_e32 v[236:237], v199
	v_cvt_pk_f32_fp8_sdwa v[238:239], v199 src0_sel:WORD_1
	v_pk_fma_f32 v[220:221], v[80:81], v[236:237], v[220:221] op_sel_hi:[0,1,1]
	v_pk_fma_f32 v[222:223], v[80:81], v[238:239], v[222:223] op_sel_hi:[0,1,1]
	v_cvt_pk_f32_fp8_e32 v[232:233], v200
	v_cvt_pk_f32_fp8_sdwa v[234:235], v200 src0_sel:WORD_1
	v_pk_fma_f32 v[224:225], v[80:81], v[232:233], v[224:225] op_sel_hi:[0,1,1]
	v_pk_fma_f32 v[226:227], v[80:81], v[234:235], v[226:227] op_sel_hi:[0,1,1]
	v_cvt_pk_f32_fp8_e32 v[236:237], v201
	v_cvt_pk_f32_fp8_sdwa v[238:239], v201 src0_sel:WORD_1
	v_pk_fma_f32 v[228:229], v[80:81], v[236:237], v[228:229] op_sel_hi:[0,1,1]
	v_pk_fma_f32 v[230:231], v[80:81], v[238:239], v[230:231] op_sel_hi:[0,1,1]
	s_waitcnt vmcnt(2)
	v_cvt_pk_f32_fp8_e32 v[232:233], v202
	v_cvt_pk_f32_fp8_sdwa v[234:235], v202 src0_sel:WORD_1
	v_pk_fma_f32 v[216:217], v[80:81], v[232:233], v[216:217] op_sel:[1,0,0]
	v_pk_fma_f32 v[218:219], v[80:81], v[234:235], v[218:219] op_sel:[1,0,0]
	v_cvt_pk_f32_fp8_e32 v[236:237], v203
	v_cvt_pk_f32_fp8_sdwa v[238:239], v203 src0_sel:WORD_1
	v_pk_fma_f32 v[220:221], v[80:81], v[236:237], v[220:221] op_sel:[1,0,0]
	v_pk_fma_f32 v[222:223], v[80:81], v[238:239], v[222:223] op_sel:[1,0,0]
	v_cvt_pk_f32_fp8_e32 v[232:233], v204
	v_cvt_pk_f32_fp8_sdwa v[234:235], v204 src0_sel:WORD_1
	v_pk_fma_f32 v[224:225], v[80:81], v[232:233], v[224:225] op_sel:[1,0,0]
	v_pk_fma_f32 v[226:227], v[80:81], v[234:235], v[226:227] op_sel:[1,0,0]
	v_cvt_pk_f32_fp8_e32 v[236:237], v205
	v_cvt_pk_f32_fp8_sdwa v[238:239], v205 src0_sel:WORD_1
	v_pk_fma_f32 v[228:229], v[80:81], v[236:237], v[228:229] op_sel:[1,0,0]
	v_pk_fma_f32 v[230:231], v[80:81], v[238:239], v[230:231] op_sel:[1,0,0]
	s_waitcnt vmcnt(1)
	v_cvt_pk_f32_fp8_e32 v[232:233], v206
	v_cvt_pk_f32_fp8_sdwa v[234:235], v206 src0_sel:WORD_1
	v_pk_fma_f32 v[216:217], v[82:83], v[232:233], v[216:217] op_sel_hi:[0,1,1]
	v_pk_fma_f32 v[218:219], v[82:83], v[234:235], v[218:219] op_sel_hi:[0,1,1]
	v_cvt_pk_f32_fp8_e32 v[236:237], v207
	v_cvt_pk_f32_fp8_sdwa v[238:239], v207 src0_sel:WORD_1
	v_pk_fma_f32 v[220:221], v[82:83], v[236:237], v[220:221] op_sel_hi:[0,1,1]
	v_pk_fma_f32 v[222:223], v[82:83], v[238:239], v[222:223] op_sel_hi:[0,1,1]
	v_cvt_pk_f32_fp8_e32 v[232:233], v208
	v_cvt_pk_f32_fp8_sdwa v[234:235], v208 src0_sel:WORD_1
	v_pk_fma_f32 v[224:225], v[82:83], v[232:233], v[224:225] op_sel_hi:[0,1,1]
	v_pk_fma_f32 v[226:227], v[82:83], v[234:235], v[226:227] op_sel_hi:[0,1,1]
	v_cvt_pk_f32_fp8_e32 v[236:237], v209
	v_cvt_pk_f32_fp8_sdwa v[238:239], v209 src0_sel:WORD_1
	v_pk_fma_f32 v[228:229], v[82:83], v[236:237], v[228:229] op_sel_hi:[0,1,1]
	v_pk_fma_f32 v[230:231], v[82:83], v[238:239], v[230:231] op_sel_hi:[0,1,1]
	s_waitcnt vmcnt(0)
; DI unsigned pk2(float a, float b) { f2_t v = {a, b}; bf2_t r = __builtin_convertvector(v, bf2_t); return __builtin_bit_cast(unsigned, r); }
; DI void wave_lds_sync() { asm volatile("s_waitcnt lgkmcnt(0)" ::: "memory"); __builtin_amdgcn_wave_barrier(); }
; DI void phase11(const Params& p, char* smem, int rep) {
;     ...
;       const int tok = __builtin_amdgcn_readfirstlane(c * 16 + w * 4 + t);
;       const int i0 = IDS[(size_t)tok * 128 + lane], i1 = IDS[(size_t)tok * 128 + 64 + lane];
;       const float a0 = ACT[(size_t)tok * 128 + lane], a1 = ACT[(size_t)tok * 128 + 64 + lane];
;       wave_lds_sync();
;       lw[(lane & 3) * 32 + (lane >> 2)] = i0; lw[(lane & 3) * 32 + 16 + (lane >> 2)] = i1;
;       lf[(lane & 3) * 32 + (lane >> 2)] = a0; lf[(lane & 3) * 32 + 16 + (lane >> 2)] = a1;
;       wave_lds_sync();
;       f2_t o[8];
; #pragma unroll
;       for (int i = 0; i < 8; ++i) o[i] = f2_t{0.f, 0.f};
;       const unsigned char* vb = V8 + s * 256 + l15 * 16;
; #pragma unroll
;       for (int batch = 0; batch < 2; ++batch) {
;         int ida[16]; float aa[16];
; #pragma unroll
;         for (int q = 0; q < 4; ++q) {
;           const int4 v = *(const int4*)(lw + g * 32 + batch * 16 + q * 4); ida[q * 4] = v.x; ida[q * 4 + 1] = v.y; ida[q * 4 + 2] = v.z; ida[q * 4 + 3] = v.w;
;           const float4 f = *(const float4*)(lf + g * 32 + batch * 16 + q * 4); aa[q * 4] = f.x; aa[q * 4 + 1] = f.y; aa[q * 4 + 2] = f.z; aa[q * 4 + 3] = f.w;
;         }
;         u32x4 rows[16];
; #pragma unroll
;         for (int k = 0; k < 16; ++k) rows[k] = *(const u32x4*)(vb + (size_t)ida[k] * 2048);
;     ...
;       float ov[16];
; #pragma unroll
;       for (int d = 0; d < 4; ++d) { ov[4 * d] = o[2 * d].x; ov[4 * d + 1] = o[2 * d].y; ov[4 * d + 2] = o[2 * d + 1].x; ov[4 * d + 3] = o[2 * d + 1].y; }
;       float q8[8], q4[4];
; #pragma unroll
;       for (int k = 0; k < 8; ++k) q8[k] = (b5 ? ov[8 + k] : ov[k]) + __shfl_xor(b5 ? ov[k] : ov[8 + k], 32);
; #pragma unroll
;       for (int k = 0; k < 4; ++k) q4[k] = (b4 ? q8[4 + k] : q8[k]) + __shfl_xor(b4 ? q8[k] : q8[4 + k], 16);
;       *(uint2*)(OUTP + (size_t)tok * D_ + s * 256 + l15 * 16 + 8 * b5 + 4 * b4) = make_uint2(pk2(q4[0], q4[1]), pk2(q4[2], q4[3]));
	v_cvt_pk_f32_fp8_e32 v[232:233], v210
	v_cvt_pk_f32_fp8_sdwa v[234:235], v210 src0_sel:WORD_1
	v_pk_fma_f32 v[216:217], v[82:83], v[232:233], v[216:217] op_sel:[1,0,0]
	v_pk_fma_f32 v[218:219], v[82:83], v[234:235], v[218:219] op_sel:[1,0,0]
	v_cvt_pk_f32_fp8_e32 v[236:237], v211
	v_cvt_pk_f32_fp8_sdwa v[238:239], v211 src0_sel:WORD_1
	v_pk_fma_f32 v[220:221], v[82:83], v[236:237], v[220:221] op_sel:[1,0,0]
	v_pk_fma_f32 v[222:223], v[82:83], v[238:239], v[222:223] op_sel:[1,0,0]
	v_cvt_pk_f32_fp8_e32 v[232:233], v212
	v_cvt_pk_f32_fp8_sdwa v[234:235], v212 src0_sel:WORD_1
	v_pk_fma_f32 v[224:225], v[82:83], v[232:233], v[224:225] op_sel:[1,0,0]
	v_pk_fma_f32 v[226:227], v[82:83], v[234:235], v[226:227] op_sel:[1,0,0]
	v_cvt_pk_f32_fp8_e32 v[236:237], v213
	v_cvt_pk_f32_fp8_sdwa v[238:239], v213 src0_sel:WORD_1
	v_pk_fma_f32 v[228:229], v[82:83], v[236:237], v[228:229] op_sel:[1,0,0]
	v_pk_fma_f32 v[230:231], v[82:83], v[238:239], v[230:231] op_sel:[1,0,0]
	ds_read_b128 v[52:55], v6 offset:528
	ds_read_b128 v[56:59], v6 offset:544
	ds_read_b128 v[60:63], v6 offset:560
	ds_read_b128 v[64:67], v6 offset:576
	ds_read_b128 v[68:71], v6 offset:592
	ds_read_b128 v[72:75], v6 offset:608
	ds_read_b128 v[76:79], v6 offset:624
	ds_read_b128 v[80:83], v6 offset:640
	v_add_u32_e32 v214, s46, v4
	s_nop 0
	v_permlane32_swap_b32_e32 v216, v224
	v_permlane32_swap_b32_e32 v217, v225
	v_permlane32_swap_b32_e32 v218, v226
	v_permlane32_swap_b32_e32 v219, v227
	v_permlane32_swap_b32_e32 v220, v228
	v_permlane32_swap_b32_e32 v221, v229
	v_permlane32_swap_b32_e32 v222, v230
	v_permlane32_swap_b32_e32 v223, v231
	v_add_f32_e32 v216, v216, v224
	v_add_f32_e32 v217, v217, v225
	v_add_f32_e32 v218, v218, v226
	v_add_f32_e32 v219, v219, v227
	v_add_f32_e32 v220, v220, v228
	v_add_f32_e32 v221, v221, v229
	v_add_f32_e32 v222, v222, v230
	v_add_f32_e32 v223, v223, v231
	s_nop 1
	v_permlane16_swap_b32_e32 v216, v220
	v_permlane16_swap_b32_e32 v217, v221
	v_permlane16_swap_b32_e32 v218, v222
	v_permlane16_swap_b32_e32 v219, v223
	v_add_f32_e32 v216, v216, v220
	v_add_f32_e32 v217, v217, v221
	v_add_f32_e32 v218, v218, v222
	v_add_f32_e32 v219, v219, v223
	v_cvt_pk_bf16_f32 v232, v216, v217
	v_cvt_pk_bf16_f32 v233, v218, v219
	global_store_dwordx2 v214, v[232:233], s[14:15]
	s_add_i32 s36, s34, 1
	s_lshl_b32 s46, s36, 12
	s_add_i32 s46, s46, s24
	s_add_i32 s37, s34, 2
	s_lshl_b32 s47, s37, 9
	s_add_u32 s42, s6, s47
	s_addc_u32 s43, s7, 0
	s_add_u32 s44, s8, s47
	s_addc_u32 s45, s9, 0
	global_load_dword v10, v3, s[42:43]
	global_load_dword v11, v3, s[42:43] offset:256
	global_load_dword v12, v3, s[44:45]
	global_load_dword v13, v3, s[44:45] offset:256
	s_waitcnt lgkmcnt(0)
	v_lshl_add_u32 v20, v20, 11, v2
	v_lshl_add_u32 v21, v21, 11, v2
	v_lshl_add_u32 v22, v22, 11, v2
	v_lshl_add_u32 v23, v23, 11, v2
	v_lshl_add_u32 v24, v24, 11, v2
	v_lshl_add_u32 v25, v25, 11, v2
	v_lshl_add_u32 v26, v26, 11, v2
	v_lshl_add_u32 v27, v27, 11, v2
	v_lshl_add_u32 v28, v28, 11, v2
	v_lshl_add_u32 v29, v29, 11, v2
	v_lshl_add_u32 v30, v30, 11, v2
	v_lshl_add_u32 v31, v31, 11, v2
	v_lshl_add_u32 v32, v32, 11, v2
	v_lshl_add_u32 v33, v33, 11, v2
	v_lshl_add_u32 v34, v34, 11, v2
	v_lshl_add_u32 v35, v35, 11, v2
	v_lshl_add_u32 v36, v36, 11, v2
	v_lshl_add_u32 v37, v37, 11, v2
	v_lshl_add_u32 v38, v38, 11, v2
	v_lshl_add_u32 v39, v39, 11, v2
	v_lshl_add_u32 v40, v40, 11, v2
	v_lshl_add_u32 v41, v41, 11, v2
	v_lshl_add_u32 v42, v42, 11, v2
	v_lshl_add_u32 v43, v43, 11, v2
	v_lshl_add_u32 v44, v44, 11, v2
	v_lshl_add_u32 v45, v45, 11, v2
	v_lshl_add_u32 v46, v46, 11, v2
	v_lshl_add_u32 v47, v47, 11, v2
	v_lshl_add_u32 v48, v48, 11, v2
	v_lshl_add_u32 v49, v49, 11, v2
	v_lshl_add_u32 v50, v50, 11, v2
	v_lshl_add_u32 v51, v51, 11, v2
	global_load_dwordx4 v[84:87], v20, s[20:21]
	global_load_dwordx4 v[88:91], v21, s[20:21]
	global_load_dwordx4 v[92:95], v22, s[20:21]
	global_load_dwordx4 v[96:99], v23, s[20:21]
	global_load_dwordx4 v[100:103], v24, s[20:21]
	global_load_dwordx4 v[104:107], v25, s[20:21]
	global_load_dwordx4 v[108:111], v26, s[20:21]
	global_load_dwordx4 v[112:115], v27, s[20:21]
	global_load_dwordx4 v[116:119], v28, s[20:21]
	global_load_dwordx4 v[120:123], v29, s[20:21]
	global_load_dwordx4 v[124:127], v30, s[20:21]
	global_load_dwordx4 v[128:131], v31, s[20:21]
	global_load_dwordx4 v[132:135], v32, s[20:21]
	global_load_dwordx4 v[136:139], v33, s[20:21]
	global_load_dwordx4 v[140:143], v34, s[20:21]
	global_load_dwordx4 v[144:147], v35, s[20:21]
	global_load_dwordx4 v[148:151], v36, s[20:21]
	global_load_dwordx4 v[152:155], v37, s[20:21]
	global_load_dwordx4 v[156:159], v38, s[20:21]
	global_load_dwordx4 v[160:163], v39, s[20:21]
	global_load_dwordx4 v[164:167], v40, s[20:21]
	global_load_dwordx4 v[168:171], v41, s[20:21]
	global_load_dwordx4 v[172:175], v42, s[20:21]
	global_load_dwordx4 v[176:179], v43, s[20:21]
	global_load_dwordx4 v[180:183], v44, s[20:21]
	global_load_dwordx4 v[184:187], v45, s[20:21]
	global_load_dwordx4 v[190:193], v46, s[20:21]
	global_load_dwordx4 v[194:197], v47, s[20:21]
	global_load_dwordx4 v[198:201], v48, s[20:21]
	global_load_dwordx4 v[202:205], v49, s[20:21]
	global_load_dwordx4 v[206:209], v50, s[20:21]
	global_load_dwordx4 v[210:213], v51, s[20:21]
	s_waitcnt vmcnt(31)
; DI f2_t cvt8lo(unsigned w) { return __builtin_amdgcn_cvt_pk_f32_fp8(w, false); }
; DI f2_t cvt8hi(unsigned w) { return __builtin_amdgcn_cvt_pk_f32_fp8(w, true); }
; DI void phase11(const Params& p, char* smem, int rep) {
;     ...
;         for (int k = 0; k < 16; ++k) rows[k] = *(const u32x4*)(vb + (size_t)ida[k] * 2048);
; #pragma unroll
;         for (int k = 0; k < 16; ++k) {
;           const f2_t a2 = {aa[k], aa[k]};
; #pragma unroll
;           for (int d = 0; d < 4; ++d) { const unsigned ww = rows[k][d]; o[2 * d] += a2 * cvt8lo(ww); o[2 * d + 1] += a2 * cvt8hi(ww); }
	v_cvt_pk_f32_fp8_e32 v[232:233], v84
	v_cvt_pk_f32_fp8_sdwa v[234:235], v84 src0_sel:WORD_1
	v_pk_fma_f32 v[216:217], v[52:53], v[232:233], 0 op_sel_hi:[0,1,0]
	v_pk_fma_f32 v[218:219], v[52:53], v[234:235], 0 op_sel_hi:[0,1,0]
	v_cvt_pk_f32_fp8_e32 v[236:237], v85
	v_cvt_pk_f32_fp8_sdwa v[238:239], v85 src0_sel:WORD_1
	v_pk_fma_f32 v[220:221], v[52:53], v[236:237], 0 op_sel_hi:[0,1,0]
	v_pk_fma_f32 v[222:223], v[52:53], v[238:239], 0 op_sel_hi:[0,1,0]
	v_cvt_pk_f32_fp8_e32 v[232:233], v86
	v_cvt_pk_f32_fp8_sdwa v[234:235], v86 src0_sel:WORD_1
	v_pk_fma_f32 v[224:225], v[52:53], v[232:233], 0 op_sel_hi:[0,1,0]
	v_pk_fma_f32 v[226:227], v[52:53], v[234:235], 0 op_sel_hi:[0,1,0]
	v_cvt_pk_f32_fp8_e32 v[236:237], v87
	v_cvt_pk_f32_fp8_sdwa v[238:239], v87 src0_sel:WORD_1
	v_pk_fma_f32 v[228:229], v[52:53], v[236:237], 0 op_sel_hi:[0,1,0]
	v_pk_fma_f32 v[230:231], v[52:53], v[238:239], 0 op_sel_hi:[0,1,0]
	s_waitcnt vmcnt(30)
	v_cvt_pk_f32_fp8_e32 v[232:233], v88
	v_cvt_pk_f32_fp8_sdwa v[234:235], v88 src0_sel:WORD_1
	v_pk_fma_f32 v[216:217], v[52:53], v[232:233], v[216:217] op_sel:[1,0,0]
	v_pk_fma_f32 v[218:219], v[52:53], v[234:235], v[218:219] op_sel:[1,0,0]
	v_cvt_pk_f32_fp8_e32 v[236:237], v89
	v_cvt_pk_f32_fp8_sdwa v[238:239], v89 src0_sel:WORD_1
	v_pk_fma_f32 v[220:221], v[52:53], v[236:237], v[220:221] op_sel:[1,0,0]
	v_pk_fma_f32 v[222:223], v[52:53], v[238:239], v[222:223] op_sel:[1,0,0]
	v_cvt_pk_f32_fp8_e32 v[232:233], v90
	v_cvt_pk_f32_fp8_sdwa v[234:235], v90 src0_sel:WORD_1
	v_pk_fma_f32 v[224:225], v[52:53], v[232:233], v[224:225] op_sel:[1,0,0]
	v_pk_fma_f32 v[226:227], v[52:53], v[234:235], v[226:227] op_sel:[1,0,0]
	v_cvt_pk_f32_fp8_e32 v[236:237], v91
	v_cvt_pk_f32_fp8_sdwa v[238:239], v91 src0_sel:WORD_1
	v_pk_fma_f32 v[228:229], v[52:53], v[236:237], v[228:229] op_sel:[1,0,0]
	v_pk_fma_f32 v[230:231], v[52:53], v[238:239], v[230:231] op_sel:[1,0,0]
	s_waitcnt vmcnt(29)
	v_cvt_pk_f32_fp8_e32 v[232:233], v92
	v_cvt_pk_f32_fp8_sdwa v[234:235], v92 src0_sel:WORD_1
	v_pk_fma_f32 v[216:217], v[54:55], v[232:233], v[216:217] op_sel_hi:[0,1,1]
	v_pk_fma_f32 v[218:219], v[54:55], v[234:235], v[218:219] op_sel_hi:[0,1,1]
	v_cvt_pk_f32_fp8_e32 v[236:237], v93
	v_cvt_pk_f32_fp8_sdwa v[238:239], v93 src0_sel:WORD_1
	v_pk_fma_f32 v[220:221], v[54:55], v[236:237], v[220:221] op_sel_hi:[0,1,1]
	v_pk_fma_f32 v[222:223], v[54:55], v[238:239], v[222:223] op_sel_hi:[0,1,1]
	v_cvt_pk_f32_fp8_e32 v[232:233], v94
	v_cvt_pk_f32_fp8_sdwa v[234:235], v94 src0_sel:WORD_1
	v_pk_fma_f32 v[224:225], v[54:55], v[232:233], v[224:225] op_sel_hi:[0,1,1]
	v_pk_fma_f32 v[226:227], v[54:55], v[234:235], v[226:227] op_sel_hi:[0,1,1]
	v_cvt_pk_f32_fp8_e32 v[236:237], v95
	v_cvt_pk_f32_fp8_sdwa v[238:239], v95 src0_sel:WORD_1
	v_pk_fma_f32 v[228:229], v[54:55], v[236:237], v[228:229] op_sel_hi:[0,1,1]
	v_pk_fma_f32 v[230:231], v[54:55], v[238:239], v[230:231] op_sel_hi:[0,1,1]
	s_waitcnt vmcnt(28)
	v_cvt_pk_f32_fp8_e32 v[232:233], v96
	v_cvt_pk_f32_fp8_sdwa v[234:235], v96 src0_sel:WORD_1
	v_pk_fma_f32 v[216:217], v[54:55], v[232:233], v[216:217] op_sel:[1,0,0]
	v_pk_fma_f32 v[218:219], v[54:55], v[234:235], v[218:219] op_sel:[1,0,0]
	v_cvt_pk_f32_fp8_e32 v[236:237], v97
	v_cvt_pk_f32_fp8_sdwa v[238:239], v97 src0_sel:WORD_1
	v_pk_fma_f32 v[220:221], v[54:55], v[236:237], v[220:221] op_sel:[1,0,0]
	v_pk_fma_f32 v[222:223], v[54:55], v[238:239], v[222:223] op_sel:[1,0,0]
	v_cvt_pk_f32_fp8_e32 v[232:233], v98
	v_cvt_pk_f32_fp8_sdwa v[234:235], v98 src0_sel:WORD_1
	v_pk_fma_f32 v[224:225], v[54:55], v[232:233], v[224:225] op_sel:[1,0,0]
	v_pk_fma_f32 v[226:227], v[54:55], v[234:235], v[226:227] op_sel:[1,0,0]
	v_cvt_pk_f32_fp8_e32 v[236:237], v99
	v_cvt_pk_f32_fp8_sdwa v[238:239], v99 src0_sel:WORD_1
	v_pk_fma_f32 v[228:229], v[54:55], v[236:237], v[228:229] op_sel:[1,0,0]
	v_pk_fma_f32 v[230:231], v[54:55], v[238:239], v[230:231] op_sel:[1,0,0]
	s_waitcnt vmcnt(27)
	v_cvt_pk_f32_fp8_e32 v[232:233], v100
	v_cvt_pk_f32_fp8_sdwa v[234:235], v100 src0_sel:WORD_1
	v_pk_fma_f32 v[216:217], v[56:57], v[232:233], v[216:217] op_sel_hi:[0,1,1]
	v_pk_fma_f32 v[218:219], v[56:57], v[234:235], v[218:219] op_sel_hi:[0,1,1]
	v_cvt_pk_f32_fp8_e32 v[236:237], v101
	v_cvt_pk_f32_fp8_sdwa v[238:239], v101 src0_sel:WORD_1
	v_pk_fma_f32 v[220:221], v[56:57], v[236:237], v[220:221] op_sel_hi:[0,1,1]
	v_pk_fma_f32 v[222:223], v[56:57], v[238:239], v[222:223] op_sel_hi:[0,1,1]
	v_cvt_pk_f32_fp8_e32 v[232:233], v102
	v_cvt_pk_f32_fp8_sdwa v[234:235], v102 src0_sel:WORD_1
	v_pk_fma_f32 v[224:225], v[56:57], v[232:233], v[224:225] op_sel_hi:[0,1,1]
	v_pk_fma_f32 v[226:227], v[56:57], v[234:235], v[226:227] op_sel_hi:[0,1,1]
	v_cvt_pk_f32_fp8_e32 v[236:237], v103
	v_cvt_pk_f32_fp8_sdwa v[238:239], v103 src0_sel:WORD_1
	v_pk_fma_f32 v[228:229], v[56:57], v[236:237], v[228:229] op_sel_hi:[0,1,1]
	v_pk_fma_f32 v[230:231], v[56:57], v[238:239], v[230:231] op_sel_hi:[0,1,1]
	s_waitcnt vmcnt(26)
	v_cvt_pk_f32_fp8_e32 v[232:233], v104
	v_cvt_pk_f32_fp8_sdwa v[234:235], v104 src0_sel:WORD_1
	v_pk_fma_f32 v[216:217], v[56:57], v[232:233], v[216:217] op_sel:[1,0,0]
	v_pk_fma_f32 v[218:219], v[56:57], v[234:235], v[218:219] op_sel:[1,0,0]
	v_cvt_pk_f32_fp8_e32 v[236:237], v105
	v_cvt_pk_f32_fp8_sdwa v[238:239], v105 src0_sel:WORD_1
	v_pk_fma_f32 v[220:221], v[56:57], v[236:237], v[220:221] op_sel:[1,0,0]
	v_pk_fma_f32 v[222:223], v[56:57], v[238:239], v[222:223] op_sel:[1,0,0]
	v_cvt_pk_f32_fp8_e32 v[232:233], v106
	v_cvt_pk_f32_fp8_sdwa v[234:235], v106 src0_sel:WORD_1
	v_pk_fma_f32 v[224:225], v[56:57], v[232:233], v[224:225] op_sel:[1,0,0]
	v_pk_fma_f32 v[226:227], v[56:57], v[234:235], v[226:227] op_sel:[1,0,0]
	v_cvt_pk_f32_fp8_e32 v[236:237], v107
	v_cvt_pk_f32_fp8_sdwa v[238:239], v107 src0_sel:WORD_1
	v_pk_fma_f32 v[228:229], v[56:57], v[236:237], v[228:229] op_sel:[1,0,0]
	v_pk_fma_f32 v[230:231], v[56:57], v[238:239], v[230:231] op_sel:[1,0,0]
	s_waitcnt vmcnt(25)
; DI f2_t cvt8lo(unsigned w) { return __builtin_amdgcn_cvt_pk_f32_fp8(w, false); }
; DI f2_t cvt8hi(unsigned w) { return __builtin_amdgcn_cvt_pk_f32_fp8(w, true); }
; DI void phase11(const Params& p, char* smem, int rep) {
;     ...
;         for (int k = 0; k < 16; ++k) rows[k] = *(const u32x4*)(vb + (size_t)ida[k] * 2048);
; #pragma unroll
;         for (int k = 0; k < 16; ++k) {
;           const f2_t a2 = {aa[k], aa[k]};
; #pragma unroll
;           for (int d = 0; d < 4; ++d) { const unsigned ww = rows[k][d]; o[2 * d] += a2 * cvt8lo(ww); o[2 * d + 1] += a2 * cvt8hi(ww); }
	v_cvt_pk_f32_fp8_e32 v[232:233], v108
	v_cvt_pk_f32_fp8_sdwa v[234:235], v108 src0_sel:WORD_1
	v_pk_fma_f32 v[216:217], v[58:59], v[232:233], v[216:217] op_sel_hi:[0,1,1]
	v_pk_fma_f32 v[218:219], v[58:59], v[234:235], v[218:219] op_sel_hi:[0,1,1]
	v_cvt_pk_f32_fp8_e32 v[236:237], v109
	v_cvt_pk_f32_fp8_sdwa v[238:239], v109 src0_sel:WORD_1
	v_pk_fma_f32 v[220:221], v[58:59], v[236:237], v[220:221] op_sel_hi:[0,1,1]
	v_pk_fma_f32 v[222:223], v[58:59], v[238:239], v[222:223] op_sel_hi:[0,1,1]
	v_cvt_pk_f32_fp8_e32 v[232:233], v110
	v_cvt_pk_f32_fp8_sdwa v[234:235], v110 src0_sel:WORD_1
	v_pk_fma_f32 v[224:225], v[58:59], v[232:233], v[224:225] op_sel_hi:[0,1,1]
	v_pk_fma_f32 v[226:227], v[58:59], v[234:235], v[226:227] op_sel_hi:[0,1,1]
	v_cvt_pk_f32_fp8_e32 v[236:237], v111
	v_cvt_pk_f32_fp8_sdwa v[238:239], v111 src0_sel:WORD_1
	v_pk_fma_f32 v[228:229], v[58:59], v[236:237], v[228:229] op_sel_hi:[0,1,1]
	v_pk_fma_f32 v[230:231], v[58:59], v[238:239], v[230:231] op_sel_hi:[0,1,1]
	s_waitcnt vmcnt(24)
	v_cvt_pk_f32_fp8_e32 v[232:233], v112
	v_cvt_pk_f32_fp8_sdwa v[234:235], v112 src0_sel:WORD_1
	v_pk_fma_f32 v[216:217], v[58:59], v[232:233], v[216:217] op_sel:[1,0,0]
	v_pk_fma_f32 v[218:219], v[58:59], v[234:235], v[218:219] op_sel:[1,0,0]
	v_cvt_pk_f32_fp8_e32 v[236:237], v113
	v_cvt_pk_f32_fp8_sdwa v[238:239], v113 src0_sel:WORD_1
	v_pk_fma_f32 v[220:221], v[58:59], v[236:237], v[220:221] op_sel:[1,0,0]
	v_pk_fma_f32 v[222:223], v[58:59], v[238:239], v[222:223] op_sel:[1,0,0]
	v_cvt_pk_f32_fp8_e32 v[232:233], v114
	v_cvt_pk_f32_fp8_sdwa v[234:235], v114 src0_sel:WORD_1
	v_pk_fma_f32 v[224:225], v[58:59], v[232:233], v[224:225] op_sel:[1,0,0]
	v_pk_fma_f32 v[226:227], v[58:59], v[234:235], v[226:227] op_sel:[1,0,0]
	v_cvt_pk_f32_fp8_e32 v[236:237], v115
	v_cvt_pk_f32_fp8_sdwa v[238:239], v115 src0_sel:WORD_1
	v_pk_fma_f32 v[228:229], v[58:59], v[236:237], v[228:229] op_sel:[1,0,0]
	v_pk_fma_f32 v[230:231], v[58:59], v[238:239], v[230:231] op_sel:[1,0,0]
	s_waitcnt vmcnt(23)
	v_cvt_pk_f32_fp8_e32 v[232:233], v116
	v_cvt_pk_f32_fp8_sdwa v[234:235], v116 src0_sel:WORD_1
	v_pk_fma_f32 v[216:217], v[60:61], v[232:233], v[216:217] op_sel_hi:[0,1,1]
	v_pk_fma_f32 v[218:219], v[60:61], v[234:235], v[218:219] op_sel_hi:[0,1,1]
	v_cvt_pk_f32_fp8_e32 v[236:237], v117
	v_cvt_pk_f32_fp8_sdwa v[238:239], v117 src0_sel:WORD_1
	v_pk_fma_f32 v[220:221], v[60:61], v[236:237], v[220:221] op_sel_hi:[0,1,1]
	v_pk_fma_f32 v[222:223], v[60:61], v[238:239], v[222:223] op_sel_hi:[0,1,1]
	v_cvt_pk_f32_fp8_e32 v[232:233], v118
	v_cvt_pk_f32_fp8_sdwa v[234:235], v118 src0_sel:WORD_1
	v_pk_fma_f32 v[224:225], v[60:61], v[232:233], v[224:225] op_sel_hi:[0,1,1]
	v_pk_fma_f32 v[226:227], v[60:61], v[234:235], v[226:227] op_sel_hi:[0,1,1]
	v_cvt_pk_f32_fp8_e32 v[236:237], v119
	v_cvt_pk_f32_fp8_sdwa v[238:239], v119 src0_sel:WORD_1
	v_pk_fma_f32 v[228:229], v[60:61], v[236:237], v[228:229] op_sel_hi:[0,1,1]
	v_pk_fma_f32 v[230:231], v[60:61], v[238:239], v[230:231] op_sel_hi:[0,1,1]
	s_waitcnt vmcnt(22)
	v_cvt_pk_f32_fp8_e32 v[232:233], v120
	v_cvt_pk_f32_fp8_sdwa v[234:235], v120 src0_sel:WORD_1
	v_pk_fma_f32 v[216:217], v[60:61], v[232:233], v[216:217] op_sel:[1,0,0]
	v_pk_fma_f32 v[218:219], v[60:61], v[234:235], v[218:219] op_sel:[1,0,0]
	v_cvt_pk_f32_fp8_e32 v[236:237], v121
	v_cvt_pk_f32_fp8_sdwa v[238:239], v121 src0_sel:WORD_1
	v_pk_fma_f32 v[220:221], v[60:61], v[236:237], v[220:221] op_sel:[1,0,0]
	v_pk_fma_f32 v[222:223], v[60:61], v[238:239], v[222:223] op_sel:[1,0,0]
	v_cvt_pk_f32_fp8_e32 v[232:233], v122
	v_cvt_pk_f32_fp8_sdwa v[234:235], v122 src0_sel:WORD_1
	v_pk_fma_f32 v[224:225], v[60:61], v[232:233], v[224:225] op_sel:[1,0,0]
	v_pk_fma_f32 v[226:227], v[60:61], v[234:235], v[226:227] op_sel:[1,0,0]
	v_cvt_pk_f32_fp8_e32 v[236:237], v123
	v_cvt_pk_f32_fp8_sdwa v[238:239], v123 src0_sel:WORD_1
	v_pk_fma_f32 v[228:229], v[60:61], v[236:237], v[228:229] op_sel:[1,0,0]
	v_pk_fma_f32 v[230:231], v[60:61], v[238:239], v[230:231] op_sel:[1,0,0]
	s_waitcnt vmcnt(21)
	v_cvt_pk_f32_fp8_e32 v[232:233], v124
	v_cvt_pk_f32_fp8_sdwa v[234:235], v124 src0_sel:WORD_1
	v_pk_fma_f32 v[216:217], v[62:63], v[232:233], v[216:217] op_sel_hi:[0,1,1]
	v_pk_fma_f32 v[218:219], v[62:63], v[234:235], v[218:219] op_sel_hi:[0,1,1]
	v_cvt_pk_f32_fp8_e32 v[236:237], v125
	v_cvt_pk_f32_fp8_sdwa v[238:239], v125 src0_sel:WORD_1
	v_pk_fma_f32 v[220:221], v[62:63], v[236:237], v[220:221] op_sel_hi:[0,1,1]
	v_pk_fma_f32 v[222:223], v[62:63], v[238:239], v[222:223] op_sel_hi:[0,1,1]
	v_cvt_pk_f32_fp8_e32 v[232:233], v126
	v_cvt_pk_f32_fp8_sdwa v[234:235], v126 src0_sel:WORD_1
	v_pk_fma_f32 v[224:225], v[62:63], v[232:233], v[224:225] op_sel_hi:[0,1,1]
	v_pk_fma_f32 v[226:227], v[62:63], v[234:235], v[226:227] op_sel_hi:[0,1,1]
	v_cvt_pk_f32_fp8_e32 v[236:237], v127
	v_cvt_pk_f32_fp8_sdwa v[238:239], v127 src0_sel:WORD_1
	v_pk_fma_f32 v[228:229], v[62:63], v[236:237], v[228:229] op_sel_hi:[0,1,1]
	v_pk_fma_f32 v[230:231], v[62:63], v[238:239], v[230:231] op_sel_hi:[0,1,1]
	s_waitcnt vmcnt(20)
	v_cvt_pk_f32_fp8_e32 v[232:233], v128
	v_cvt_pk_f32_fp8_sdwa v[234:235], v128 src0_sel:WORD_1
	v_pk_fma_f32 v[216:217], v[62:63], v[232:233], v[216:217] op_sel:[1,0,0]
	v_pk_fma_f32 v[218:219], v[62:63], v[234:235], v[218:219] op_sel:[1,0,0]
	v_cvt_pk_f32_fp8_e32 v[236:237], v129
	v_cvt_pk_f32_fp8_sdwa v[238:239], v129 src0_sel:WORD_1
	v_pk_fma_f32 v[220:221], v[62:63], v[236:237], v[220:221] op_sel:[1,0,0]
	v_pk_fma_f32 v[222:223], v[62:63], v[238:239], v[222:223] op_sel:[1,0,0]
	v_cvt_pk_f32_fp8_e32 v[232:233], v130
	v_cvt_pk_f32_fp8_sdwa v[234:235], v130 src0_sel:WORD_1
	v_pk_fma_f32 v[224:225], v[62:63], v[232:233], v[224:225] op_sel:[1,0,0]
	v_pk_fma_f32 v[226:227], v[62:63], v[234:235], v[226:227] op_sel:[1,0,0]
	v_cvt_pk_f32_fp8_e32 v[236:237], v131
	v_cvt_pk_f32_fp8_sdwa v[238:239], v131 src0_sel:WORD_1
	v_pk_fma_f32 v[228:229], v[62:63], v[236:237], v[228:229] op_sel:[1,0,0]
	v_pk_fma_f32 v[230:231], v[62:63], v[238:239], v[230:231] op_sel:[1,0,0]
	s_waitcnt vmcnt(19)
; DI f2_t cvt8lo(unsigned w) { return __builtin_amdgcn_cvt_pk_f32_fp8(w, false); }
; DI f2_t cvt8hi(unsigned w) { return __builtin_amdgcn_cvt_pk_f32_fp8(w, true); }
; DI void wave_lds_sync() { asm volatile("s_waitcnt lgkmcnt(0)" ::: "memory"); __builtin_amdgcn_wave_barrier(); }
; DI void phase11(const Params& p, char* smem, int rep) {
;     ...
;       wave_lds_sync();
;       lw[(lane & 3) * 32 + (lane >> 2)] = i0; lw[(lane & 3) * 32 + 16 + (lane >> 2)] = i1;
;       lf[(lane & 3) * 32 + (lane >> 2)] = a0; lf[(lane & 3) * 32 + 16 + (lane >> 2)] = a1;
;       wave_lds_sync();
;     ...
;         for (int k = 0; k < 16; ++k) rows[k] = *(const u32x4*)(vb + (size_t)ida[k] * 2048);
; #pragma unroll
;         for (int k = 0; k < 16; ++k) {
;           const f2_t a2 = {aa[k], aa[k]};
; #pragma unroll
;           for (int d = 0; d < 4; ++d) { const unsigned ww = rows[k][d]; o[2 * d] += a2 * cvt8lo(ww); o[2 * d + 1] += a2 * cvt8hi(ww); }
	v_cvt_pk_f32_fp8_e32 v[232:233], v132
	v_cvt_pk_f32_fp8_sdwa v[234:235], v132 src0_sel:WORD_1
	v_pk_fma_f32 v[216:217], v[64:65], v[232:233], v[216:217] op_sel_hi:[0,1,1]
	v_pk_fma_f32 v[218:219], v[64:65], v[234:235], v[218:219] op_sel_hi:[0,1,1]
	v_cvt_pk_f32_fp8_e32 v[236:237], v133
	v_cvt_pk_f32_fp8_sdwa v[238:239], v133 src0_sel:WORD_1
	v_pk_fma_f32 v[220:221], v[64:65], v[236:237], v[220:221] op_sel_hi:[0,1,1]
	v_pk_fma_f32 v[222:223], v[64:65], v[238:239], v[222:223] op_sel_hi:[0,1,1]
	v_cvt_pk_f32_fp8_e32 v[232:233], v134
	v_cvt_pk_f32_fp8_sdwa v[234:235], v134 src0_sel:WORD_1
	v_pk_fma_f32 v[224:225], v[64:65], v[232:233], v[224:225] op_sel_hi:[0,1,1]
	v_pk_fma_f32 v[226:227], v[64:65], v[234:235], v[226:227] op_sel_hi:[0,1,1]
	v_cvt_pk_f32_fp8_e32 v[236:237], v135
	v_cvt_pk_f32_fp8_sdwa v[238:239], v135 src0_sel:WORD_1
	v_pk_fma_f32 v[228:229], v[64:65], v[236:237], v[228:229] op_sel_hi:[0,1,1]
	v_pk_fma_f32 v[230:231], v[64:65], v[238:239], v[230:231] op_sel_hi:[0,1,1]
	s_waitcnt vmcnt(18)
	v_cvt_pk_f32_fp8_e32 v[232:233], v136
	v_cvt_pk_f32_fp8_sdwa v[234:235], v136 src0_sel:WORD_1
	v_pk_fma_f32 v[216:217], v[64:65], v[232:233], v[216:217] op_sel:[1,0,0]
	v_pk_fma_f32 v[218:219], v[64:65], v[234:235], v[218:219] op_sel:[1,0,0]
	v_cvt_pk_f32_fp8_e32 v[236:237], v137
	v_cvt_pk_f32_fp8_sdwa v[238:239], v137 src0_sel:WORD_1
	v_pk_fma_f32 v[220:221], v[64:65], v[236:237], v[220:221] op_sel:[1,0,0]
	v_pk_fma_f32 v[222:223], v[64:65], v[238:239], v[222:223] op_sel:[1,0,0]
	v_cvt_pk_f32_fp8_e32 v[232:233], v138
	v_cvt_pk_f32_fp8_sdwa v[234:235], v138 src0_sel:WORD_1
	v_pk_fma_f32 v[224:225], v[64:65], v[232:233], v[224:225] op_sel:[1,0,0]
	v_pk_fma_f32 v[226:227], v[64:65], v[234:235], v[226:227] op_sel:[1,0,0]
	v_cvt_pk_f32_fp8_e32 v[236:237], v139
	v_cvt_pk_f32_fp8_sdwa v[238:239], v139 src0_sel:WORD_1
	v_pk_fma_f32 v[228:229], v[64:65], v[236:237], v[228:229] op_sel:[1,0,0]
	v_pk_fma_f32 v[230:231], v[64:65], v[238:239], v[230:231] op_sel:[1,0,0]
	s_waitcnt vmcnt(17)
	v_cvt_pk_f32_fp8_e32 v[232:233], v140
	v_cvt_pk_f32_fp8_sdwa v[234:235], v140 src0_sel:WORD_1
	v_pk_fma_f32 v[216:217], v[66:67], v[232:233], v[216:217] op_sel_hi:[0,1,1]
	v_pk_fma_f32 v[218:219], v[66:67], v[234:235], v[218:219] op_sel_hi:[0,1,1]
	v_cvt_pk_f32_fp8_e32 v[236:237], v141
	v_cvt_pk_f32_fp8_sdwa v[238:239], v141 src0_sel:WORD_1
	v_pk_fma_f32 v[220:221], v[66:67], v[236:237], v[220:221] op_sel_hi:[0,1,1]
	v_pk_fma_f32 v[222:223], v[66:67], v[238:239], v[222:223] op_sel_hi:[0,1,1]
	v_cvt_pk_f32_fp8_e32 v[232:233], v142
	v_cvt_pk_f32_fp8_sdwa v[234:235], v142 src0_sel:WORD_1
	v_pk_fma_f32 v[224:225], v[66:67], v[232:233], v[224:225] op_sel_hi:[0,1,1]
	v_pk_fma_f32 v[226:227], v[66:67], v[234:235], v[226:227] op_sel_hi:[0,1,1]
	v_cvt_pk_f32_fp8_e32 v[236:237], v143
	v_cvt_pk_f32_fp8_sdwa v[238:239], v143 src0_sel:WORD_1
	v_pk_fma_f32 v[228:229], v[66:67], v[236:237], v[228:229] op_sel_hi:[0,1,1]
	v_pk_fma_f32 v[230:231], v[66:67], v[238:239], v[230:231] op_sel_hi:[0,1,1]
	s_waitcnt vmcnt(16)
	v_cvt_pk_f32_fp8_e32 v[232:233], v144
	v_cvt_pk_f32_fp8_sdwa v[234:235], v144 src0_sel:WORD_1
	v_pk_fma_f32 v[216:217], v[66:67], v[232:233], v[216:217] op_sel:[1,0,0]
	v_pk_fma_f32 v[218:219], v[66:67], v[234:235], v[218:219] op_sel:[1,0,0]
	v_cvt_pk_f32_fp8_e32 v[236:237], v145
	v_cvt_pk_f32_fp8_sdwa v[238:239], v145 src0_sel:WORD_1
	v_pk_fma_f32 v[220:221], v[66:67], v[236:237], v[220:221] op_sel:[1,0,0]
	v_pk_fma_f32 v[222:223], v[66:67], v[238:239], v[222:223] op_sel:[1,0,0]
	v_cvt_pk_f32_fp8_e32 v[232:233], v146
	v_cvt_pk_f32_fp8_sdwa v[234:235], v146 src0_sel:WORD_1
	v_pk_fma_f32 v[224:225], v[66:67], v[232:233], v[224:225] op_sel:[1,0,0]
	v_pk_fma_f32 v[226:227], v[66:67], v[234:235], v[226:227] op_sel:[1,0,0]
	v_cvt_pk_f32_fp8_e32 v[236:237], v147
	v_cvt_pk_f32_fp8_sdwa v[238:239], v147 src0_sel:WORD_1
	v_pk_fma_f32 v[228:229], v[66:67], v[236:237], v[228:229] op_sel:[1,0,0]
	v_pk_fma_f32 v[230:231], v[66:67], v[238:239], v[230:231] op_sel:[1,0,0]
	ds_write2_b32 v5, v10, v11 offset0:4 offset1:20
	ds_write2_b32 v5, v12, v13 offset0:132 offset1:148
	s_waitcnt lgkmcnt(0)
	ds_read_b128 v[20:23], v6 offset:16
	ds_read_b128 v[24:27], v6 offset:32
	ds_read_b128 v[28:31], v6 offset:48
	ds_read_b128 v[32:35], v6 offset:64
	ds_read_b128 v[36:39], v6 offset:80
	ds_read_b128 v[40:43], v6 offset:96
	ds_read_b128 v[44:47], v6 offset:112
	ds_read_b128 v[48:51], v6 offset:128
	s_waitcnt vmcnt(15)
	v_cvt_pk_f32_fp8_e32 v[232:233], v148
	v_cvt_pk_f32_fp8_sdwa v[234:235], v148 src0_sel:WORD_1
	v_pk_fma_f32 v[216:217], v[68:69], v[232:233], v[216:217] op_sel_hi:[0,1,1]
	v_pk_fma_f32 v[218:219], v[68:69], v[234:235], v[218:219] op_sel_hi:[0,1,1]
	v_cvt_pk_f32_fp8_e32 v[236:237], v149
	v_cvt_pk_f32_fp8_sdwa v[238:239], v149 src0_sel:WORD_1
	v_pk_fma_f32 v[220:221], v[68:69], v[236:237], v[220:221] op_sel_hi:[0,1,1]
	v_pk_fma_f32 v[222:223], v[68:69], v[238:239], v[222:223] op_sel_hi:[0,1,1]
	v_cvt_pk_f32_fp8_e32 v[232:233], v150
	v_cvt_pk_f32_fp8_sdwa v[234:235], v150 src0_sel:WORD_1
	v_pk_fma_f32 v[224:225], v[68:69], v[232:233], v[224:225] op_sel_hi:[0,1,1]
	v_pk_fma_f32 v[226:227], v[68:69], v[234:235], v[226:227] op_sel_hi:[0,1,1]
	v_cvt_pk_f32_fp8_e32 v[236:237], v151
	v_cvt_pk_f32_fp8_sdwa v[238:239], v151 src0_sel:WORD_1
	v_pk_fma_f32 v[228:229], v[68:69], v[236:237], v[228:229] op_sel_hi:[0,1,1]
	v_pk_fma_f32 v[230:231], v[68:69], v[238:239], v[230:231] op_sel_hi:[0,1,1]
	s_waitcnt vmcnt(14)
; DI f2_t cvt8lo(unsigned w) { return __builtin_amdgcn_cvt_pk_f32_fp8(w, false); }
; DI f2_t cvt8hi(unsigned w) { return __builtin_amdgcn_cvt_pk_f32_fp8(w, true); }
; DI void phase11(const Params& p, char* smem, int rep) {
;     ...
;         for (int k = 0; k < 16; ++k) rows[k] = *(const u32x4*)(vb + (size_t)ida[k] * 2048);
; #pragma unroll
;         for (int k = 0; k < 16; ++k) {
;           const f2_t a2 = {aa[k], aa[k]};
; #pragma unroll
;           for (int d = 0; d < 4; ++d) { const unsigned ww = rows[k][d]; o[2 * d] += a2 * cvt8lo(ww); o[2 * d + 1] += a2 * cvt8hi(ww); }
	v_cvt_pk_f32_fp8_e32 v[232:233], v152
	v_cvt_pk_f32_fp8_sdwa v[234:235], v152 src0_sel:WORD_1
	v_pk_fma_f32 v[216:217], v[68:69], v[232:233], v[216:217] op_sel:[1,0,0]
	v_pk_fma_f32 v[218:219], v[68:69], v[234:235], v[218:219] op_sel:[1,0,0]
	v_cvt_pk_f32_fp8_e32 v[236:237], v153
	v_cvt_pk_f32_fp8_sdwa v[238:239], v153 src0_sel:WORD_1
	v_pk_fma_f32 v[220:221], v[68:69], v[236:237], v[220:221] op_sel:[1,0,0]
	v_pk_fma_f32 v[222:223], v[68:69], v[238:239], v[222:223] op_sel:[1,0,0]
	v_cvt_pk_f32_fp8_e32 v[232:233], v154
	v_cvt_pk_f32_fp8_sdwa v[234:235], v154 src0_sel:WORD_1
	v_pk_fma_f32 v[224:225], v[68:69], v[232:233], v[224:225] op_sel:[1,0,0]
	v_pk_fma_f32 v[226:227], v[68:69], v[234:235], v[226:227] op_sel:[1,0,0]
	v_cvt_pk_f32_fp8_e32 v[236:237], v155
	v_cvt_pk_f32_fp8_sdwa v[238:239], v155 src0_sel:WORD_1
	v_pk_fma_f32 v[228:229], v[68:69], v[236:237], v[228:229] op_sel:[1,0,0]
	v_pk_fma_f32 v[230:231], v[68:69], v[238:239], v[230:231] op_sel:[1,0,0]
	s_waitcnt vmcnt(13)
	v_cvt_pk_f32_fp8_e32 v[232:233], v156
	v_cvt_pk_f32_fp8_sdwa v[234:235], v156 src0_sel:WORD_1
	v_pk_fma_f32 v[216:217], v[70:71], v[232:233], v[216:217] op_sel_hi:[0,1,1]
	v_pk_fma_f32 v[218:219], v[70:71], v[234:235], v[218:219] op_sel_hi:[0,1,1]
	v_cvt_pk_f32_fp8_e32 v[236:237], v157
	v_cvt_pk_f32_fp8_sdwa v[238:239], v157 src0_sel:WORD_1
	v_pk_fma_f32 v[220:221], v[70:71], v[236:237], v[220:221] op_sel_hi:[0,1,1]
	v_pk_fma_f32 v[222:223], v[70:71], v[238:239], v[222:223] op_sel_hi:[0,1,1]
	v_cvt_pk_f32_fp8_e32 v[232:233], v158
	v_cvt_pk_f32_fp8_sdwa v[234:235], v158 src0_sel:WORD_1
	v_pk_fma_f32 v[224:225], v[70:71], v[232:233], v[224:225] op_sel_hi:[0,1,1]
	v_pk_fma_f32 v[226:227], v[70:71], v[234:235], v[226:227] op_sel_hi:[0,1,1]
	v_cvt_pk_f32_fp8_e32 v[236:237], v159
	v_cvt_pk_f32_fp8_sdwa v[238:239], v159 src0_sel:WORD_1
	v_pk_fma_f32 v[228:229], v[70:71], v[236:237], v[228:229] op_sel_hi:[0,1,1]
	v_pk_fma_f32 v[230:231], v[70:71], v[238:239], v[230:231] op_sel_hi:[0,1,1]
	s_waitcnt vmcnt(12)
	v_cvt_pk_f32_fp8_e32 v[232:233], v160
	v_cvt_pk_f32_fp8_sdwa v[234:235], v160 src0_sel:WORD_1
	v_pk_fma_f32 v[216:217], v[70:71], v[232:233], v[216:217] op_sel:[1,0,0]
	v_pk_fma_f32 v[218:219], v[70:71], v[234:235], v[218:219] op_sel:[1,0,0]
	v_cvt_pk_f32_fp8_e32 v[236:237], v161
	v_cvt_pk_f32_fp8_sdwa v[238:239], v161 src0_sel:WORD_1
	v_pk_fma_f32 v[220:221], v[70:71], v[236:237], v[220:221] op_sel:[1,0,0]
	v_pk_fma_f32 v[222:223], v[70:71], v[238:239], v[222:223] op_sel:[1,0,0]
	v_cvt_pk_f32_fp8_e32 v[232:233], v162
	v_cvt_pk_f32_fp8_sdwa v[234:235], v162 src0_sel:WORD_1
	v_pk_fma_f32 v[224:225], v[70:71], v[232:233], v[224:225] op_sel:[1,0,0]
	v_pk_fma_f32 v[226:227], v[70:71], v[234:235], v[226:227] op_sel:[1,0,0]
	v_cvt_pk_f32_fp8_e32 v[236:237], v163
	v_cvt_pk_f32_fp8_sdwa v[238:239], v163 src0_sel:WORD_1
	v_pk_fma_f32 v[228:229], v[70:71], v[236:237], v[228:229] op_sel:[1,0,0]
	v_pk_fma_f32 v[230:231], v[70:71], v[238:239], v[230:231] op_sel:[1,0,0]
	s_waitcnt vmcnt(11)
	v_cvt_pk_f32_fp8_e32 v[232:233], v164
	v_cvt_pk_f32_fp8_sdwa v[234:235], v164 src0_sel:WORD_1
	v_pk_fma_f32 v[216:217], v[72:73], v[232:233], v[216:217] op_sel_hi:[0,1,1]
	v_pk_fma_f32 v[218:219], v[72:73], v[234:235], v[218:219] op_sel_hi:[0,1,1]
	v_cvt_pk_f32_fp8_e32 v[236:237], v165
	v_cvt_pk_f32_fp8_sdwa v[238:239], v165 src0_sel:WORD_1
	v_pk_fma_f32 v[220:221], v[72:73], v[236:237], v[220:221] op_sel_hi:[0,1,1]
	v_pk_fma_f32 v[222:223], v[72:73], v[238:239], v[222:223] op_sel_hi:[0,1,1]
	v_cvt_pk_f32_fp8_e32 v[232:233], v166
	v_cvt_pk_f32_fp8_sdwa v[234:235], v166 src0_sel:WORD_1
	v_pk_fma_f32 v[224:225], v[72:73], v[232:233], v[224:225] op_sel_hi:[0,1,1]
	v_pk_fma_f32 v[226:227], v[72:73], v[234:235], v[226:227] op_sel_hi:[0,1,1]
	v_cvt_pk_f32_fp8_e32 v[236:237], v167
	v_cvt_pk_f32_fp8_sdwa v[238:239], v167 src0_sel:WORD_1
	v_pk_fma_f32 v[228:229], v[72:73], v[236:237], v[228:229] op_sel_hi:[0,1,1]
	v_pk_fma_f32 v[230:231], v[72:73], v[238:239], v[230:231] op_sel_hi:[0,1,1]
	s_waitcnt vmcnt(10)
	v_cvt_pk_f32_fp8_e32 v[232:233], v168
	v_cvt_pk_f32_fp8_sdwa v[234:235], v168 src0_sel:WORD_1
	v_pk_fma_f32 v[216:217], v[72:73], v[232:233], v[216:217] op_sel:[1,0,0]
	v_pk_fma_f32 v[218:219], v[72:73], v[234:235], v[218:219] op_sel:[1,0,0]
	v_cvt_pk_f32_fp8_e32 v[236:237], v169
	v_cvt_pk_f32_fp8_sdwa v[238:239], v169 src0_sel:WORD_1
	v_pk_fma_f32 v[220:221], v[72:73], v[236:237], v[220:221] op_sel:[1,0,0]
	v_pk_fma_f32 v[222:223], v[72:73], v[238:239], v[222:223] op_sel:[1,0,0]
	v_cvt_pk_f32_fp8_e32 v[232:233], v170
	v_cvt_pk_f32_fp8_sdwa v[234:235], v170 src0_sel:WORD_1
	v_pk_fma_f32 v[224:225], v[72:73], v[232:233], v[224:225] op_sel:[1,0,0]
	v_pk_fma_f32 v[226:227], v[72:73], v[234:235], v[226:227] op_sel:[1,0,0]
	v_cvt_pk_f32_fp8_e32 v[236:237], v171
	v_cvt_pk_f32_fp8_sdwa v[238:239], v171 src0_sel:WORD_1
	v_pk_fma_f32 v[228:229], v[72:73], v[236:237], v[228:229] op_sel:[1,0,0]
	v_pk_fma_f32 v[230:231], v[72:73], v[238:239], v[230:231] op_sel:[1,0,0]
	s_waitcnt vmcnt(9)
	v_cvt_pk_f32_fp8_e32 v[232:233], v172
	v_cvt_pk_f32_fp8_sdwa v[234:235], v172 src0_sel:WORD_1
	v_pk_fma_f32 v[216:217], v[74:75], v[232:233], v[216:217] op_sel_hi:[0,1,1]
	v_pk_fma_f32 v[218:219], v[74:75], v[234:235], v[218:219] op_sel_hi:[0,1,1]
	v_cvt_pk_f32_fp8_e32 v[236:237], v173
	v_cvt_pk_f32_fp8_sdwa v[238:239], v173 src0_sel:WORD_1
	v_pk_fma_f32 v[220:221], v[74:75], v[236:237], v[220:221] op_sel_hi:[0,1,1]
	v_pk_fma_f32 v[222:223], v[74:75], v[238:239], v[222:223] op_sel_hi:[0,1,1]
	v_cvt_pk_f32_fp8_e32 v[232:233], v174
	v_cvt_pk_f32_fp8_sdwa v[234:235], v174 src0_sel:WORD_1
	v_pk_fma_f32 v[224:225], v[74:75], v[232:233], v[224:225] op_sel_hi:[0,1,1]
	v_pk_fma_f32 v[226:227], v[74:75], v[234:235], v[226:227] op_sel_hi:[0,1,1]
	v_cvt_pk_f32_fp8_e32 v[236:237], v175
	v_cvt_pk_f32_fp8_sdwa v[238:239], v175 src0_sel:WORD_1
	v_pk_fma_f32 v[228:229], v[74:75], v[236:237], v[228:229] op_sel_hi:[0,1,1]
	v_pk_fma_f32 v[230:231], v[74:75], v[238:239], v[230:231] op_sel_hi:[0,1,1]
	s_waitcnt vmcnt(8)
; DI f2_t cvt8lo(unsigned w) { return __builtin_amdgcn_cvt_pk_f32_fp8(w, false); }
; DI f2_t cvt8hi(unsigned w) { return __builtin_amdgcn_cvt_pk_f32_fp8(w, true); }
; DI void phase11(const Params& p, char* smem, int rep) {
;     ...
;         for (int k = 0; k < 16; ++k) rows[k] = *(const u32x4*)(vb + (size_t)ida[k] * 2048);
; #pragma unroll
;         for (int k = 0; k < 16; ++k) {
;           const f2_t a2 = {aa[k], aa[k]};
; #pragma unroll
;           for (int d = 0; d < 4; ++d) { const unsigned ww = rows[k][d]; o[2 * d] += a2 * cvt8lo(ww); o[2 * d + 1] += a2 * cvt8hi(ww); }
	v_cvt_pk_f32_fp8_e32 v[232:233], v176
	v_cvt_pk_f32_fp8_sdwa v[234:235], v176 src0_sel:WORD_1
	v_pk_fma_f32 v[216:217], v[74:75], v[232:233], v[216:217] op_sel:[1,0,0]
	v_pk_fma_f32 v[218:219], v[74:75], v[234:235], v[218:219] op_sel:[1,0,0]
	v_cvt_pk_f32_fp8_e32 v[236:237], v177
	v_cvt_pk_f32_fp8_sdwa v[238:239], v177 src0_sel:WORD_1
	v_pk_fma_f32 v[220:221], v[74:75], v[236:237], v[220:221] op_sel:[1,0,0]
	v_pk_fma_f32 v[222:223], v[74:75], v[238:239], v[222:223] op_sel:[1,0,0]
	v_cvt_pk_f32_fp8_e32 v[232:233], v178
	v_cvt_pk_f32_fp8_sdwa v[234:235], v178 src0_sel:WORD_1
	v_pk_fma_f32 v[224:225], v[74:75], v[232:233], v[224:225] op_sel:[1,0,0]
	v_pk_fma_f32 v[226:227], v[74:75], v[234:235], v[226:227] op_sel:[1,0,0]
	v_cvt_pk_f32_fp8_e32 v[236:237], v179
	v_cvt_pk_f32_fp8_sdwa v[238:239], v179 src0_sel:WORD_1
	v_pk_fma_f32 v[228:229], v[74:75], v[236:237], v[228:229] op_sel:[1,0,0]
	v_pk_fma_f32 v[230:231], v[74:75], v[238:239], v[230:231] op_sel:[1,0,0]
	s_waitcnt vmcnt(7)
	v_cvt_pk_f32_fp8_e32 v[232:233], v180
	v_cvt_pk_f32_fp8_sdwa v[234:235], v180 src0_sel:WORD_1
	v_pk_fma_f32 v[216:217], v[76:77], v[232:233], v[216:217] op_sel_hi:[0,1,1]
	v_pk_fma_f32 v[218:219], v[76:77], v[234:235], v[218:219] op_sel_hi:[0,1,1]
	v_cvt_pk_f32_fp8_e32 v[236:237], v181
	v_cvt_pk_f32_fp8_sdwa v[238:239], v181 src0_sel:WORD_1
	v_pk_fma_f32 v[220:221], v[76:77], v[236:237], v[220:221] op_sel_hi:[0,1,1]
	v_pk_fma_f32 v[222:223], v[76:77], v[238:239], v[222:223] op_sel_hi:[0,1,1]
	v_cvt_pk_f32_fp8_e32 v[232:233], v182
	v_cvt_pk_f32_fp8_sdwa v[234:235], v182 src0_sel:WORD_1
	v_pk_fma_f32 v[224:225], v[76:77], v[232:233], v[224:225] op_sel_hi:[0,1,1]
	v_pk_fma_f32 v[226:227], v[76:77], v[234:235], v[226:227] op_sel_hi:[0,1,1]
	v_cvt_pk_f32_fp8_e32 v[236:237], v183
	v_cvt_pk_f32_fp8_sdwa v[238:239], v183 src0_sel:WORD_1
	v_pk_fma_f32 v[228:229], v[76:77], v[236:237], v[228:229] op_sel_hi:[0,1,1]
	v_pk_fma_f32 v[230:231], v[76:77], v[238:239], v[230:231] op_sel_hi:[0,1,1]
	s_waitcnt vmcnt(6)
	v_cvt_pk_f32_fp8_e32 v[232:233], v184
	v_cvt_pk_f32_fp8_sdwa v[234:235], v184 src0_sel:WORD_1
	v_pk_fma_f32 v[216:217], v[76:77], v[232:233], v[216:217] op_sel:[1,0,0]
	v_pk_fma_f32 v[218:219], v[76:77], v[234:235], v[218:219] op_sel:[1,0,0]
	v_cvt_pk_f32_fp8_e32 v[236:237], v185
	v_cvt_pk_f32_fp8_sdwa v[238:239], v185 src0_sel:WORD_1
	v_pk_fma_f32 v[220:221], v[76:77], v[236:237], v[220:221] op_sel:[1,0,0]
	v_pk_fma_f32 v[222:223], v[76:77], v[238:239], v[222:223] op_sel:[1,0,0]
	v_cvt_pk_f32_fp8_e32 v[232:233], v186
	v_cvt_pk_f32_fp8_sdwa v[234:235], v186 src0_sel:WORD_1
	v_pk_fma_f32 v[224:225], v[76:77], v[232:233], v[224:225] op_sel:[1,0,0]
	v_pk_fma_f32 v[226:227], v[76:77], v[234:235], v[226:227] op_sel:[1,0,0]
	v_cvt_pk_f32_fp8_e32 v[236:237], v187
	v_cvt_pk_f32_fp8_sdwa v[238:239], v187 src0_sel:WORD_1
	v_pk_fma_f32 v[228:229], v[76:77], v[236:237], v[228:229] op_sel:[1,0,0]
	v_pk_fma_f32 v[230:231], v[76:77], v[238:239], v[230:231] op_sel:[1,0,0]
	s_waitcnt vmcnt(5)
	v_cvt_pk_f32_fp8_e32 v[232:233], v190
	v_cvt_pk_f32_fp8_sdwa v[234:235], v190 src0_sel:WORD_1
	v_pk_fma_f32 v[216:217], v[78:79], v[232:233], v[216:217] op_sel_hi:[0,1,1]
	v_pk_fma_f32 v[218:219], v[78:79], v[234:235], v[218:219] op_sel_hi:[0,1,1]
	v_cvt_pk_f32_fp8_e32 v[236:237], v191
	v_cvt_pk_f32_fp8_sdwa v[238:239], v191 src0_sel:WORD_1
	v_pk_fma_f32 v[220:221], v[78:79], v[236:237], v[220:221] op_sel_hi:[0,1,1]
	v_pk_fma_f32 v[222:223], v[78:79], v[238:239], v[222:223] op_sel_hi:[0,1,1]
	v_cvt_pk_f32_fp8_e32 v[232:233], v192
	v_cvt_pk_f32_fp8_sdwa v[234:235], v192 src0_sel:WORD_1
	v_pk_fma_f32 v[224:225], v[78:79], v[232:233], v[224:225] op_sel_hi:[0,1,1]
	v_pk_fma_f32 v[226:227], v[78:79], v[234:235], v[226:227] op_sel_hi:[0,1,1]
	v_cvt_pk_f32_fp8_e32 v[236:237], v193
	v_cvt_pk_f32_fp8_sdwa v[238:239], v193 src0_sel:WORD_1
	v_pk_fma_f32 v[228:229], v[78:79], v[236:237], v[228:229] op_sel_hi:[0,1,1]
	v_pk_fma_f32 v[230:231], v[78:79], v[238:239], v[230:231] op_sel_hi:[0,1,1]
	s_waitcnt vmcnt(4)
	v_cvt_pk_f32_fp8_e32 v[232:233], v194
	v_cvt_pk_f32_fp8_sdwa v[234:235], v194 src0_sel:WORD_1
	v_pk_fma_f32 v[216:217], v[78:79], v[232:233], v[216:217] op_sel:[1,0,0]
	v_pk_fma_f32 v[218:219], v[78:79], v[234:235], v[218:219] op_sel:[1,0,0]
	v_cvt_pk_f32_fp8_e32 v[236:237], v195
	v_cvt_pk_f32_fp8_sdwa v[238:239], v195 src0_sel:WORD_1
	v_pk_fma_f32 v[220:221], v[78:79], v[236:237], v[220:221] op_sel:[1,0,0]
	v_pk_fma_f32 v[222:223], v[78:79], v[238:239], v[222:223] op_sel:[1,0,0]
	v_cvt_pk_f32_fp8_e32 v[232:233], v196
	v_cvt_pk_f32_fp8_sdwa v[234:235], v196 src0_sel:WORD_1
	v_pk_fma_f32 v[224:225], v[78:79], v[232:233], v[224:225] op_sel:[1,0,0]
	v_pk_fma_f32 v[226:227], v[78:79], v[234:235], v[226:227] op_sel:[1,0,0]
	v_cvt_pk_f32_fp8_e32 v[236:237], v197
	v_cvt_pk_f32_fp8_sdwa v[238:239], v197 src0_sel:WORD_1
	v_pk_fma_f32 v[228:229], v[78:79], v[236:237], v[228:229] op_sel:[1,0,0]
	v_pk_fma_f32 v[230:231], v[78:79], v[238:239], v[230:231] op_sel:[1,0,0]
	s_waitcnt vmcnt(3)
	v_cvt_pk_f32_fp8_e32 v[232:233], v198
	v_cvt_pk_f32_fp8_sdwa v[234:235], v198 src0_sel:WORD_1
	v_pk_fma_f32 v[216:217], v[80:81], v[232:233], v[216:217] op_sel_hi:[0,1,1]
	v_pk_fma_f32 v[218:219], v[80:81], v[234:235], v[218:219] op_sel_hi:[0,1,1]
	v_cvt_pk_f32_fp8_e32 v[236:237], v199
	v_cvt_pk_f32_fp8_sdwa v[238:239], v199 src0_sel:WORD_1
	v_pk_fma_f32 v[220:221], v[80:81], v[236:237], v[220:221] op_sel_hi:[0,1,1]
	v_pk_fma_f32 v[222:223], v[80:81], v[238:239], v[222:223] op_sel_hi:[0,1,1]
	v_cvt_pk_f32_fp8_e32 v[232:233], v200
	v_cvt_pk_f32_fp8_sdwa v[234:235], v200 src0_sel:WORD_1
	v_pk_fma_f32 v[224:225], v[80:81], v[232:233], v[224:225] op_sel_hi:[0,1,1]
	v_pk_fma_f32 v[226:227], v[80:81], v[234:235], v[226:227] op_sel_hi:[0,1,1]
	v_cvt_pk_f32_fp8_e32 v[236:237], v201
	v_cvt_pk_f32_fp8_sdwa v[238:239], v201 src0_sel:WORD_1
	v_pk_fma_f32 v[228:229], v[80:81], v[236:237], v[228:229] op_sel_hi:[0,1,1]
	v_pk_fma_f32 v[230:231], v[80:81], v[238:239], v[230:231] op_sel_hi:[0,1,1]
	s_waitcnt vmcnt(2)
; DI unsigned pk2(float a, float b) { f2_t v = {a, b}; bf2_t r = __builtin_convertvector(v, bf2_t); return __builtin_bit_cast(unsigned, r); }
; DI f2_t cvt8lo(unsigned w) { return __builtin_amdgcn_cvt_pk_f32_fp8(w, false); }
; DI f2_t cvt8hi(unsigned w) { return __builtin_amdgcn_cvt_pk_f32_fp8(w, true); }
; DI void wave_lds_sync() { asm volatile("s_waitcnt lgkmcnt(0)" ::: "memory"); __builtin_amdgcn_wave_barrier(); }
; DI void phase11(const Params& p, char* smem, int rep) {
;     ...
;       const int tok = __builtin_amdgcn_readfirstlane(c * 16 + w * 4 + t);
;       const int i0 = IDS[(size_t)tok * 128 + lane], i1 = IDS[(size_t)tok * 128 + 64 + lane];
;       const float a0 = ACT[(size_t)tok * 128 + lane], a1 = ACT[(size_t)tok * 128 + 64 + lane];
;       wave_lds_sync();
;       lw[(lane & 3) * 32 + (lane >> 2)] = i0; lw[(lane & 3) * 32 + 16 + (lane >> 2)] = i1;
;       lf[(lane & 3) * 32 + (lane >> 2)] = a0; lf[(lane & 3) * 32 + 16 + (lane >> 2)] = a1;
;       wave_lds_sync();
;     ...
;         for (int k = 0; k < 16; ++k) rows[k] = *(const u32x4*)(vb + (size_t)ida[k] * 2048);
; #pragma unroll
;         for (int k = 0; k < 16; ++k) {
;           const f2_t a2 = {aa[k], aa[k]};
; #pragma unroll
;           for (int d = 0; d < 4; ++d) { const unsigned ww = rows[k][d]; o[2 * d] += a2 * cvt8lo(ww); o[2 * d + 1] += a2 * cvt8hi(ww); }
;         }
;       }
;       float ov[16];
; #pragma unroll
;       for (int d = 0; d < 4; ++d) { ov[4 * d] = o[2 * d].x; ov[4 * d + 1] = o[2 * d].y; ov[4 * d + 2] = o[2 * d + 1].x; ov[4 * d + 3] = o[2 * d + 1].y; }
;       float q8[8], q4[4];
; #pragma unroll
;       for (int k = 0; k < 8; ++k) q8[k] = (b5 ? ov[8 + k] : ov[k]) + __shfl_xor(b5 ? ov[k] : ov[8 + k], 32);
; #pragma unroll
;       for (int k = 0; k < 4; ++k) q4[k] = (b4 ? q8[4 + k] : q8[k]) + __shfl_xor(b4 ? q8[k] : q8[4 + k], 16);
;       *(uint2*)(OUTP + (size_t)tok * D_ + s * 256 + l15 * 16 + 8 * b5 + 4 * b4) = make_uint2(pk2(q4[0], q4[1]), pk2(q4[2], q4[3]));
	v_cvt_pk_f32_fp8_e32 v[232:233], v202
	v_cvt_pk_f32_fp8_sdwa v[234:235], v202 src0_sel:WORD_1
	v_pk_fma_f32 v[216:217], v[80:81], v[232:233], v[216:217] op_sel:[1,0,0]
	v_pk_fma_f32 v[218:219], v[80:81], v[234:235], v[218:219] op_sel:[1,0,0]
	v_cvt_pk_f32_fp8_e32 v[236:237], v203
	v_cvt_pk_f32_fp8_sdwa v[238:239], v203 src0_sel:WORD_1
	v_pk_fma_f32 v[220:221], v[80:81], v[236:237], v[220:221] op_sel:[1,0,0]
	v_pk_fma_f32 v[222:223], v[80:81], v[238:239], v[222:223] op_sel:[1,0,0]
	v_cvt_pk_f32_fp8_e32 v[232:233], v204
	v_cvt_pk_f32_fp8_sdwa v[234:235], v204 src0_sel:WORD_1
	v_pk_fma_f32 v[224:225], v[80:81], v[232:233], v[224:225] op_sel:[1,0,0]
	v_pk_fma_f32 v[226:227], v[80:81], v[234:235], v[226:227] op_sel:[1,0,0]
	v_cvt_pk_f32_fp8_e32 v[236:237], v205
	v_cvt_pk_f32_fp8_sdwa v[238:239], v205 src0_sel:WORD_1
	v_pk_fma_f32 v[228:229], v[80:81], v[236:237], v[228:229] op_sel:[1,0,0]
	v_pk_fma_f32 v[230:231], v[80:81], v[238:239], v[230:231] op_sel:[1,0,0]
	s_waitcnt vmcnt(1)
	v_cvt_pk_f32_fp8_e32 v[232:233], v206
	v_cvt_pk_f32_fp8_sdwa v[234:235], v206 src0_sel:WORD_1
	v_pk_fma_f32 v[216:217], v[82:83], v[232:233], v[216:217] op_sel_hi:[0,1,1]
	v_pk_fma_f32 v[218:219], v[82:83], v[234:235], v[218:219] op_sel_hi:[0,1,1]
	v_cvt_pk_f32_fp8_e32 v[236:237], v207
	v_cvt_pk_f32_fp8_sdwa v[238:239], v207 src0_sel:WORD_1
	v_pk_fma_f32 v[220:221], v[82:83], v[236:237], v[220:221] op_sel_hi:[0,1,1]
	v_pk_fma_f32 v[222:223], v[82:83], v[238:239], v[222:223] op_sel_hi:[0,1,1]
	v_cvt_pk_f32_fp8_e32 v[232:233], v208
	v_cvt_pk_f32_fp8_sdwa v[234:235], v208 src0_sel:WORD_1
	v_pk_fma_f32 v[224:225], v[82:83], v[232:233], v[224:225] op_sel_hi:[0,1,1]
	v_pk_fma_f32 v[226:227], v[82:83], v[234:235], v[226:227] op_sel_hi:[0,1,1]
	v_cvt_pk_f32_fp8_e32 v[236:237], v209
	v_cvt_pk_f32_fp8_sdwa v[238:239], v209 src0_sel:WORD_1
	v_pk_fma_f32 v[228:229], v[82:83], v[236:237], v[228:229] op_sel_hi:[0,1,1]
	v_pk_fma_f32 v[230:231], v[82:83], v[238:239], v[230:231] op_sel_hi:[0,1,1]
	s_waitcnt vmcnt(0)
	v_cvt_pk_f32_fp8_e32 v[232:233], v210
	v_cvt_pk_f32_fp8_sdwa v[234:235], v210 src0_sel:WORD_1
	v_pk_fma_f32 v[216:217], v[82:83], v[232:233], v[216:217] op_sel:[1,0,0]
	v_pk_fma_f32 v[218:219], v[82:83], v[234:235], v[218:219] op_sel:[1,0,0]
	v_cvt_pk_f32_fp8_e32 v[236:237], v211
	v_cvt_pk_f32_fp8_sdwa v[238:239], v211 src0_sel:WORD_1
	v_pk_fma_f32 v[220:221], v[82:83], v[236:237], v[220:221] op_sel:[1,0,0]
	v_pk_fma_f32 v[222:223], v[82:83], v[238:239], v[222:223] op_sel:[1,0,0]
	v_cvt_pk_f32_fp8_e32 v[232:233], v212
	v_cvt_pk_f32_fp8_sdwa v[234:235], v212 src0_sel:WORD_1
	v_pk_fma_f32 v[224:225], v[82:83], v[232:233], v[224:225] op_sel:[1,0,0]
	v_pk_fma_f32 v[226:227], v[82:83], v[234:235], v[226:227] op_sel:[1,0,0]
	v_cvt_pk_f32_fp8_e32 v[236:237], v213
	v_cvt_pk_f32_fp8_sdwa v[238:239], v213 src0_sel:WORD_1
	v_pk_fma_f32 v[228:229], v[82:83], v[236:237], v[228:229] op_sel:[1,0,0]
	v_pk_fma_f32 v[230:231], v[82:83], v[238:239], v[230:231] op_sel:[1,0,0]
	ds_read_b128 v[52:55], v6 offset:528
	ds_read_b128 v[56:59], v6 offset:544
	ds_read_b128 v[60:63], v6 offset:560
	ds_read_b128 v[64:67], v6 offset:576
	ds_read_b128 v[68:71], v6 offset:592
	ds_read_b128 v[72:75], v6 offset:608
	ds_read_b128 v[76:79], v6 offset:624
	ds_read_b128 v[80:83], v6 offset:640
	v_add_u32_e32 v214, s46, v4
	s_nop 0
	v_permlane32_swap_b32_e32 v216, v224
	v_permlane32_swap_b32_e32 v217, v225
	v_permlane32_swap_b32_e32 v218, v226
	v_permlane32_swap_b32_e32 v219, v227
	v_permlane32_swap_b32_e32 v220, v228
	v_permlane32_swap_b32_e32 v221, v229
	v_permlane32_swap_b32_e32 v222, v230
	v_permlane32_swap_b32_e32 v223, v231
	v_add_f32_e32 v216, v216, v224
	v_add_f32_e32 v217, v217, v225
	v_add_f32_e32 v218, v218, v226
	v_add_f32_e32 v219, v219, v227
	v_add_f32_e32 v220, v220, v228
	v_add_f32_e32 v221, v221, v229
	v_add_f32_e32 v222, v222, v230
	v_add_f32_e32 v223, v223, v231
	s_nop 1
	v_permlane16_swap_b32_e32 v216, v220
	v_permlane16_swap_b32_e32 v217, v221
	v_permlane16_swap_b32_e32 v218, v222
	v_permlane16_swap_b32_e32 v219, v223
	v_add_f32_e32 v216, v216, v220
	v_add_f32_e32 v217, v217, v221
	v_add_f32_e32 v218, v218, v222
	v_add_f32_e32 v219, v219, v223
	v_cvt_pk_bf16_f32 v232, v216, v217
	v_cvt_pk_bf16_f32 v233, v218, v219
	global_store_dwordx2 v214, v[232:233], s[14:15]
	s_add_i32 s36, s34, 2
	s_lshl_b32 s46, s36, 12
	s_add_i32 s46, s46, s24
	s_add_i32 s37, s34, 3
	s_lshl_b32 s47, s37, 9
	s_add_u32 s42, s6, s47
	s_addc_u32 s43, s7, 0
	s_add_u32 s44, s8, s47
	s_addc_u32 s45, s9, 0
	global_load_dword v10, v3, s[42:43]
	global_load_dword v11, v3, s[42:43] offset:256
	global_load_dword v12, v3, s[44:45]
	global_load_dword v13, v3, s[44:45] offset:256
	s_waitcnt lgkmcnt(0)
; DI f2_t cvt8lo(unsigned w) { return __builtin_amdgcn_cvt_pk_f32_fp8(w, false); }
; DI f2_t cvt8hi(unsigned w) { return __builtin_amdgcn_cvt_pk_f32_fp8(w, true); }
; DI void phase11(const Params& p, char* smem, int rep) {
;     ...
;         u32x4 rows[16];
; #pragma unroll
;         for (int k = 0; k < 16; ++k) rows[k] = *(const u32x4*)(vb + (size_t)ida[k] * 2048);
; #pragma unroll
;         for (int k = 0; k < 16; ++k) {
;           const f2_t a2 = {aa[k], aa[k]};
; #pragma unroll
;           for (int d = 0; d < 4; ++d) { const unsigned ww = rows[k][d]; o[2 * d] += a2 * cvt8lo(ww); o[2 * d + 1] += a2 * cvt8hi(ww); }
	v_lshl_add_u32 v20, v20, 11, v2
	v_lshl_add_u32 v21, v21, 11, v2
	v_lshl_add_u32 v22, v22, 11, v2
	v_lshl_add_u32 v23, v23, 11, v2
	v_lshl_add_u32 v24, v24, 11, v2
	v_lshl_add_u32 v25, v25, 11, v2
	v_lshl_add_u32 v26, v26, 11, v2
	v_lshl_add_u32 v27, v27, 11, v2
	v_lshl_add_u32 v28, v28, 11, v2
	v_lshl_add_u32 v29, v29, 11, v2
	v_lshl_add_u32 v30, v30, 11, v2
	v_lshl_add_u32 v31, v31, 11, v2
	v_lshl_add_u32 v32, v32, 11, v2
	v_lshl_add_u32 v33, v33, 11, v2
	v_lshl_add_u32 v34, v34, 11, v2
	v_lshl_add_u32 v35, v35, 11, v2
	v_lshl_add_u32 v36, v36, 11, v2
	v_lshl_add_u32 v37, v37, 11, v2
	v_lshl_add_u32 v38, v38, 11, v2
	v_lshl_add_u32 v39, v39, 11, v2
	v_lshl_add_u32 v40, v40, 11, v2
	v_lshl_add_u32 v41, v41, 11, v2
	v_lshl_add_u32 v42, v42, 11, v2
	v_lshl_add_u32 v43, v43, 11, v2
	v_lshl_add_u32 v44, v44, 11, v2
	v_lshl_add_u32 v45, v45, 11, v2
	v_lshl_add_u32 v46, v46, 11, v2
	v_lshl_add_u32 v47, v47, 11, v2
	v_lshl_add_u32 v48, v48, 11, v2
	v_lshl_add_u32 v49, v49, 11, v2
	v_lshl_add_u32 v50, v50, 11, v2
	v_lshl_add_u32 v51, v51, 11, v2
	global_load_dwordx4 v[84:87], v20, s[20:21]
	global_load_dwordx4 v[88:91], v21, s[20:21]
	global_load_dwordx4 v[92:95], v22, s[20:21]
	global_load_dwordx4 v[96:99], v23, s[20:21]
	global_load_dwordx4 v[100:103], v24, s[20:21]
	global_load_dwordx4 v[104:107], v25, s[20:21]
	global_load_dwordx4 v[108:111], v26, s[20:21]
	global_load_dwordx4 v[112:115], v27, s[20:21]
	global_load_dwordx4 v[116:119], v28, s[20:21]
	global_load_dwordx4 v[120:123], v29, s[20:21]
	global_load_dwordx4 v[124:127], v30, s[20:21]
	global_load_dwordx4 v[128:131], v31, s[20:21]
	global_load_dwordx4 v[132:135], v32, s[20:21]
	global_load_dwordx4 v[136:139], v33, s[20:21]
	global_load_dwordx4 v[140:143], v34, s[20:21]
	global_load_dwordx4 v[144:147], v35, s[20:21]
	global_load_dwordx4 v[148:151], v36, s[20:21]
	global_load_dwordx4 v[152:155], v37, s[20:21]
	global_load_dwordx4 v[156:159], v38, s[20:21]
	global_load_dwordx4 v[160:163], v39, s[20:21]
	global_load_dwordx4 v[164:167], v40, s[20:21]
	global_load_dwordx4 v[168:171], v41, s[20:21]
	global_load_dwordx4 v[172:175], v42, s[20:21]
	global_load_dwordx4 v[176:179], v43, s[20:21]
	global_load_dwordx4 v[180:183], v44, s[20:21]
	global_load_dwordx4 v[184:187], v45, s[20:21]
	global_load_dwordx4 v[190:193], v46, s[20:21]
	global_load_dwordx4 v[194:197], v47, s[20:21]
	global_load_dwordx4 v[198:201], v48, s[20:21]
	global_load_dwordx4 v[202:205], v49, s[20:21]
	global_load_dwordx4 v[206:209], v50, s[20:21]
	global_load_dwordx4 v[210:213], v51, s[20:21]
	s_waitcnt vmcnt(31)
	v_cvt_pk_f32_fp8_e32 v[232:233], v84
	v_cvt_pk_f32_fp8_sdwa v[234:235], v84 src0_sel:WORD_1
	v_pk_fma_f32 v[216:217], v[52:53], v[232:233], 0 op_sel_hi:[0,1,0]
	v_pk_fma_f32 v[218:219], v[52:53], v[234:235], 0 op_sel_hi:[0,1,0]
	v_cvt_pk_f32_fp8_e32 v[236:237], v85
	v_cvt_pk_f32_fp8_sdwa v[238:239], v85 src0_sel:WORD_1
	v_pk_fma_f32 v[220:221], v[52:53], v[236:237], 0 op_sel_hi:[0,1,0]
	v_pk_fma_f32 v[222:223], v[52:53], v[238:239], 0 op_sel_hi:[0,1,0]
	v_cvt_pk_f32_fp8_e32 v[232:233], v86
	v_cvt_pk_f32_fp8_sdwa v[234:235], v86 src0_sel:WORD_1
	v_pk_fma_f32 v[224:225], v[52:53], v[232:233], 0 op_sel_hi:[0,1,0]
	v_pk_fma_f32 v[226:227], v[52:53], v[234:235], 0 op_sel_hi:[0,1,0]
	v_cvt_pk_f32_fp8_e32 v[236:237], v87
	v_cvt_pk_f32_fp8_sdwa v[238:239], v87 src0_sel:WORD_1
	v_pk_fma_f32 v[228:229], v[52:53], v[236:237], 0 op_sel_hi:[0,1,0]
	v_pk_fma_f32 v[230:231], v[52:53], v[238:239], 0 op_sel_hi:[0,1,0]
	s_waitcnt vmcnt(30)
	v_cvt_pk_f32_fp8_e32 v[232:233], v88
	v_cvt_pk_f32_fp8_sdwa v[234:235], v88 src0_sel:WORD_1
	v_pk_fma_f32 v[216:217], v[52:53], v[232:233], v[216:217] op_sel:[1,0,0]
	v_pk_fma_f32 v[218:219], v[52:53], v[234:235], v[218:219] op_sel:[1,0,0]
	v_cvt_pk_f32_fp8_e32 v[236:237], v89
	v_cvt_pk_f32_fp8_sdwa v[238:239], v89 src0_sel:WORD_1
	v_pk_fma_f32 v[220:221], v[52:53], v[236:237], v[220:221] op_sel:[1,0,0]
	v_pk_fma_f32 v[222:223], v[52:53], v[238:239], v[222:223] op_sel:[1,0,0]
	v_cvt_pk_f32_fp8_e32 v[232:233], v90
	v_cvt_pk_f32_fp8_sdwa v[234:235], v90 src0_sel:WORD_1
	v_pk_fma_f32 v[224:225], v[52:53], v[232:233], v[224:225] op_sel:[1,0,0]
	v_pk_fma_f32 v[226:227], v[52:53], v[234:235], v[226:227] op_sel:[1,0,0]
	v_cvt_pk_f32_fp8_e32 v[236:237], v91
	v_cvt_pk_f32_fp8_sdwa v[238:239], v91 src0_sel:WORD_1
	v_pk_fma_f32 v[228:229], v[52:53], v[236:237], v[228:229] op_sel:[1,0,0]
	v_pk_fma_f32 v[230:231], v[52:53], v[238:239], v[230:231] op_sel:[1,0,0]
	s_waitcnt vmcnt(29)
	v_cvt_pk_f32_fp8_e32 v[232:233], v92
	v_cvt_pk_f32_fp8_sdwa v[234:235], v92 src0_sel:WORD_1
	v_pk_fma_f32 v[216:217], v[54:55], v[232:233], v[216:217] op_sel_hi:[0,1,1]
	v_pk_fma_f32 v[218:219], v[54:55], v[234:235], v[218:219] op_sel_hi:[0,1,1]
	v_cvt_pk_f32_fp8_e32 v[236:237], v93
	v_cvt_pk_f32_fp8_sdwa v[238:239], v93 src0_sel:WORD_1
	v_pk_fma_f32 v[220:221], v[54:55], v[236:237], v[220:221] op_sel_hi:[0,1,1]
	v_pk_fma_f32 v[222:223], v[54:55], v[238:239], v[222:223] op_sel_hi:[0,1,1]
	v_cvt_pk_f32_fp8_e32 v[232:233], v94
	v_cvt_pk_f32_fp8_sdwa v[234:235], v94 src0_sel:WORD_1
	v_pk_fma_f32 v[224:225], v[54:55], v[232:233], v[224:225] op_sel_hi:[0,1,1]
	v_pk_fma_f32 v[226:227], v[54:55], v[234:235], v[226:227] op_sel_hi:[0,1,1]
	v_cvt_pk_f32_fp8_e32 v[236:237], v95
	v_cvt_pk_f32_fp8_sdwa v[238:239], v95 src0_sel:WORD_1
	v_pk_fma_f32 v[228:229], v[54:55], v[236:237], v[228:229] op_sel_hi:[0,1,1]
	v_pk_fma_f32 v[230:231], v[54:55], v[238:239], v[230:231] op_sel_hi:[0,1,1]
	s_waitcnt vmcnt(28)
; DI f2_t cvt8lo(unsigned w) { return __builtin_amdgcn_cvt_pk_f32_fp8(w, false); }
; DI f2_t cvt8hi(unsigned w) { return __builtin_amdgcn_cvt_pk_f32_fp8(w, true); }
; DI void phase11(const Params& p, char* smem, int rep) {
;     ...
;         for (int k = 0; k < 16; ++k) rows[k] = *(const u32x4*)(vb + (size_t)ida[k] * 2048);
; #pragma unroll
;         for (int k = 0; k < 16; ++k) {
;           const f2_t a2 = {aa[k], aa[k]};
; #pragma unroll
;           for (int d = 0; d < 4; ++d) { const unsigned ww = rows[k][d]; o[2 * d] += a2 * cvt8lo(ww); o[2 * d + 1] += a2 * cvt8hi(ww); }
	v_cvt_pk_f32_fp8_e32 v[232:233], v96
	v_cvt_pk_f32_fp8_sdwa v[234:235], v96 src0_sel:WORD_1
	v_pk_fma_f32 v[216:217], v[54:55], v[232:233], v[216:217] op_sel:[1,0,0]
	v_pk_fma_f32 v[218:219], v[54:55], v[234:235], v[218:219] op_sel:[1,0,0]
	v_cvt_pk_f32_fp8_e32 v[236:237], v97
	v_cvt_pk_f32_fp8_sdwa v[238:239], v97 src0_sel:WORD_1
	v_pk_fma_f32 v[220:221], v[54:55], v[236:237], v[220:221] op_sel:[1,0,0]
	v_pk_fma_f32 v[222:223], v[54:55], v[238:239], v[222:223] op_sel:[1,0,0]
	v_cvt_pk_f32_fp8_e32 v[232:233], v98
	v_cvt_pk_f32_fp8_sdwa v[234:235], v98 src0_sel:WORD_1
	v_pk_fma_f32 v[224:225], v[54:55], v[232:233], v[224:225] op_sel:[1,0,0]
	v_pk_fma_f32 v[226:227], v[54:55], v[234:235], v[226:227] op_sel:[1,0,0]
	v_cvt_pk_f32_fp8_e32 v[236:237], v99
	v_cvt_pk_f32_fp8_sdwa v[238:239], v99 src0_sel:WORD_1
	v_pk_fma_f32 v[228:229], v[54:55], v[236:237], v[228:229] op_sel:[1,0,0]
	v_pk_fma_f32 v[230:231], v[54:55], v[238:239], v[230:231] op_sel:[1,0,0]
	s_waitcnt vmcnt(27)
	v_cvt_pk_f32_fp8_e32 v[232:233], v100
	v_cvt_pk_f32_fp8_sdwa v[234:235], v100 src0_sel:WORD_1
	v_pk_fma_f32 v[216:217], v[56:57], v[232:233], v[216:217] op_sel_hi:[0,1,1]
	v_pk_fma_f32 v[218:219], v[56:57], v[234:235], v[218:219] op_sel_hi:[0,1,1]
	v_cvt_pk_f32_fp8_e32 v[236:237], v101
	v_cvt_pk_f32_fp8_sdwa v[238:239], v101 src0_sel:WORD_1
	v_pk_fma_f32 v[220:221], v[56:57], v[236:237], v[220:221] op_sel_hi:[0,1,1]
	v_pk_fma_f32 v[222:223], v[56:57], v[238:239], v[222:223] op_sel_hi:[0,1,1]
	v_cvt_pk_f32_fp8_e32 v[232:233], v102
	v_cvt_pk_f32_fp8_sdwa v[234:235], v102 src0_sel:WORD_1
	v_pk_fma_f32 v[224:225], v[56:57], v[232:233], v[224:225] op_sel_hi:[0,1,1]
	v_pk_fma_f32 v[226:227], v[56:57], v[234:235], v[226:227] op_sel_hi:[0,1,1]
	v_cvt_pk_f32_fp8_e32 v[236:237], v103
	v_cvt_pk_f32_fp8_sdwa v[238:239], v103 src0_sel:WORD_1
	v_pk_fma_f32 v[228:229], v[56:57], v[236:237], v[228:229] op_sel_hi:[0,1,1]
	v_pk_fma_f32 v[230:231], v[56:57], v[238:239], v[230:231] op_sel_hi:[0,1,1]
	s_waitcnt vmcnt(26)
	v_cvt_pk_f32_fp8_e32 v[232:233], v104
	v_cvt_pk_f32_fp8_sdwa v[234:235], v104 src0_sel:WORD_1
	v_pk_fma_f32 v[216:217], v[56:57], v[232:233], v[216:217] op_sel:[1,0,0]
	v_pk_fma_f32 v[218:219], v[56:57], v[234:235], v[218:219] op_sel:[1,0,0]
	v_cvt_pk_f32_fp8_e32 v[236:237], v105
	v_cvt_pk_f32_fp8_sdwa v[238:239], v105 src0_sel:WORD_1
	v_pk_fma_f32 v[220:221], v[56:57], v[236:237], v[220:221] op_sel:[1,0,0]
	v_pk_fma_f32 v[222:223], v[56:57], v[238:239], v[222:223] op_sel:[1,0,0]
	v_cvt_pk_f32_fp8_e32 v[232:233], v106
	v_cvt_pk_f32_fp8_sdwa v[234:235], v106 src0_sel:WORD_1
	v_pk_fma_f32 v[224:225], v[56:57], v[232:233], v[224:225] op_sel:[1,0,0]
	v_pk_fma_f32 v[226:227], v[56:57], v[234:235], v[226:227] op_sel:[1,0,0]
	v_cvt_pk_f32_fp8_e32 v[236:237], v107
	v_cvt_pk_f32_fp8_sdwa v[238:239], v107 src0_sel:WORD_1
	v_pk_fma_f32 v[228:229], v[56:57], v[236:237], v[228:229] op_sel:[1,0,0]
	v_pk_fma_f32 v[230:231], v[56:57], v[238:239], v[230:231] op_sel:[1,0,0]
	s_waitcnt vmcnt(25)
	v_cvt_pk_f32_fp8_e32 v[232:233], v108
	v_cvt_pk_f32_fp8_sdwa v[234:235], v108 src0_sel:WORD_1
	v_pk_fma_f32 v[216:217], v[58:59], v[232:233], v[216:217] op_sel_hi:[0,1,1]
	v_pk_fma_f32 v[218:219], v[58:59], v[234:235], v[218:219] op_sel_hi:[0,1,1]
	v_cvt_pk_f32_fp8_e32 v[236:237], v109
	v_cvt_pk_f32_fp8_sdwa v[238:239], v109 src0_sel:WORD_1
	v_pk_fma_f32 v[220:221], v[58:59], v[236:237], v[220:221] op_sel_hi:[0,1,1]
	v_pk_fma_f32 v[222:223], v[58:59], v[238:239], v[222:223] op_sel_hi:[0,1,1]
	v_cvt_pk_f32_fp8_e32 v[232:233], v110
	v_cvt_pk_f32_fp8_sdwa v[234:235], v110 src0_sel:WORD_1
	v_pk_fma_f32 v[224:225], v[58:59], v[232:233], v[224:225] op_sel_hi:[0,1,1]
	v_pk_fma_f32 v[226:227], v[58:59], v[234:235], v[226:227] op_sel_hi:[0,1,1]
	v_cvt_pk_f32_fp8_e32 v[236:237], v111
	v_cvt_pk_f32_fp8_sdwa v[238:239], v111 src0_sel:WORD_1
	v_pk_fma_f32 v[228:229], v[58:59], v[236:237], v[228:229] op_sel_hi:[0,1,1]
	v_pk_fma_f32 v[230:231], v[58:59], v[238:239], v[230:231] op_sel_hi:[0,1,1]
	s_waitcnt vmcnt(24)
	v_cvt_pk_f32_fp8_e32 v[232:233], v112
	v_cvt_pk_f32_fp8_sdwa v[234:235], v112 src0_sel:WORD_1
	v_pk_fma_f32 v[216:217], v[58:59], v[232:233], v[216:217] op_sel:[1,0,0]
	v_pk_fma_f32 v[218:219], v[58:59], v[234:235], v[218:219] op_sel:[1,0,0]
	v_cvt_pk_f32_fp8_e32 v[236:237], v113
	v_cvt_pk_f32_fp8_sdwa v[238:239], v113 src0_sel:WORD_1
	v_pk_fma_f32 v[220:221], v[58:59], v[236:237], v[220:221] op_sel:[1,0,0]
	v_pk_fma_f32 v[222:223], v[58:59], v[238:239], v[222:223] op_sel:[1,0,0]
	v_cvt_pk_f32_fp8_e32 v[232:233], v114
	v_cvt_pk_f32_fp8_sdwa v[234:235], v114 src0_sel:WORD_1
	v_pk_fma_f32 v[224:225], v[58:59], v[232:233], v[224:225] op_sel:[1,0,0]
	v_pk_fma_f32 v[226:227], v[58:59], v[234:235], v[226:227] op_sel:[1,0,0]
	v_cvt_pk_f32_fp8_e32 v[236:237], v115
	v_cvt_pk_f32_fp8_sdwa v[238:239], v115 src0_sel:WORD_1
	v_pk_fma_f32 v[228:229], v[58:59], v[236:237], v[228:229] op_sel:[1,0,0]
	v_pk_fma_f32 v[230:231], v[58:59], v[238:239], v[230:231] op_sel:[1,0,0]
	s_waitcnt vmcnt(23)
	v_cvt_pk_f32_fp8_e32 v[232:233], v116
	v_cvt_pk_f32_fp8_sdwa v[234:235], v116 src0_sel:WORD_1
	v_pk_fma_f32 v[216:217], v[60:61], v[232:233], v[216:217] op_sel_hi:[0,1,1]
	v_pk_fma_f32 v[218:219], v[60:61], v[234:235], v[218:219] op_sel_hi:[0,1,1]
	v_cvt_pk_f32_fp8_e32 v[236:237], v117
	v_cvt_pk_f32_fp8_sdwa v[238:239], v117 src0_sel:WORD_1
	v_pk_fma_f32 v[220:221], v[60:61], v[236:237], v[220:221] op_sel_hi:[0,1,1]
	v_pk_fma_f32 v[222:223], v[60:61], v[238:239], v[222:223] op_sel_hi:[0,1,1]
	v_cvt_pk_f32_fp8_e32 v[232:233], v118
	v_cvt_pk_f32_fp8_sdwa v[234:235], v118 src0_sel:WORD_1
	v_pk_fma_f32 v[224:225], v[60:61], v[232:233], v[224:225] op_sel_hi:[0,1,1]
	v_pk_fma_f32 v[226:227], v[60:61], v[234:235], v[226:227] op_sel_hi:[0,1,1]
	v_cvt_pk_f32_fp8_e32 v[236:237], v119
	v_cvt_pk_f32_fp8_sdwa v[238:239], v119 src0_sel:WORD_1
	v_pk_fma_f32 v[228:229], v[60:61], v[236:237], v[228:229] op_sel_hi:[0,1,1]
	v_pk_fma_f32 v[230:231], v[60:61], v[238:239], v[230:231] op_sel_hi:[0,1,1]
	s_waitcnt vmcnt(22)
; DI f2_t cvt8lo(unsigned w) { return __builtin_amdgcn_cvt_pk_f32_fp8(w, false); }
; DI f2_t cvt8hi(unsigned w) { return __builtin_amdgcn_cvt_pk_f32_fp8(w, true); }
; DI void phase11(const Params& p, char* smem, int rep) {
;     ...
;         for (int k = 0; k < 16; ++k) rows[k] = *(const u32x4*)(vb + (size_t)ida[k] * 2048);
; #pragma unroll
;         for (int k = 0; k < 16; ++k) {
;           const f2_t a2 = {aa[k], aa[k]};
; #pragma unroll
;           for (int d = 0; d < 4; ++d) { const unsigned ww = rows[k][d]; o[2 * d] += a2 * cvt8lo(ww); o[2 * d + 1] += a2 * cvt8hi(ww); }
	v_cvt_pk_f32_fp8_e32 v[232:233], v120
	v_cvt_pk_f32_fp8_sdwa v[234:235], v120 src0_sel:WORD_1
	v_pk_fma_f32 v[216:217], v[60:61], v[232:233], v[216:217] op_sel:[1,0,0]
	v_pk_fma_f32 v[218:219], v[60:61], v[234:235], v[218:219] op_sel:[1,0,0]
	v_cvt_pk_f32_fp8_e32 v[236:237], v121
	v_cvt_pk_f32_fp8_sdwa v[238:239], v121 src0_sel:WORD_1
	v_pk_fma_f32 v[220:221], v[60:61], v[236:237], v[220:221] op_sel:[1,0,0]
	v_pk_fma_f32 v[222:223], v[60:61], v[238:239], v[222:223] op_sel:[1,0,0]
	v_cvt_pk_f32_fp8_e32 v[232:233], v122
	v_cvt_pk_f32_fp8_sdwa v[234:235], v122 src0_sel:WORD_1
	v_pk_fma_f32 v[224:225], v[60:61], v[232:233], v[224:225] op_sel:[1,0,0]
	v_pk_fma_f32 v[226:227], v[60:61], v[234:235], v[226:227] op_sel:[1,0,0]
	v_cvt_pk_f32_fp8_e32 v[236:237], v123
	v_cvt_pk_f32_fp8_sdwa v[238:239], v123 src0_sel:WORD_1
	v_pk_fma_f32 v[228:229], v[60:61], v[236:237], v[228:229] op_sel:[1,0,0]
	v_pk_fma_f32 v[230:231], v[60:61], v[238:239], v[230:231] op_sel:[1,0,0]
	s_waitcnt vmcnt(21)
	v_cvt_pk_f32_fp8_e32 v[232:233], v124
	v_cvt_pk_f32_fp8_sdwa v[234:235], v124 src0_sel:WORD_1
	v_pk_fma_f32 v[216:217], v[62:63], v[232:233], v[216:217] op_sel_hi:[0,1,1]
	v_pk_fma_f32 v[218:219], v[62:63], v[234:235], v[218:219] op_sel_hi:[0,1,1]
	v_cvt_pk_f32_fp8_e32 v[236:237], v125
	v_cvt_pk_f32_fp8_sdwa v[238:239], v125 src0_sel:WORD_1
	v_pk_fma_f32 v[220:221], v[62:63], v[236:237], v[220:221] op_sel_hi:[0,1,1]
	v_pk_fma_f32 v[222:223], v[62:63], v[238:239], v[222:223] op_sel_hi:[0,1,1]
	v_cvt_pk_f32_fp8_e32 v[232:233], v126
	v_cvt_pk_f32_fp8_sdwa v[234:235], v126 src0_sel:WORD_1
	v_pk_fma_f32 v[224:225], v[62:63], v[232:233], v[224:225] op_sel_hi:[0,1,1]
	v_pk_fma_f32 v[226:227], v[62:63], v[234:235], v[226:227] op_sel_hi:[0,1,1]
	v_cvt_pk_f32_fp8_e32 v[236:237], v127
	v_cvt_pk_f32_fp8_sdwa v[238:239], v127 src0_sel:WORD_1
	v_pk_fma_f32 v[228:229], v[62:63], v[236:237], v[228:229] op_sel_hi:[0,1,1]
	v_pk_fma_f32 v[230:231], v[62:63], v[238:239], v[230:231] op_sel_hi:[0,1,1]
	s_waitcnt vmcnt(20)
	v_cvt_pk_f32_fp8_e32 v[232:233], v128
	v_cvt_pk_f32_fp8_sdwa v[234:235], v128 src0_sel:WORD_1
	v_pk_fma_f32 v[216:217], v[62:63], v[232:233], v[216:217] op_sel:[1,0,0]
	v_pk_fma_f32 v[218:219], v[62:63], v[234:235], v[218:219] op_sel:[1,0,0]
	v_cvt_pk_f32_fp8_e32 v[236:237], v129
	v_cvt_pk_f32_fp8_sdwa v[238:239], v129 src0_sel:WORD_1
	v_pk_fma_f32 v[220:221], v[62:63], v[236:237], v[220:221] op_sel:[1,0,0]
	v_pk_fma_f32 v[222:223], v[62:63], v[238:239], v[222:223] op_sel:[1,0,0]
	v_cvt_pk_f32_fp8_e32 v[232:233], v130
	v_cvt_pk_f32_fp8_sdwa v[234:235], v130 src0_sel:WORD_1
	v_pk_fma_f32 v[224:225], v[62:63], v[232:233], v[224:225] op_sel:[1,0,0]
	v_pk_fma_f32 v[226:227], v[62:63], v[234:235], v[226:227] op_sel:[1,0,0]
	v_cvt_pk_f32_fp8_e32 v[236:237], v131
	v_cvt_pk_f32_fp8_sdwa v[238:239], v131 src0_sel:WORD_1
	v_pk_fma_f32 v[228:229], v[62:63], v[236:237], v[228:229] op_sel:[1,0,0]
	v_pk_fma_f32 v[230:231], v[62:63], v[238:239], v[230:231] op_sel:[1,0,0]
	s_waitcnt vmcnt(19)
	v_cvt_pk_f32_fp8_e32 v[232:233], v132
	v_cvt_pk_f32_fp8_sdwa v[234:235], v132 src0_sel:WORD_1
	v_pk_fma_f32 v[216:217], v[64:65], v[232:233], v[216:217] op_sel_hi:[0,1,1]
	v_pk_fma_f32 v[218:219], v[64:65], v[234:235], v[218:219] op_sel_hi:[0,1,1]
	v_cvt_pk_f32_fp8_e32 v[236:237], v133
	v_cvt_pk_f32_fp8_sdwa v[238:239], v133 src0_sel:WORD_1
	v_pk_fma_f32 v[220:221], v[64:65], v[236:237], v[220:221] op_sel_hi:[0,1,1]
	v_pk_fma_f32 v[222:223], v[64:65], v[238:239], v[222:223] op_sel_hi:[0,1,1]
	v_cvt_pk_f32_fp8_e32 v[232:233], v134
	v_cvt_pk_f32_fp8_sdwa v[234:235], v134 src0_sel:WORD_1
	v_pk_fma_f32 v[224:225], v[64:65], v[232:233], v[224:225] op_sel_hi:[0,1,1]
	v_pk_fma_f32 v[226:227], v[64:65], v[234:235], v[226:227] op_sel_hi:[0,1,1]
	v_cvt_pk_f32_fp8_e32 v[236:237], v135
	v_cvt_pk_f32_fp8_sdwa v[238:239], v135 src0_sel:WORD_1
	v_pk_fma_f32 v[228:229], v[64:65], v[236:237], v[228:229] op_sel_hi:[0,1,1]
	v_pk_fma_f32 v[230:231], v[64:65], v[238:239], v[230:231] op_sel_hi:[0,1,1]
	s_waitcnt vmcnt(18)
	v_cvt_pk_f32_fp8_e32 v[232:233], v136
	v_cvt_pk_f32_fp8_sdwa v[234:235], v136 src0_sel:WORD_1
	v_pk_fma_f32 v[216:217], v[64:65], v[232:233], v[216:217] op_sel:[1,0,0]
	v_pk_fma_f32 v[218:219], v[64:65], v[234:235], v[218:219] op_sel:[1,0,0]
	v_cvt_pk_f32_fp8_e32 v[236:237], v137
	v_cvt_pk_f32_fp8_sdwa v[238:239], v137 src0_sel:WORD_1
	v_pk_fma_f32 v[220:221], v[64:65], v[236:237], v[220:221] op_sel:[1,0,0]
	v_pk_fma_f32 v[222:223], v[64:65], v[238:239], v[222:223] op_sel:[1,0,0]
	v_cvt_pk_f32_fp8_e32 v[232:233], v138
	v_cvt_pk_f32_fp8_sdwa v[234:235], v138 src0_sel:WORD_1
	v_pk_fma_f32 v[224:225], v[64:65], v[232:233], v[224:225] op_sel:[1,0,0]
	v_pk_fma_f32 v[226:227], v[64:65], v[234:235], v[226:227] op_sel:[1,0,0]
	v_cvt_pk_f32_fp8_e32 v[236:237], v139
	v_cvt_pk_f32_fp8_sdwa v[238:239], v139 src0_sel:WORD_1
	v_pk_fma_f32 v[228:229], v[64:65], v[236:237], v[228:229] op_sel:[1,0,0]
	v_pk_fma_f32 v[230:231], v[64:65], v[238:239], v[230:231] op_sel:[1,0,0]
	s_waitcnt vmcnt(17)
	v_cvt_pk_f32_fp8_e32 v[232:233], v140
	v_cvt_pk_f32_fp8_sdwa v[234:235], v140 src0_sel:WORD_1
	v_pk_fma_f32 v[216:217], v[66:67], v[232:233], v[216:217] op_sel_hi:[0,1,1]
	v_pk_fma_f32 v[218:219], v[66:67], v[234:235], v[218:219] op_sel_hi:[0,1,1]
	v_cvt_pk_f32_fp8_e32 v[236:237], v141
	v_cvt_pk_f32_fp8_sdwa v[238:239], v141 src0_sel:WORD_1
	v_pk_fma_f32 v[220:221], v[66:67], v[236:237], v[220:221] op_sel_hi:[0,1,1]
	v_pk_fma_f32 v[222:223], v[66:67], v[238:239], v[222:223] op_sel_hi:[0,1,1]
	v_cvt_pk_f32_fp8_e32 v[232:233], v142
	v_cvt_pk_f32_fp8_sdwa v[234:235], v142 src0_sel:WORD_1
	v_pk_fma_f32 v[224:225], v[66:67], v[232:233], v[224:225] op_sel_hi:[0,1,1]
	v_pk_fma_f32 v[226:227], v[66:67], v[234:235], v[226:227] op_sel_hi:[0,1,1]
	v_cvt_pk_f32_fp8_e32 v[236:237], v143
	v_cvt_pk_f32_fp8_sdwa v[238:239], v143 src0_sel:WORD_1
	v_pk_fma_f32 v[228:229], v[66:67], v[236:237], v[228:229] op_sel_hi:[0,1,1]
	v_pk_fma_f32 v[230:231], v[66:67], v[238:239], v[230:231] op_sel_hi:[0,1,1]
	s_waitcnt vmcnt(16)
; DI f2_t cvt8lo(unsigned w) { return __builtin_amdgcn_cvt_pk_f32_fp8(w, false); }
; DI f2_t cvt8hi(unsigned w) { return __builtin_amdgcn_cvt_pk_f32_fp8(w, true); }
; DI void wave_lds_sync() { asm volatile("s_waitcnt lgkmcnt(0)" ::: "memory"); __builtin_amdgcn_wave_barrier(); }
; DI void phase11(const Params& p, char* smem, int rep) {
;     ...
;       wave_lds_sync();
;       lw[(lane & 3) * 32 + (lane >> 2)] = i0; lw[(lane & 3) * 32 + 16 + (lane >> 2)] = i1;
;       lf[(lane & 3) * 32 + (lane >> 2)] = a0; lf[(lane & 3) * 32 + 16 + (lane >> 2)] = a1;
;       wave_lds_sync();
;     ...
;         for (int k = 0; k < 16; ++k) rows[k] = *(const u32x4*)(vb + (size_t)ida[k] * 2048);
; #pragma unroll
;         for (int k = 0; k < 16; ++k) {
;           const f2_t a2 = {aa[k], aa[k]};
; #pragma unroll
;           for (int d = 0; d < 4; ++d) { const unsigned ww = rows[k][d]; o[2 * d] += a2 * cvt8lo(ww); o[2 * d + 1] += a2 * cvt8hi(ww); }
	v_cvt_pk_f32_fp8_e32 v[232:233], v144
	v_cvt_pk_f32_fp8_sdwa v[234:235], v144 src0_sel:WORD_1
	v_pk_fma_f32 v[216:217], v[66:67], v[232:233], v[216:217] op_sel:[1,0,0]
	v_pk_fma_f32 v[218:219], v[66:67], v[234:235], v[218:219] op_sel:[1,0,0]
	v_cvt_pk_f32_fp8_e32 v[236:237], v145
	v_cvt_pk_f32_fp8_sdwa v[238:239], v145 src0_sel:WORD_1
	v_pk_fma_f32 v[220:221], v[66:67], v[236:237], v[220:221] op_sel:[1,0,0]
	v_pk_fma_f32 v[222:223], v[66:67], v[238:239], v[222:223] op_sel:[1,0,0]
	v_cvt_pk_f32_fp8_e32 v[232:233], v146
	v_cvt_pk_f32_fp8_sdwa v[234:235], v146 src0_sel:WORD_1
	v_pk_fma_f32 v[224:225], v[66:67], v[232:233], v[224:225] op_sel:[1,0,0]
	v_pk_fma_f32 v[226:227], v[66:67], v[234:235], v[226:227] op_sel:[1,0,0]
	v_cvt_pk_f32_fp8_e32 v[236:237], v147
	v_cvt_pk_f32_fp8_sdwa v[238:239], v147 src0_sel:WORD_1
	v_pk_fma_f32 v[228:229], v[66:67], v[236:237], v[228:229] op_sel:[1,0,0]
	v_pk_fma_f32 v[230:231], v[66:67], v[238:239], v[230:231] op_sel:[1,0,0]
	ds_write2_b32 v5, v10, v11 offset0:4 offset1:20
	ds_write2_b32 v5, v12, v13 offset0:132 offset1:148
	s_waitcnt lgkmcnt(0)
	ds_read_b128 v[20:23], v6 offset:16
	ds_read_b128 v[24:27], v6 offset:32
	ds_read_b128 v[28:31], v6 offset:48
	ds_read_b128 v[32:35], v6 offset:64
	ds_read_b128 v[36:39], v6 offset:80
	ds_read_b128 v[40:43], v6 offset:96
	ds_read_b128 v[44:47], v6 offset:112
	ds_read_b128 v[48:51], v6 offset:128
	s_waitcnt vmcnt(15)
	v_cvt_pk_f32_fp8_e32 v[232:233], v148
	v_cvt_pk_f32_fp8_sdwa v[234:235], v148 src0_sel:WORD_1
	v_pk_fma_f32 v[216:217], v[68:69], v[232:233], v[216:217] op_sel_hi:[0,1,1]
	v_pk_fma_f32 v[218:219], v[68:69], v[234:235], v[218:219] op_sel_hi:[0,1,1]
	v_cvt_pk_f32_fp8_e32 v[236:237], v149
	v_cvt_pk_f32_fp8_sdwa v[238:239], v149 src0_sel:WORD_1
	v_pk_fma_f32 v[220:221], v[68:69], v[236:237], v[220:221] op_sel_hi:[0,1,1]
	v_pk_fma_f32 v[222:223], v[68:69], v[238:239], v[222:223] op_sel_hi:[0,1,1]
	v_cvt_pk_f32_fp8_e32 v[232:233], v150
	v_cvt_pk_f32_fp8_sdwa v[234:235], v150 src0_sel:WORD_1
	v_pk_fma_f32 v[224:225], v[68:69], v[232:233], v[224:225] op_sel_hi:[0,1,1]
	v_pk_fma_f32 v[226:227], v[68:69], v[234:235], v[226:227] op_sel_hi:[0,1,1]
	v_cvt_pk_f32_fp8_e32 v[236:237], v151
	v_cvt_pk_f32_fp8_sdwa v[238:239], v151 src0_sel:WORD_1
	v_pk_fma_f32 v[228:229], v[68:69], v[236:237], v[228:229] op_sel_hi:[0,1,1]
	v_pk_fma_f32 v[230:231], v[68:69], v[238:239], v[230:231] op_sel_hi:[0,1,1]
	s_waitcnt vmcnt(14)
	v_cvt_pk_f32_fp8_e32 v[232:233], v152
	v_cvt_pk_f32_fp8_sdwa v[234:235], v152 src0_sel:WORD_1
	v_pk_fma_f32 v[216:217], v[68:69], v[232:233], v[216:217] op_sel:[1,0,0]
	v_pk_fma_f32 v[218:219], v[68:69], v[234:235], v[218:219] op_sel:[1,0,0]
	v_cvt_pk_f32_fp8_e32 v[236:237], v153
	v_cvt_pk_f32_fp8_sdwa v[238:239], v153 src0_sel:WORD_1
	v_pk_fma_f32 v[220:221], v[68:69], v[236:237], v[220:221] op_sel:[1,0,0]
	v_pk_fma_f32 v[222:223], v[68:69], v[238:239], v[222:223] op_sel:[1,0,0]
	v_cvt_pk_f32_fp8_e32 v[232:233], v154
	v_cvt_pk_f32_fp8_sdwa v[234:235], v154 src0_sel:WORD_1
	v_pk_fma_f32 v[224:225], v[68:69], v[232:233], v[224:225] op_sel:[1,0,0]
	v_pk_fma_f32 v[226:227], v[68:69], v[234:235], v[226:227] op_sel:[1,0,0]
	v_cvt_pk_f32_fp8_e32 v[236:237], v155
	v_cvt_pk_f32_fp8_sdwa v[238:239], v155 src0_sel:WORD_1
	v_pk_fma_f32 v[228:229], v[68:69], v[236:237], v[228:229] op_sel:[1,0,0]
	v_pk_fma_f32 v[230:231], v[68:69], v[238:239], v[230:231] op_sel:[1,0,0]
	s_waitcnt vmcnt(13)
	v_cvt_pk_f32_fp8_e32 v[232:233], v156
	v_cvt_pk_f32_fp8_sdwa v[234:235], v156 src0_sel:WORD_1
	v_pk_fma_f32 v[216:217], v[70:71], v[232:233], v[216:217] op_sel_hi:[0,1,1]
	v_pk_fma_f32 v[218:219], v[70:71], v[234:235], v[218:219] op_sel_hi:[0,1,1]
	v_cvt_pk_f32_fp8_e32 v[236:237], v157
	v_cvt_pk_f32_fp8_sdwa v[238:239], v157 src0_sel:WORD_1
	v_pk_fma_f32 v[220:221], v[70:71], v[236:237], v[220:221] op_sel_hi:[0,1,1]
	v_pk_fma_f32 v[222:223], v[70:71], v[238:239], v[222:223] op_sel_hi:[0,1,1]
	v_cvt_pk_f32_fp8_e32 v[232:233], v158
	v_cvt_pk_f32_fp8_sdwa v[234:235], v158 src0_sel:WORD_1
	v_pk_fma_f32 v[224:225], v[70:71], v[232:233], v[224:225] op_sel_hi:[0,1,1]
	v_pk_fma_f32 v[226:227], v[70:71], v[234:235], v[226:227] op_sel_hi:[0,1,1]
	v_cvt_pk_f32_fp8_e32 v[236:237], v159
	v_cvt_pk_f32_fp8_sdwa v[238:239], v159 src0_sel:WORD_1
	v_pk_fma_f32 v[228:229], v[70:71], v[236:237], v[228:229] op_sel_hi:[0,1,1]
	v_pk_fma_f32 v[230:231], v[70:71], v[238:239], v[230:231] op_sel_hi:[0,1,1]
	s_waitcnt vmcnt(12)
	v_cvt_pk_f32_fp8_e32 v[232:233], v160
	v_cvt_pk_f32_fp8_sdwa v[234:235], v160 src0_sel:WORD_1
	v_pk_fma_f32 v[216:217], v[70:71], v[232:233], v[216:217] op_sel:[1,0,0]
	v_pk_fma_f32 v[218:219], v[70:71], v[234:235], v[218:219] op_sel:[1,0,0]
	v_cvt_pk_f32_fp8_e32 v[236:237], v161
	v_cvt_pk_f32_fp8_sdwa v[238:239], v161 src0_sel:WORD_1
	v_pk_fma_f32 v[220:221], v[70:71], v[236:237], v[220:221] op_sel:[1,0,0]
	v_pk_fma_f32 v[222:223], v[70:71], v[238:239], v[222:223] op_sel:[1,0,0]
	v_cvt_pk_f32_fp8_e32 v[232:233], v162
	v_cvt_pk_f32_fp8_sdwa v[234:235], v162 src0_sel:WORD_1
	v_pk_fma_f32 v[224:225], v[70:71], v[232:233], v[224:225] op_sel:[1,0,0]
	v_pk_fma_f32 v[226:227], v[70:71], v[234:235], v[226:227] op_sel:[1,0,0]
	v_cvt_pk_f32_fp8_e32 v[236:237], v163
	v_cvt_pk_f32_fp8_sdwa v[238:239], v163 src0_sel:WORD_1
	v_pk_fma_f32 v[228:229], v[70:71], v[236:237], v[228:229] op_sel:[1,0,0]
	v_pk_fma_f32 v[230:231], v[70:71], v[238:239], v[230:231] op_sel:[1,0,0]
	s_waitcnt vmcnt(11)
; DI f2_t cvt8lo(unsigned w) { return __builtin_amdgcn_cvt_pk_f32_fp8(w, false); }
; DI f2_t cvt8hi(unsigned w) { return __builtin_amdgcn_cvt_pk_f32_fp8(w, true); }
; DI void phase11(const Params& p, char* smem, int rep) {
;     ...
;         for (int k = 0; k < 16; ++k) rows[k] = *(const u32x4*)(vb + (size_t)ida[k] * 2048);
; #pragma unroll
;         for (int k = 0; k < 16; ++k) {
;           const f2_t a2 = {aa[k], aa[k]};
; #pragma unroll
;           for (int d = 0; d < 4; ++d) { const unsigned ww = rows[k][d]; o[2 * d] += a2 * cvt8lo(ww); o[2 * d + 1] += a2 * cvt8hi(ww); }
	v_cvt_pk_f32_fp8_e32 v[232:233], v164
	v_cvt_pk_f32_fp8_sdwa v[234:235], v164 src0_sel:WORD_1
	v_pk_fma_f32 v[216:217], v[72:73], v[232:233], v[216:217] op_sel_hi:[0,1,1]
	v_pk_fma_f32 v[218:219], v[72:73], v[234:235], v[218:219] op_sel_hi:[0,1,1]
	v_cvt_pk_f32_fp8_e32 v[236:237], v165
	v_cvt_pk_f32_fp8_sdwa v[238:239], v165 src0_sel:WORD_1
	v_pk_fma_f32 v[220:221], v[72:73], v[236:237], v[220:221] op_sel_hi:[0,1,1]
	v_pk_fma_f32 v[222:223], v[72:73], v[238:239], v[222:223] op_sel_hi:[0,1,1]
	v_cvt_pk_f32_fp8_e32 v[232:233], v166
	v_cvt_pk_f32_fp8_sdwa v[234:235], v166 src0_sel:WORD_1
	v_pk_fma_f32 v[224:225], v[72:73], v[232:233], v[224:225] op_sel_hi:[0,1,1]
	v_pk_fma_f32 v[226:227], v[72:73], v[234:235], v[226:227] op_sel_hi:[0,1,1]
	v_cvt_pk_f32_fp8_e32 v[236:237], v167
	v_cvt_pk_f32_fp8_sdwa v[238:239], v167 src0_sel:WORD_1
	v_pk_fma_f32 v[228:229], v[72:73], v[236:237], v[228:229] op_sel_hi:[0,1,1]
	v_pk_fma_f32 v[230:231], v[72:73], v[238:239], v[230:231] op_sel_hi:[0,1,1]
	s_waitcnt vmcnt(10)
	v_cvt_pk_f32_fp8_e32 v[232:233], v168
	v_cvt_pk_f32_fp8_sdwa v[234:235], v168 src0_sel:WORD_1
	v_pk_fma_f32 v[216:217], v[72:73], v[232:233], v[216:217] op_sel:[1,0,0]
	v_pk_fma_f32 v[218:219], v[72:73], v[234:235], v[218:219] op_sel:[1,0,0]
	v_cvt_pk_f32_fp8_e32 v[236:237], v169
	v_cvt_pk_f32_fp8_sdwa v[238:239], v169 src0_sel:WORD_1
	v_pk_fma_f32 v[220:221], v[72:73], v[236:237], v[220:221] op_sel:[1,0,0]
	v_pk_fma_f32 v[222:223], v[72:73], v[238:239], v[222:223] op_sel:[1,0,0]
	v_cvt_pk_f32_fp8_e32 v[232:233], v170
	v_cvt_pk_f32_fp8_sdwa v[234:235], v170 src0_sel:WORD_1
	v_pk_fma_f32 v[224:225], v[72:73], v[232:233], v[224:225] op_sel:[1,0,0]
	v_pk_fma_f32 v[226:227], v[72:73], v[234:235], v[226:227] op_sel:[1,0,0]
	v_cvt_pk_f32_fp8_e32 v[236:237], v171
	v_cvt_pk_f32_fp8_sdwa v[238:239], v171 src0_sel:WORD_1
	v_pk_fma_f32 v[228:229], v[72:73], v[236:237], v[228:229] op_sel:[1,0,0]
	v_pk_fma_f32 v[230:231], v[72:73], v[238:239], v[230:231] op_sel:[1,0,0]
	s_waitcnt vmcnt(9)
	v_cvt_pk_f32_fp8_e32 v[232:233], v172
	v_cvt_pk_f32_fp8_sdwa v[234:235], v172 src0_sel:WORD_1
	v_pk_fma_f32 v[216:217], v[74:75], v[232:233], v[216:217] op_sel_hi:[0,1,1]
	v_pk_fma_f32 v[218:219], v[74:75], v[234:235], v[218:219] op_sel_hi:[0,1,1]
	v_cvt_pk_f32_fp8_e32 v[236:237], v173
	v_cvt_pk_f32_fp8_sdwa v[238:239], v173 src0_sel:WORD_1
	v_pk_fma_f32 v[220:221], v[74:75], v[236:237], v[220:221] op_sel_hi:[0,1,1]
	v_pk_fma_f32 v[222:223], v[74:75], v[238:239], v[222:223] op_sel_hi:[0,1,1]
	v_cvt_pk_f32_fp8_e32 v[232:233], v174
	v_cvt_pk_f32_fp8_sdwa v[234:235], v174 src0_sel:WORD_1
	v_pk_fma_f32 v[224:225], v[74:75], v[232:233], v[224:225] op_sel_hi:[0,1,1]
	v_pk_fma_f32 v[226:227], v[74:75], v[234:235], v[226:227] op_sel_hi:[0,1,1]
	v_cvt_pk_f32_fp8_e32 v[236:237], v175
	v_cvt_pk_f32_fp8_sdwa v[238:239], v175 src0_sel:WORD_1
	v_pk_fma_f32 v[228:229], v[74:75], v[236:237], v[228:229] op_sel_hi:[0,1,1]
	v_pk_fma_f32 v[230:231], v[74:75], v[238:239], v[230:231] op_sel_hi:[0,1,1]
	s_waitcnt vmcnt(8)
	v_cvt_pk_f32_fp8_e32 v[232:233], v176
	v_cvt_pk_f32_fp8_sdwa v[234:235], v176 src0_sel:WORD_1
	v_pk_fma_f32 v[216:217], v[74:75], v[232:233], v[216:217] op_sel:[1,0,0]
	v_pk_fma_f32 v[218:219], v[74:75], v[234:235], v[218:219] op_sel:[1,0,0]
	v_cvt_pk_f32_fp8_e32 v[236:237], v177
	v_cvt_pk_f32_fp8_sdwa v[238:239], v177 src0_sel:WORD_1
	v_pk_fma_f32 v[220:221], v[74:75], v[236:237], v[220:221] op_sel:[1,0,0]
	v_pk_fma_f32 v[222:223], v[74:75], v[238:239], v[222:223] op_sel:[1,0,0]
	v_cvt_pk_f32_fp8_e32 v[232:233], v178
	v_cvt_pk_f32_fp8_sdwa v[234:235], v178 src0_sel:WORD_1
	v_pk_fma_f32 v[224:225], v[74:75], v[232:233], v[224:225] op_sel:[1,0,0]
	v_pk_fma_f32 v[226:227], v[74:75], v[234:235], v[226:227] op_sel:[1,0,0]
	v_cvt_pk_f32_fp8_e32 v[236:237], v179
	v_cvt_pk_f32_fp8_sdwa v[238:239], v179 src0_sel:WORD_1
	v_pk_fma_f32 v[228:229], v[74:75], v[236:237], v[228:229] op_sel:[1,0,0]
	v_pk_fma_f32 v[230:231], v[74:75], v[238:239], v[230:231] op_sel:[1,0,0]
	s_waitcnt vmcnt(7)
	v_cvt_pk_f32_fp8_e32 v[232:233], v180
	v_cvt_pk_f32_fp8_sdwa v[234:235], v180 src0_sel:WORD_1
	v_pk_fma_f32 v[216:217], v[76:77], v[232:233], v[216:217] op_sel_hi:[0,1,1]
	v_pk_fma_f32 v[218:219], v[76:77], v[234:235], v[218:219] op_sel_hi:[0,1,1]
	v_cvt_pk_f32_fp8_e32 v[236:237], v181
	v_cvt_pk_f32_fp8_sdwa v[238:239], v181 src0_sel:WORD_1
	v_pk_fma_f32 v[220:221], v[76:77], v[236:237], v[220:221] op_sel_hi:[0,1,1]
	v_pk_fma_f32 v[222:223], v[76:77], v[238:239], v[222:223] op_sel_hi:[0,1,1]
	v_cvt_pk_f32_fp8_e32 v[232:233], v182
	v_cvt_pk_f32_fp8_sdwa v[234:235], v182 src0_sel:WORD_1
	v_pk_fma_f32 v[224:225], v[76:77], v[232:233], v[224:225] op_sel_hi:[0,1,1]
	v_pk_fma_f32 v[226:227], v[76:77], v[234:235], v[226:227] op_sel_hi:[0,1,1]
	v_cvt_pk_f32_fp8_e32 v[236:237], v183
	v_cvt_pk_f32_fp8_sdwa v[238:239], v183 src0_sel:WORD_1
	v_pk_fma_f32 v[228:229], v[76:77], v[236:237], v[228:229] op_sel_hi:[0,1,1]
	v_pk_fma_f32 v[230:231], v[76:77], v[238:239], v[230:231] op_sel_hi:[0,1,1]
	s_waitcnt vmcnt(6)
	v_cvt_pk_f32_fp8_e32 v[232:233], v184
	v_cvt_pk_f32_fp8_sdwa v[234:235], v184 src0_sel:WORD_1
	v_pk_fma_f32 v[216:217], v[76:77], v[232:233], v[216:217] op_sel:[1,0,0]
	v_pk_fma_f32 v[218:219], v[76:77], v[234:235], v[218:219] op_sel:[1,0,0]
	v_cvt_pk_f32_fp8_e32 v[236:237], v185
	v_cvt_pk_f32_fp8_sdwa v[238:239], v185 src0_sel:WORD_1
	v_pk_fma_f32 v[220:221], v[76:77], v[236:237], v[220:221] op_sel:[1,0,0]
	v_pk_fma_f32 v[222:223], v[76:77], v[238:239], v[222:223] op_sel:[1,0,0]
	v_cvt_pk_f32_fp8_e32 v[232:233], v186
	v_cvt_pk_f32_fp8_sdwa v[234:235], v186 src0_sel:WORD_1
	v_pk_fma_f32 v[224:225], v[76:77], v[232:233], v[224:225] op_sel:[1,0,0]
	v_pk_fma_f32 v[226:227], v[76:77], v[234:235], v[226:227] op_sel:[1,0,0]
	v_cvt_pk_f32_fp8_e32 v[236:237], v187
	v_cvt_pk_f32_fp8_sdwa v[238:239], v187 src0_sel:WORD_1
	v_pk_fma_f32 v[228:229], v[76:77], v[236:237], v[228:229] op_sel:[1,0,0]
	v_pk_fma_f32 v[230:231], v[76:77], v[238:239], v[230:231] op_sel:[1,0,0]
	s_waitcnt vmcnt(5)
; DI f2_t cvt8lo(unsigned w) { return __builtin_amdgcn_cvt_pk_f32_fp8(w, false); }
; DI f2_t cvt8hi(unsigned w) { return __builtin_amdgcn_cvt_pk_f32_fp8(w, true); }
; DI void phase11(const Params& p, char* smem, int rep) {
;     ...
;         for (int k = 0; k < 16; ++k) rows[k] = *(const u32x4*)(vb + (size_t)ida[k] * 2048);
; #pragma unroll
;         for (int k = 0; k < 16; ++k) {
;           const f2_t a2 = {aa[k], aa[k]};
; #pragma unroll
;           for (int d = 0; d < 4; ++d) { const unsigned ww = rows[k][d]; o[2 * d] += a2 * cvt8lo(ww); o[2 * d + 1] += a2 * cvt8hi(ww); }
	v_cvt_pk_f32_fp8_e32 v[232:233], v190
	v_cvt_pk_f32_fp8_sdwa v[234:235], v190 src0_sel:WORD_1
	v_pk_fma_f32 v[216:217], v[78:79], v[232:233], v[216:217] op_sel_hi:[0,1,1]
	v_pk_fma_f32 v[218:219], v[78:79], v[234:235], v[218:219] op_sel_hi:[0,1,1]
	v_cvt_pk_f32_fp8_e32 v[236:237], v191
	v_cvt_pk_f32_fp8_sdwa v[238:239], v191 src0_sel:WORD_1
	v_pk_fma_f32 v[220:221], v[78:79], v[236:237], v[220:221] op_sel_hi:[0,1,1]
	v_pk_fma_f32 v[222:223], v[78:79], v[238:239], v[222:223] op_sel_hi:[0,1,1]
	v_cvt_pk_f32_fp8_e32 v[232:233], v192
	v_cvt_pk_f32_fp8_sdwa v[234:235], v192 src0_sel:WORD_1
	v_pk_fma_f32 v[224:225], v[78:79], v[232:233], v[224:225] op_sel_hi:[0,1,1]
	v_pk_fma_f32 v[226:227], v[78:79], v[234:235], v[226:227] op_sel_hi:[0,1,1]
	v_cvt_pk_f32_fp8_e32 v[236:237], v193
	v_cvt_pk_f32_fp8_sdwa v[238:239], v193 src0_sel:WORD_1
	v_pk_fma_f32 v[228:229], v[78:79], v[236:237], v[228:229] op_sel_hi:[0,1,1]
	v_pk_fma_f32 v[230:231], v[78:79], v[238:239], v[230:231] op_sel_hi:[0,1,1]
	s_waitcnt vmcnt(4)
	v_cvt_pk_f32_fp8_e32 v[232:233], v194
	v_cvt_pk_f32_fp8_sdwa v[234:235], v194 src0_sel:WORD_1
	v_pk_fma_f32 v[216:217], v[78:79], v[232:233], v[216:217] op_sel:[1,0,0]
	v_pk_fma_f32 v[218:219], v[78:79], v[234:235], v[218:219] op_sel:[1,0,0]
	v_cvt_pk_f32_fp8_e32 v[236:237], v195
	v_cvt_pk_f32_fp8_sdwa v[238:239], v195 src0_sel:WORD_1
	v_pk_fma_f32 v[220:221], v[78:79], v[236:237], v[220:221] op_sel:[1,0,0]
	v_pk_fma_f32 v[222:223], v[78:79], v[238:239], v[222:223] op_sel:[1,0,0]
	v_cvt_pk_f32_fp8_e32 v[232:233], v196
	v_cvt_pk_f32_fp8_sdwa v[234:235], v196 src0_sel:WORD_1
	v_pk_fma_f32 v[224:225], v[78:79], v[232:233], v[224:225] op_sel:[1,0,0]
	v_pk_fma_f32 v[226:227], v[78:79], v[234:235], v[226:227] op_sel:[1,0,0]
	v_cvt_pk_f32_fp8_e32 v[236:237], v197
	v_cvt_pk_f32_fp8_sdwa v[238:239], v197 src0_sel:WORD_1
	v_pk_fma_f32 v[228:229], v[78:79], v[236:237], v[228:229] op_sel:[1,0,0]
	v_pk_fma_f32 v[230:231], v[78:79], v[238:239], v[230:231] op_sel:[1,0,0]
	s_waitcnt vmcnt(3)
	v_cvt_pk_f32_fp8_e32 v[232:233], v198
	v_cvt_pk_f32_fp8_sdwa v[234:235], v198 src0_sel:WORD_1
	v_pk_fma_f32 v[216:217], v[80:81], v[232:233], v[216:217] op_sel_hi:[0,1,1]
	v_pk_fma_f32 v[218:219], v[80:81], v[234:235], v[218:219] op_sel_hi:[0,1,1]
	v_cvt_pk_f32_fp8_e32 v[236:237], v199
	v_cvt_pk_f32_fp8_sdwa v[238:239], v199 src0_sel:WORD_1
	v_pk_fma_f32 v[220:221], v[80:81], v[236:237], v[220:221] op_sel_hi:[0,1,1]
	v_pk_fma_f32 v[222:223], v[80:81], v[238:239], v[222:223] op_sel_hi:[0,1,1]
	v_cvt_pk_f32_fp8_e32 v[232:233], v200
	v_cvt_pk_f32_fp8_sdwa v[234:235], v200 src0_sel:WORD_1
	v_pk_fma_f32 v[224:225], v[80:81], v[232:233], v[224:225] op_sel_hi:[0,1,1]
	v_pk_fma_f32 v[226:227], v[80:81], v[234:235], v[226:227] op_sel_hi:[0,1,1]
	v_cvt_pk_f32_fp8_e32 v[236:237], v201
	v_cvt_pk_f32_fp8_sdwa v[238:239], v201 src0_sel:WORD_1
	v_pk_fma_f32 v[228:229], v[80:81], v[236:237], v[228:229] op_sel_hi:[0,1,1]
	v_pk_fma_f32 v[230:231], v[80:81], v[238:239], v[230:231] op_sel_hi:[0,1,1]
	s_waitcnt vmcnt(2)
	v_cvt_pk_f32_fp8_e32 v[232:233], v202
	v_cvt_pk_f32_fp8_sdwa v[234:235], v202 src0_sel:WORD_1
	v_pk_fma_f32 v[216:217], v[80:81], v[232:233], v[216:217] op_sel:[1,0,0]
	v_pk_fma_f32 v[218:219], v[80:81], v[234:235], v[218:219] op_sel:[1,0,0]
	v_cvt_pk_f32_fp8_e32 v[236:237], v203
	v_cvt_pk_f32_fp8_sdwa v[238:239], v203 src0_sel:WORD_1
	v_pk_fma_f32 v[220:221], v[80:81], v[236:237], v[220:221] op_sel:[1,0,0]
	v_pk_fma_f32 v[222:223], v[80:81], v[238:239], v[222:223] op_sel:[1,0,0]
	v_cvt_pk_f32_fp8_e32 v[232:233], v204
	v_cvt_pk_f32_fp8_sdwa v[234:235], v204 src0_sel:WORD_1
	v_pk_fma_f32 v[224:225], v[80:81], v[232:233], v[224:225] op_sel:[1,0,0]
	v_pk_fma_f32 v[226:227], v[80:81], v[234:235], v[226:227] op_sel:[1,0,0]
	v_cvt_pk_f32_fp8_e32 v[236:237], v205
	v_cvt_pk_f32_fp8_sdwa v[238:239], v205 src0_sel:WORD_1
	v_pk_fma_f32 v[228:229], v[80:81], v[236:237], v[228:229] op_sel:[1,0,0]
	v_pk_fma_f32 v[230:231], v[80:81], v[238:239], v[230:231] op_sel:[1,0,0]
	s_waitcnt vmcnt(1)
	v_cvt_pk_f32_fp8_e32 v[232:233], v206
	v_cvt_pk_f32_fp8_sdwa v[234:235], v206 src0_sel:WORD_1
	v_pk_fma_f32 v[216:217], v[82:83], v[232:233], v[216:217] op_sel_hi:[0,1,1]
	v_pk_fma_f32 v[218:219], v[82:83], v[234:235], v[218:219] op_sel_hi:[0,1,1]
	v_cvt_pk_f32_fp8_e32 v[236:237], v207
	v_cvt_pk_f32_fp8_sdwa v[238:239], v207 src0_sel:WORD_1
	v_pk_fma_f32 v[220:221], v[82:83], v[236:237], v[220:221] op_sel_hi:[0,1,1]
	v_pk_fma_f32 v[222:223], v[82:83], v[238:239], v[222:223] op_sel_hi:[0,1,1]
	v_cvt_pk_f32_fp8_e32 v[232:233], v208
	v_cvt_pk_f32_fp8_sdwa v[234:235], v208 src0_sel:WORD_1
	v_pk_fma_f32 v[224:225], v[82:83], v[232:233], v[224:225] op_sel_hi:[0,1,1]
	v_pk_fma_f32 v[226:227], v[82:83], v[234:235], v[226:227] op_sel_hi:[0,1,1]
	v_cvt_pk_f32_fp8_e32 v[236:237], v209
	v_cvt_pk_f32_fp8_sdwa v[238:239], v209 src0_sel:WORD_1
	v_pk_fma_f32 v[228:229], v[82:83], v[236:237], v[228:229] op_sel_hi:[0,1,1]
	v_pk_fma_f32 v[230:231], v[82:83], v[238:239], v[230:231] op_sel_hi:[0,1,1]
	s_waitcnt vmcnt(0)
; DI unsigned pk2(float a, float b) { f2_t v = {a, b}; bf2_t r = __builtin_convertvector(v, bf2_t); return __builtin_bit_cast(unsigned, r); }
; DI void wave_lds_sync() { asm volatile("s_waitcnt lgkmcnt(0)" ::: "memory"); __builtin_amdgcn_wave_barrier(); }
; DI void phase11(const Params& p, char* smem, int rep) {
;     ...
;       const int tok = __builtin_amdgcn_readfirstlane(c * 16 + w * 4 + t);
;       const int i0 = IDS[(size_t)tok * 128 + lane], i1 = IDS[(size_t)tok * 128 + 64 + lane];
;       const float a0 = ACT[(size_t)tok * 128 + lane], a1 = ACT[(size_t)tok * 128 + 64 + lane];
;       wave_lds_sync();
;       lw[(lane & 3) * 32 + (lane >> 2)] = i0; lw[(lane & 3) * 32 + 16 + (lane >> 2)] = i1;
;       lf[(lane & 3) * 32 + (lane >> 2)] = a0; lf[(lane & 3) * 32 + 16 + (lane >> 2)] = a1;
;       wave_lds_sync();
;       f2_t o[8];
; #pragma unroll
;       for (int i = 0; i < 8; ++i) o[i] = f2_t{0.f, 0.f};
;       const unsigned char* vb = V8 + s * 256 + l15 * 16;
; #pragma unroll
;       for (int batch = 0; batch < 2; ++batch) {
;         int ida[16]; float aa[16];
; #pragma unroll
;         for (int q = 0; q < 4; ++q) {
;           const int4 v = *(const int4*)(lw + g * 32 + batch * 16 + q * 4); ida[q * 4] = v.x; ida[q * 4 + 1] = v.y; ida[q * 4 + 2] = v.z; ida[q * 4 + 3] = v.w;
;           const float4 f = *(const float4*)(lf + g * 32 + batch * 16 + q * 4); aa[q * 4] = f.x; aa[q * 4 + 1] = f.y; aa[q * 4 + 2] = f.z; aa[q * 4 + 3] = f.w;
;         }
;         u32x4 rows[16];
; #pragma unroll
;         for (int k = 0; k < 16; ++k) rows[k] = *(const u32x4*)(vb + (size_t)ida[k] * 2048);
;     ...
;       float ov[16];
; #pragma unroll
;       for (int d = 0; d < 4; ++d) { ov[4 * d] = o[2 * d].x; ov[4 * d + 1] = o[2 * d].y; ov[4 * d + 2] = o[2 * d + 1].x; ov[4 * d + 3] = o[2 * d + 1].y; }
;       float q8[8], q4[4];
; #pragma unroll
;       for (int k = 0; k < 8; ++k) q8[k] = (b5 ? ov[8 + k] : ov[k]) + __shfl_xor(b5 ? ov[k] : ov[8 + k], 32);
; #pragma unroll
;       for (int k = 0; k < 4; ++k) q4[k] = (b4 ? q8[4 + k] : q8[k]) + __shfl_xor(b4 ? q8[k] : q8[4 + k], 16);
;       *(uint2*)(OUTP + (size_t)tok * D_ + s * 256 + l15 * 16 + 8 * b5 + 4 * b4) = make_uint2(pk2(q4[0], q4[1]), pk2(q4[2], q4[3]));
	v_cvt_pk_f32_fp8_e32 v[232:233], v210
	v_cvt_pk_f32_fp8_sdwa v[234:235], v210 src0_sel:WORD_1
	v_pk_fma_f32 v[216:217], v[82:83], v[232:233], v[216:217] op_sel:[1,0,0]
	v_pk_fma_f32 v[218:219], v[82:83], v[234:235], v[218:219] op_sel:[1,0,0]
	v_cvt_pk_f32_fp8_e32 v[236:237], v211
	v_cvt_pk_f32_fp8_sdwa v[238:239], v211 src0_sel:WORD_1
	v_pk_fma_f32 v[220:221], v[82:83], v[236:237], v[220:221] op_sel:[1,0,0]
	v_pk_fma_f32 v[222:223], v[82:83], v[238:239], v[222:223] op_sel:[1,0,0]
	v_cvt_pk_f32_fp8_e32 v[232:233], v212
	v_cvt_pk_f32_fp8_sdwa v[234:235], v212 src0_sel:WORD_1
	v_pk_fma_f32 v[224:225], v[82:83], v[232:233], v[224:225] op_sel:[1,0,0]
	v_pk_fma_f32 v[226:227], v[82:83], v[234:235], v[226:227] op_sel:[1,0,0]
	v_cvt_pk_f32_fp8_e32 v[236:237], v213
	v_cvt_pk_f32_fp8_sdwa v[238:239], v213 src0_sel:WORD_1
	v_pk_fma_f32 v[228:229], v[82:83], v[236:237], v[228:229] op_sel:[1,0,0]
	v_pk_fma_f32 v[230:231], v[82:83], v[238:239], v[230:231] op_sel:[1,0,0]
	ds_read_b128 v[52:55], v6 offset:528
	ds_read_b128 v[56:59], v6 offset:544
	ds_read_b128 v[60:63], v6 offset:560
	ds_read_b128 v[64:67], v6 offset:576
	ds_read_b128 v[68:71], v6 offset:592
	ds_read_b128 v[72:75], v6 offset:608
	ds_read_b128 v[76:79], v6 offset:624
	ds_read_b128 v[80:83], v6 offset:640
	v_add_u32_e32 v214, s46, v4
	s_nop 0
	v_permlane32_swap_b32_e32 v216, v224
	v_permlane32_swap_b32_e32 v217, v225
	v_permlane32_swap_b32_e32 v218, v226
	v_permlane32_swap_b32_e32 v219, v227
	v_permlane32_swap_b32_e32 v220, v228
	v_permlane32_swap_b32_e32 v221, v229
	v_permlane32_swap_b32_e32 v222, v230
	v_permlane32_swap_b32_e32 v223, v231
	v_add_f32_e32 v216, v216, v224
	v_add_f32_e32 v217, v217, v225
	v_add_f32_e32 v218, v218, v226
	v_add_f32_e32 v219, v219, v227
	v_add_f32_e32 v220, v220, v228
	v_add_f32_e32 v221, v221, v229
	v_add_f32_e32 v222, v222, v230
	v_add_f32_e32 v223, v223, v231
	s_nop 1
	v_permlane16_swap_b32_e32 v216, v220
	v_permlane16_swap_b32_e32 v217, v221
	v_permlane16_swap_b32_e32 v218, v222
	v_permlane16_swap_b32_e32 v219, v223
	v_add_f32_e32 v216, v216, v220
	v_add_f32_e32 v217, v217, v221
	v_add_f32_e32 v218, v218, v222
	v_add_f32_e32 v219, v219, v223
	v_cvt_pk_bf16_f32 v232, v216, v217
	v_cvt_pk_bf16_f32 v233, v218, v219
	global_store_dwordx2 v214, v[232:233], s[14:15]
	s_add_i32 s36, s34, 3
	s_lshl_b32 s46, s36, 12
	s_add_i32 s46, s46, s24
	s_add_i32 s37, s34, 4
	s_add_i32 s51, s48, 1
	s_cmp_lt_u32 s51, s49
	s_cselect_b32 s37, s37, 8192
	s_cmp_lt_u32 s37, 8192
	s_cselect_b32 s37, s37, 0
	s_lshl_b32 s47, s37, 9
	s_add_u32 s42, s6, s47
	s_addc_u32 s43, s7, 0
	s_add_u32 s44, s8, s47
	s_addc_u32 s45, s9, 0
	global_load_dword v10, v3, s[42:43]
	global_load_dword v11, v3, s[42:43] offset:256
	global_load_dword v12, v3, s[44:45]
	global_load_dword v13, v3, s[44:45] offset:256
	s_waitcnt lgkmcnt(0)
	v_lshl_add_u32 v20, v20, 11, v2
	v_lshl_add_u32 v21, v21, 11, v2
	v_lshl_add_u32 v22, v22, 11, v2
	v_lshl_add_u32 v23, v23, 11, v2
	v_lshl_add_u32 v24, v24, 11, v2
	v_lshl_add_u32 v25, v25, 11, v2
	v_lshl_add_u32 v26, v26, 11, v2
	v_lshl_add_u32 v27, v27, 11, v2
	v_lshl_add_u32 v28, v28, 11, v2
	v_lshl_add_u32 v29, v29, 11, v2
	v_lshl_add_u32 v30, v30, 11, v2
	v_lshl_add_u32 v31, v31, 11, v2
	v_lshl_add_u32 v32, v32, 11, v2
	v_lshl_add_u32 v33, v33, 11, v2
	v_lshl_add_u32 v34, v34, 11, v2
	v_lshl_add_u32 v35, v35, 11, v2
	v_lshl_add_u32 v36, v36, 11, v2
	v_lshl_add_u32 v37, v37, 11, v2
	v_lshl_add_u32 v38, v38, 11, v2
	v_lshl_add_u32 v39, v39, 11, v2
	v_lshl_add_u32 v40, v40, 11, v2
	v_lshl_add_u32 v41, v41, 11, v2
	v_lshl_add_u32 v42, v42, 11, v2
	v_lshl_add_u32 v43, v43, 11, v2
	v_lshl_add_u32 v44, v44, 11, v2
	v_lshl_add_u32 v45, v45, 11, v2
	v_lshl_add_u32 v46, v46, 11, v2
	v_lshl_add_u32 v47, v47, 11, v2
	v_lshl_add_u32 v48, v48, 11, v2
	v_lshl_add_u32 v49, v49, 11, v2
	v_lshl_add_u32 v50, v50, 11, v2
	v_lshl_add_u32 v51, v51, 11, v2
	global_load_dwordx4 v[84:87], v20, s[20:21]
	global_load_dwordx4 v[88:91], v21, s[20:21]
	global_load_dwordx4 v[92:95], v22, s[20:21]
	global_load_dwordx4 v[96:99], v23, s[20:21]
	global_load_dwordx4 v[100:103], v24, s[20:21]
	global_load_dwordx4 v[104:107], v25, s[20:21]
	global_load_dwordx4 v[108:111], v26, s[20:21]
	global_load_dwordx4 v[112:115], v27, s[20:21]
	global_load_dwordx4 v[116:119], v28, s[20:21]
	global_load_dwordx4 v[120:123], v29, s[20:21]
	global_load_dwordx4 v[124:127], v30, s[20:21]
	global_load_dwordx4 v[128:131], v31, s[20:21]
	global_load_dwordx4 v[132:135], v32, s[20:21]
	global_load_dwordx4 v[136:139], v33, s[20:21]
	global_load_dwordx4 v[140:143], v34, s[20:21]
	global_load_dwordx4 v[144:147], v35, s[20:21]
	global_load_dwordx4 v[148:151], v36, s[20:21]
	global_load_dwordx4 v[152:155], v37, s[20:21]
	global_load_dwordx4 v[156:159], v38, s[20:21]
	global_load_dwordx4 v[160:163], v39, s[20:21]
	global_load_dwordx4 v[164:167], v40, s[20:21]
	global_load_dwordx4 v[168:171], v41, s[20:21]
	global_load_dwordx4 v[172:175], v42, s[20:21]
	global_load_dwordx4 v[176:179], v43, s[20:21]
	global_load_dwordx4 v[180:183], v44, s[20:21]
	global_load_dwordx4 v[184:187], v45, s[20:21]
	global_load_dwordx4 v[190:193], v46, s[20:21]
	global_load_dwordx4 v[194:197], v47, s[20:21]
	global_load_dwordx4 v[198:201], v48, s[20:21]
	global_load_dwordx4 v[202:205], v49, s[20:21]
	global_load_dwordx4 v[206:209], v50, s[20:21]
	global_load_dwordx4 v[210:213], v51, s[20:21]
	s_waitcnt vmcnt(31)
; DI f2_t cvt8lo(unsigned w) { return __builtin_amdgcn_cvt_pk_f32_fp8(w, false); }
; DI f2_t cvt8hi(unsigned w) { return __builtin_amdgcn_cvt_pk_f32_fp8(w, true); }
; DI void phase11(const Params& p, char* smem, int rep) {
;     ...
; #pragma unroll
;         for (int k = 0; k < 16; ++k) {
;           const f2_t a2 = {aa[k], aa[k]};
; #pragma unroll
;           for (int d = 0; d < 4; ++d) { const unsigned ww = rows[k][d]; o[2 * d] += a2 * cvt8lo(ww); o[2 * d + 1] += a2 * cvt8hi(ww); }
;         }
	v_cvt_pk_f32_fp8_e32 v[232:233], v84
	v_cvt_pk_f32_fp8_sdwa v[234:235], v84 src0_sel:WORD_1
	v_pk_fma_f32 v[216:217], v[52:53], v[232:233], 0 op_sel_hi:[0,1,0]
	v_pk_fma_f32 v[218:219], v[52:53], v[234:235], 0 op_sel_hi:[0,1,0]
	v_cvt_pk_f32_fp8_e32 v[236:237], v85
	v_cvt_pk_f32_fp8_sdwa v[238:239], v85 src0_sel:WORD_1
	v_pk_fma_f32 v[220:221], v[52:53], v[236:237], 0 op_sel_hi:[0,1,0]
	v_pk_fma_f32 v[222:223], v[52:53], v[238:239], 0 op_sel_hi:[0,1,0]
	v_cvt_pk_f32_fp8_e32 v[232:233], v86
	v_cvt_pk_f32_fp8_sdwa v[234:235], v86 src0_sel:WORD_1
	v_pk_fma_f32 v[224:225], v[52:53], v[232:233], 0 op_sel_hi:[0,1,0]
	v_pk_fma_f32 v[226:227], v[52:53], v[234:235], 0 op_sel_hi:[0,1,0]
	v_cvt_pk_f32_fp8_e32 v[236:237], v87
	v_cvt_pk_f32_fp8_sdwa v[238:239], v87 src0_sel:WORD_1
	v_pk_fma_f32 v[228:229], v[52:53], v[236:237], 0 op_sel_hi:[0,1,0]
	v_pk_fma_f32 v[230:231], v[52:53], v[238:239], 0 op_sel_hi:[0,1,0]
	s_waitcnt vmcnt(30)
	v_cvt_pk_f32_fp8_e32 v[232:233], v88
	v_cvt_pk_f32_fp8_sdwa v[234:235], v88 src0_sel:WORD_1
	v_pk_fma_f32 v[216:217], v[52:53], v[232:233], v[216:217] op_sel:[1,0,0]
	v_pk_fma_f32 v[218:219], v[52:53], v[234:235], v[218:219] op_sel:[1,0,0]
	v_cvt_pk_f32_fp8_e32 v[236:237], v89
	v_cvt_pk_f32_fp8_sdwa v[238:239], v89 src0_sel:WORD_1
	v_pk_fma_f32 v[220:221], v[52:53], v[236:237], v[220:221] op_sel:[1,0,0]
	v_pk_fma_f32 v[222:223], v[52:53], v[238:239], v[222:223] op_sel:[1,0,0]
	v_cvt_pk_f32_fp8_e32 v[232:233], v90
	v_cvt_pk_f32_fp8_sdwa v[234:235], v90 src0_sel:WORD_1
	v_pk_fma_f32 v[224:225], v[52:53], v[232:233], v[224:225] op_sel:[1,0,0]
	v_pk_fma_f32 v[226:227], v[52:53], v[234:235], v[226:227] op_sel:[1,0,0]
	v_cvt_pk_f32_fp8_e32 v[236:237], v91
	v_cvt_pk_f32_fp8_sdwa v[238:239], v91 src0_sel:WORD_1
	v_pk_fma_f32 v[228:229], v[52:53], v[236:237], v[228:229] op_sel:[1,0,0]
	v_pk_fma_f32 v[230:231], v[52:53], v[238:239], v[230:231] op_sel:[1,0,0]
	s_waitcnt vmcnt(29)
	v_cvt_pk_f32_fp8_e32 v[232:233], v92
	v_cvt_pk_f32_fp8_sdwa v[234:235], v92 src0_sel:WORD_1
	v_pk_fma_f32 v[216:217], v[54:55], v[232:233], v[216:217] op_sel_hi:[0,1,1]
	v_pk_fma_f32 v[218:219], v[54:55], v[234:235], v[218:219] op_sel_hi:[0,1,1]
	v_cvt_pk_f32_fp8_e32 v[236:237], v93
	v_cvt_pk_f32_fp8_sdwa v[238:239], v93 src0_sel:WORD_1
	v_pk_fma_f32 v[220:221], v[54:55], v[236:237], v[220:221] op_sel_hi:[0,1,1]
	v_pk_fma_f32 v[222:223], v[54:55], v[238:239], v[222:223] op_sel_hi:[0,1,1]
	v_cvt_pk_f32_fp8_e32 v[232:233], v94
	v_cvt_pk_f32_fp8_sdwa v[234:235], v94 src0_sel:WORD_1
	v_pk_fma_f32 v[224:225], v[54:55], v[232:233], v[224:225] op_sel_hi:[0,1,1]
	v_pk_fma_f32 v[226:227], v[54:55], v[234:235], v[226:227] op_sel_hi:[0,1,1]
	v_cvt_pk_f32_fp8_e32 v[236:237], v95
	v_cvt_pk_f32_fp8_sdwa v[238:239], v95 src0_sel:WORD_1
	v_pk_fma_f32 v[228:229], v[54:55], v[236:237], v[228:229] op_sel_hi:[0,1,1]
	v_pk_fma_f32 v[230:231], v[54:55], v[238:239], v[230:231] op_sel_hi:[0,1,1]
	s_waitcnt vmcnt(28)
	v_cvt_pk_f32_fp8_e32 v[232:233], v96
	v_cvt_pk_f32_fp8_sdwa v[234:235], v96 src0_sel:WORD_1
	v_pk_fma_f32 v[216:217], v[54:55], v[232:233], v[216:217] op_sel:[1,0,0]
	v_pk_fma_f32 v[218:219], v[54:55], v[234:235], v[218:219] op_sel:[1,0,0]
	v_cvt_pk_f32_fp8_e32 v[236:237], v97
	v_cvt_pk_f32_fp8_sdwa v[238:239], v97 src0_sel:WORD_1
	v_pk_fma_f32 v[220:221], v[54:55], v[236:237], v[220:221] op_sel:[1,0,0]
	v_pk_fma_f32 v[222:223], v[54:55], v[238:239], v[222:223] op_sel:[1,0,0]
	v_cvt_pk_f32_fp8_e32 v[232:233], v98
	v_cvt_pk_f32_fp8_sdwa v[234:235], v98 src0_sel:WORD_1
	v_pk_fma_f32 v[224:225], v[54:55], v[232:233], v[224:225] op_sel:[1,0,0]
	v_pk_fma_f32 v[226:227], v[54:55], v[234:235], v[226:227] op_sel:[1,0,0]
	v_cvt_pk_f32_fp8_e32 v[236:237], v99
	v_cvt_pk_f32_fp8_sdwa v[238:239], v99 src0_sel:WORD_1
	v_pk_fma_f32 v[228:229], v[54:55], v[236:237], v[228:229] op_sel:[1,0,0]
	v_pk_fma_f32 v[230:231], v[54:55], v[238:239], v[230:231] op_sel:[1,0,0]
	s_waitcnt vmcnt(27)
	v_cvt_pk_f32_fp8_e32 v[232:233], v100
	v_cvt_pk_f32_fp8_sdwa v[234:235], v100 src0_sel:WORD_1
	v_pk_fma_f32 v[216:217], v[56:57], v[232:233], v[216:217] op_sel_hi:[0,1,1]
	v_pk_fma_f32 v[218:219], v[56:57], v[234:235], v[218:219] op_sel_hi:[0,1,1]
	v_cvt_pk_f32_fp8_e32 v[236:237], v101
	v_cvt_pk_f32_fp8_sdwa v[238:239], v101 src0_sel:WORD_1
	v_pk_fma_f32 v[220:221], v[56:57], v[236:237], v[220:221] op_sel_hi:[0,1,1]
	v_pk_fma_f32 v[222:223], v[56:57], v[238:239], v[222:223] op_sel_hi:[0,1,1]
	v_cvt_pk_f32_fp8_e32 v[232:233], v102
	v_cvt_pk_f32_fp8_sdwa v[234:235], v102 src0_sel:WORD_1
	v_pk_fma_f32 v[224:225], v[56:57], v[232:233], v[224:225] op_sel_hi:[0,1,1]
	v_pk_fma_f32 v[226:227], v[56:57], v[234:235], v[226:227] op_sel_hi:[0,1,1]
	v_cvt_pk_f32_fp8_e32 v[236:237], v103
	v_cvt_pk_f32_fp8_sdwa v[238:239], v103 src0_sel:WORD_1
	v_pk_fma_f32 v[228:229], v[56:57], v[236:237], v[228:229] op_sel_hi:[0,1,1]
	v_pk_fma_f32 v[230:231], v[56:57], v[238:239], v[230:231] op_sel_hi:[0,1,1]
	s_waitcnt vmcnt(26)
	v_cvt_pk_f32_fp8_e32 v[232:233], v104
	v_cvt_pk_f32_fp8_sdwa v[234:235], v104 src0_sel:WORD_1
	v_pk_fma_f32 v[216:217], v[56:57], v[232:233], v[216:217] op_sel:[1,0,0]
	v_pk_fma_f32 v[218:219], v[56:57], v[234:235], v[218:219] op_sel:[1,0,0]
	v_cvt_pk_f32_fp8_e32 v[236:237], v105
	v_cvt_pk_f32_fp8_sdwa v[238:239], v105 src0_sel:WORD_1
	v_pk_fma_f32 v[220:221], v[56:57], v[236:237], v[220:221] op_sel:[1,0,0]
	v_pk_fma_f32 v[222:223], v[56:57], v[238:239], v[222:223] op_sel:[1,0,0]
	v_cvt_pk_f32_fp8_e32 v[232:233], v106
	v_cvt_pk_f32_fp8_sdwa v[234:235], v106 src0_sel:WORD_1
	v_pk_fma_f32 v[224:225], v[56:57], v[232:233], v[224:225] op_sel:[1,0,0]
	v_pk_fma_f32 v[226:227], v[56:57], v[234:235], v[226:227] op_sel:[1,0,0]
	v_cvt_pk_f32_fp8_e32 v[236:237], v107
	v_cvt_pk_f32_fp8_sdwa v[238:239], v107 src0_sel:WORD_1
	v_pk_fma_f32 v[228:229], v[56:57], v[236:237], v[228:229] op_sel:[1,0,0]
	v_pk_fma_f32 v[230:231], v[56:57], v[238:239], v[230:231] op_sel:[1,0,0]
	s_waitcnt vmcnt(25)
; DI f2_t cvt8lo(unsigned w) { return __builtin_amdgcn_cvt_pk_f32_fp8(w, false); }
; DI f2_t cvt8hi(unsigned w) { return __builtin_amdgcn_cvt_pk_f32_fp8(w, true); }
; DI void phase11(const Params& p, char* smem, int rep) {
;     ...
; #pragma unroll
;         for (int k = 0; k < 16; ++k) {
;           const f2_t a2 = {aa[k], aa[k]};
; #pragma unroll
;           for (int d = 0; d < 4; ++d) { const unsigned ww = rows[k][d]; o[2 * d] += a2 * cvt8lo(ww); o[2 * d + 1] += a2 * cvt8hi(ww); }
;         }
	v_cvt_pk_f32_fp8_e32 v[232:233], v108
	v_cvt_pk_f32_fp8_sdwa v[234:235], v108 src0_sel:WORD_1
	v_pk_fma_f32 v[216:217], v[58:59], v[232:233], v[216:217] op_sel_hi:[0,1,1]
	v_pk_fma_f32 v[218:219], v[58:59], v[234:235], v[218:219] op_sel_hi:[0,1,1]
	v_cvt_pk_f32_fp8_e32 v[236:237], v109
	v_cvt_pk_f32_fp8_sdwa v[238:239], v109 src0_sel:WORD_1
	v_pk_fma_f32 v[220:221], v[58:59], v[236:237], v[220:221] op_sel_hi:[0,1,1]
	v_pk_fma_f32 v[222:223], v[58:59], v[238:239], v[222:223] op_sel_hi:[0,1,1]
	v_cvt_pk_f32_fp8_e32 v[232:233], v110
	v_cvt_pk_f32_fp8_sdwa v[234:235], v110 src0_sel:WORD_1
	v_pk_fma_f32 v[224:225], v[58:59], v[232:233], v[224:225] op_sel_hi:[0,1,1]
	v_pk_fma_f32 v[226:227], v[58:59], v[234:235], v[226:227] op_sel_hi:[0,1,1]
	v_cvt_pk_f32_fp8_e32 v[236:237], v111
	v_cvt_pk_f32_fp8_sdwa v[238:239], v111 src0_sel:WORD_1
	v_pk_fma_f32 v[228:229], v[58:59], v[236:237], v[228:229] op_sel_hi:[0,1,1]
	v_pk_fma_f32 v[230:231], v[58:59], v[238:239], v[230:231] op_sel_hi:[0,1,1]
	s_waitcnt vmcnt(24)
	v_cvt_pk_f32_fp8_e32 v[232:233], v112
	v_cvt_pk_f32_fp8_sdwa v[234:235], v112 src0_sel:WORD_1
	v_pk_fma_f32 v[216:217], v[58:59], v[232:233], v[216:217] op_sel:[1,0,0]
	v_pk_fma_f32 v[218:219], v[58:59], v[234:235], v[218:219] op_sel:[1,0,0]
	v_cvt_pk_f32_fp8_e32 v[236:237], v113
	v_cvt_pk_f32_fp8_sdwa v[238:239], v113 src0_sel:WORD_1
	v_pk_fma_f32 v[220:221], v[58:59], v[236:237], v[220:221] op_sel:[1,0,0]
	v_pk_fma_f32 v[222:223], v[58:59], v[238:239], v[222:223] op_sel:[1,0,0]
	v_cvt_pk_f32_fp8_e32 v[232:233], v114
	v_cvt_pk_f32_fp8_sdwa v[234:235], v114 src0_sel:WORD_1
	v_pk_fma_f32 v[224:225], v[58:59], v[232:233], v[224:225] op_sel:[1,0,0]
	v_pk_fma_f32 v[226:227], v[58:59], v[234:235], v[226:227] op_sel:[1,0,0]
	v_cvt_pk_f32_fp8_e32 v[236:237], v115
	v_cvt_pk_f32_fp8_sdwa v[238:239], v115 src0_sel:WORD_1
	v_pk_fma_f32 v[228:229], v[58:59], v[236:237], v[228:229] op_sel:[1,0,0]
	v_pk_fma_f32 v[230:231], v[58:59], v[238:239], v[230:231] op_sel:[1,0,0]
	s_waitcnt vmcnt(23)
	v_cvt_pk_f32_fp8_e32 v[232:233], v116
	v_cvt_pk_f32_fp8_sdwa v[234:235], v116 src0_sel:WORD_1
	v_pk_fma_f32 v[216:217], v[60:61], v[232:233], v[216:217] op_sel_hi:[0,1,1]
	v_pk_fma_f32 v[218:219], v[60:61], v[234:235], v[218:219] op_sel_hi:[0,1,1]
	v_cvt_pk_f32_fp8_e32 v[236:237], v117
	v_cvt_pk_f32_fp8_sdwa v[238:239], v117 src0_sel:WORD_1
	v_pk_fma_f32 v[220:221], v[60:61], v[236:237], v[220:221] op_sel_hi:[0,1,1]
	v_pk_fma_f32 v[222:223], v[60:61], v[238:239], v[222:223] op_sel_hi:[0,1,1]
	v_cvt_pk_f32_fp8_e32 v[232:233], v118
	v_cvt_pk_f32_fp8_sdwa v[234:235], v118 src0_sel:WORD_1
	v_pk_fma_f32 v[224:225], v[60:61], v[232:233], v[224:225] op_sel_hi:[0,1,1]
	v_pk_fma_f32 v[226:227], v[60:61], v[234:235], v[226:227] op_sel_hi:[0,1,1]
	v_cvt_pk_f32_fp8_e32 v[236:237], v119
	v_cvt_pk_f32_fp8_sdwa v[238:239], v119 src0_sel:WORD_1
	v_pk_fma_f32 v[228:229], v[60:61], v[236:237], v[228:229] op_sel_hi:[0,1,1]
	v_pk_fma_f32 v[230:231], v[60:61], v[238:239], v[230:231] op_sel_hi:[0,1,1]
	s_waitcnt vmcnt(22)
	v_cvt_pk_f32_fp8_e32 v[232:233], v120
	v_cvt_pk_f32_fp8_sdwa v[234:235], v120 src0_sel:WORD_1
	v_pk_fma_f32 v[216:217], v[60:61], v[232:233], v[216:217] op_sel:[1,0,0]
	v_pk_fma_f32 v[218:219], v[60:61], v[234:235], v[218:219] op_sel:[1,0,0]
	v_cvt_pk_f32_fp8_e32 v[236:237], v121
	v_cvt_pk_f32_fp8_sdwa v[238:239], v121 src0_sel:WORD_1
	v_pk_fma_f32 v[220:221], v[60:61], v[236:237], v[220:221] op_sel:[1,0,0]
	v_pk_fma_f32 v[222:223], v[60:61], v[238:239], v[222:223] op_sel:[1,0,0]
	v_cvt_pk_f32_fp8_e32 v[232:233], v122
	v_cvt_pk_f32_fp8_sdwa v[234:235], v122 src0_sel:WORD_1
	v_pk_fma_f32 v[224:225], v[60:61], v[232:233], v[224:225] op_sel:[1,0,0]
	v_pk_fma_f32 v[226:227], v[60:61], v[234:235], v[226:227] op_sel:[1,0,0]
	v_cvt_pk_f32_fp8_e32 v[236:237], v123
	v_cvt_pk_f32_fp8_sdwa v[238:239], v123 src0_sel:WORD_1
	v_pk_fma_f32 v[228:229], v[60:61], v[236:237], v[228:229] op_sel:[1,0,0]
	v_pk_fma_f32 v[230:231], v[60:61], v[238:239], v[230:231] op_sel:[1,0,0]
	s_waitcnt vmcnt(21)
	v_cvt_pk_f32_fp8_e32 v[232:233], v124
	v_cvt_pk_f32_fp8_sdwa v[234:235], v124 src0_sel:WORD_1
	v_pk_fma_f32 v[216:217], v[62:63], v[232:233], v[216:217] op_sel_hi:[0,1,1]
	v_pk_fma_f32 v[218:219], v[62:63], v[234:235], v[218:219] op_sel_hi:[0,1,1]
	v_cvt_pk_f32_fp8_e32 v[236:237], v125
	v_cvt_pk_f32_fp8_sdwa v[238:239], v125 src0_sel:WORD_1
	v_pk_fma_f32 v[220:221], v[62:63], v[236:237], v[220:221] op_sel_hi:[0,1,1]
	v_pk_fma_f32 v[222:223], v[62:63], v[238:239], v[222:223] op_sel_hi:[0,1,1]
	v_cvt_pk_f32_fp8_e32 v[232:233], v126
	v_cvt_pk_f32_fp8_sdwa v[234:235], v126 src0_sel:WORD_1
	v_pk_fma_f32 v[224:225], v[62:63], v[232:233], v[224:225] op_sel_hi:[0,1,1]
	v_pk_fma_f32 v[226:227], v[62:63], v[234:235], v[226:227] op_sel_hi:[0,1,1]
	v_cvt_pk_f32_fp8_e32 v[236:237], v127
	v_cvt_pk_f32_fp8_sdwa v[238:239], v127 src0_sel:WORD_1
	v_pk_fma_f32 v[228:229], v[62:63], v[236:237], v[228:229] op_sel_hi:[0,1,1]
	v_pk_fma_f32 v[230:231], v[62:63], v[238:239], v[230:231] op_sel_hi:[0,1,1]
	s_waitcnt vmcnt(20)
	v_cvt_pk_f32_fp8_e32 v[232:233], v128
	v_cvt_pk_f32_fp8_sdwa v[234:235], v128 src0_sel:WORD_1
	v_pk_fma_f32 v[216:217], v[62:63], v[232:233], v[216:217] op_sel:[1,0,0]
	v_pk_fma_f32 v[218:219], v[62:63], v[234:235], v[218:219] op_sel:[1,0,0]
	v_cvt_pk_f32_fp8_e32 v[236:237], v129
	v_cvt_pk_f32_fp8_sdwa v[238:239], v129 src0_sel:WORD_1
	v_pk_fma_f32 v[220:221], v[62:63], v[236:237], v[220:221] op_sel:[1,0,0]
	v_pk_fma_f32 v[222:223], v[62:63], v[238:239], v[222:223] op_sel:[1,0,0]
	v_cvt_pk_f32_fp8_e32 v[232:233], v130
	v_cvt_pk_f32_fp8_sdwa v[234:235], v130 src0_sel:WORD_1
	v_pk_fma_f32 v[224:225], v[62:63], v[232:233], v[224:225] op_sel:[1,0,0]
	v_pk_fma_f32 v[226:227], v[62:63], v[234:235], v[226:227] op_sel:[1,0,0]
	v_cvt_pk_f32_fp8_e32 v[236:237], v131
	v_cvt_pk_f32_fp8_sdwa v[238:239], v131 src0_sel:WORD_1
	v_pk_fma_f32 v[228:229], v[62:63], v[236:237], v[228:229] op_sel:[1,0,0]
	v_pk_fma_f32 v[230:231], v[62:63], v[238:239], v[230:231] op_sel:[1,0,0]
	s_waitcnt vmcnt(19)
; DI f2_t cvt8lo(unsigned w) { return __builtin_amdgcn_cvt_pk_f32_fp8(w, false); }
; DI f2_t cvt8hi(unsigned w) { return __builtin_amdgcn_cvt_pk_f32_fp8(w, true); }
; DI void wave_lds_sync() { asm volatile("s_waitcnt lgkmcnt(0)" ::: "memory"); __builtin_amdgcn_wave_barrier(); }
; DI void phase11(const Params& p, char* smem, int rep) {
;     ...
;       wave_lds_sync();
;       lw[(lane & 3) * 32 + (lane >> 2)] = i0; lw[(lane & 3) * 32 + 16 + (lane >> 2)] = i1;
;       lf[(lane & 3) * 32 + (lane >> 2)] = a0; lf[(lane & 3) * 32 + 16 + (lane >> 2)] = a1;
;       wave_lds_sync();
;     ...
; #pragma unroll
;         for (int k = 0; k < 16; ++k) {
;           const f2_t a2 = {aa[k], aa[k]};
; #pragma unroll
;           for (int d = 0; d < 4; ++d) { const unsigned ww = rows[k][d]; o[2 * d] += a2 * cvt8lo(ww); o[2 * d + 1] += a2 * cvt8hi(ww); }
;         }
	v_cvt_pk_f32_fp8_e32 v[232:233], v132
	v_cvt_pk_f32_fp8_sdwa v[234:235], v132 src0_sel:WORD_1
	v_pk_fma_f32 v[216:217], v[64:65], v[232:233], v[216:217] op_sel_hi:[0,1,1]
	v_pk_fma_f32 v[218:219], v[64:65], v[234:235], v[218:219] op_sel_hi:[0,1,1]
	v_cvt_pk_f32_fp8_e32 v[236:237], v133
	v_cvt_pk_f32_fp8_sdwa v[238:239], v133 src0_sel:WORD_1
	v_pk_fma_f32 v[220:221], v[64:65], v[236:237], v[220:221] op_sel_hi:[0,1,1]
	v_pk_fma_f32 v[222:223], v[64:65], v[238:239], v[222:223] op_sel_hi:[0,1,1]
	v_cvt_pk_f32_fp8_e32 v[232:233], v134
	v_cvt_pk_f32_fp8_sdwa v[234:235], v134 src0_sel:WORD_1
	v_pk_fma_f32 v[224:225], v[64:65], v[232:233], v[224:225] op_sel_hi:[0,1,1]
	v_pk_fma_f32 v[226:227], v[64:65], v[234:235], v[226:227] op_sel_hi:[0,1,1]
	v_cvt_pk_f32_fp8_e32 v[236:237], v135
	v_cvt_pk_f32_fp8_sdwa v[238:239], v135 src0_sel:WORD_1
	v_pk_fma_f32 v[228:229], v[64:65], v[236:237], v[228:229] op_sel_hi:[0,1,1]
	v_pk_fma_f32 v[230:231], v[64:65], v[238:239], v[230:231] op_sel_hi:[0,1,1]
	s_waitcnt vmcnt(18)
	v_cvt_pk_f32_fp8_e32 v[232:233], v136
	v_cvt_pk_f32_fp8_sdwa v[234:235], v136 src0_sel:WORD_1
	v_pk_fma_f32 v[216:217], v[64:65], v[232:233], v[216:217] op_sel:[1,0,0]
	v_pk_fma_f32 v[218:219], v[64:65], v[234:235], v[218:219] op_sel:[1,0,0]
	v_cvt_pk_f32_fp8_e32 v[236:237], v137
	v_cvt_pk_f32_fp8_sdwa v[238:239], v137 src0_sel:WORD_1
	v_pk_fma_f32 v[220:221], v[64:65], v[236:237], v[220:221] op_sel:[1,0,0]
	v_pk_fma_f32 v[222:223], v[64:65], v[238:239], v[222:223] op_sel:[1,0,0]
	v_cvt_pk_f32_fp8_e32 v[232:233], v138
	v_cvt_pk_f32_fp8_sdwa v[234:235], v138 src0_sel:WORD_1
	v_pk_fma_f32 v[224:225], v[64:65], v[232:233], v[224:225] op_sel:[1,0,0]
	v_pk_fma_f32 v[226:227], v[64:65], v[234:235], v[226:227] op_sel:[1,0,0]
	v_cvt_pk_f32_fp8_e32 v[236:237], v139
	v_cvt_pk_f32_fp8_sdwa v[238:239], v139 src0_sel:WORD_1
	v_pk_fma_f32 v[228:229], v[64:65], v[236:237], v[228:229] op_sel:[1,0,0]
	v_pk_fma_f32 v[230:231], v[64:65], v[238:239], v[230:231] op_sel:[1,0,0]
	s_waitcnt vmcnt(17)
	v_cvt_pk_f32_fp8_e32 v[232:233], v140
	v_cvt_pk_f32_fp8_sdwa v[234:235], v140 src0_sel:WORD_1
	v_pk_fma_f32 v[216:217], v[66:67], v[232:233], v[216:217] op_sel_hi:[0,1,1]
	v_pk_fma_f32 v[218:219], v[66:67], v[234:235], v[218:219] op_sel_hi:[0,1,1]
	v_cvt_pk_f32_fp8_e32 v[236:237], v141
	v_cvt_pk_f32_fp8_sdwa v[238:239], v141 src0_sel:WORD_1
	v_pk_fma_f32 v[220:221], v[66:67], v[236:237], v[220:221] op_sel_hi:[0,1,1]
	v_pk_fma_f32 v[222:223], v[66:67], v[238:239], v[222:223] op_sel_hi:[0,1,1]
	v_cvt_pk_f32_fp8_e32 v[232:233], v142
	v_cvt_pk_f32_fp8_sdwa v[234:235], v142 src0_sel:WORD_1
	v_pk_fma_f32 v[224:225], v[66:67], v[232:233], v[224:225] op_sel_hi:[0,1,1]
	v_pk_fma_f32 v[226:227], v[66:67], v[234:235], v[226:227] op_sel_hi:[0,1,1]
	v_cvt_pk_f32_fp8_e32 v[236:237], v143
	v_cvt_pk_f32_fp8_sdwa v[238:239], v143 src0_sel:WORD_1
	v_pk_fma_f32 v[228:229], v[66:67], v[236:237], v[228:229] op_sel_hi:[0,1,1]
	v_pk_fma_f32 v[230:231], v[66:67], v[238:239], v[230:231] op_sel_hi:[0,1,1]
	s_waitcnt vmcnt(16)
	v_cvt_pk_f32_fp8_e32 v[232:233], v144
	v_cvt_pk_f32_fp8_sdwa v[234:235], v144 src0_sel:WORD_1
	v_pk_fma_f32 v[216:217], v[66:67], v[232:233], v[216:217] op_sel:[1,0,0]
	v_pk_fma_f32 v[218:219], v[66:67], v[234:235], v[218:219] op_sel:[1,0,0]
	v_cvt_pk_f32_fp8_e32 v[236:237], v145
	v_cvt_pk_f32_fp8_sdwa v[238:239], v145 src0_sel:WORD_1
	v_pk_fma_f32 v[220:221], v[66:67], v[236:237], v[220:221] op_sel:[1,0,0]
	v_pk_fma_f32 v[222:223], v[66:67], v[238:239], v[222:223] op_sel:[1,0,0]
	v_cvt_pk_f32_fp8_e32 v[232:233], v146
	v_cvt_pk_f32_fp8_sdwa v[234:235], v146 src0_sel:WORD_1
	v_pk_fma_f32 v[224:225], v[66:67], v[232:233], v[224:225] op_sel:[1,0,0]
	v_pk_fma_f32 v[226:227], v[66:67], v[234:235], v[226:227] op_sel:[1,0,0]
	v_cvt_pk_f32_fp8_e32 v[236:237], v147
	v_cvt_pk_f32_fp8_sdwa v[238:239], v147 src0_sel:WORD_1
	v_pk_fma_f32 v[228:229], v[66:67], v[236:237], v[228:229] op_sel:[1,0,0]
	v_pk_fma_f32 v[230:231], v[66:67], v[238:239], v[230:231] op_sel:[1,0,0]
	ds_write2_b32 v5, v10, v11 offset0:4 offset1:20
	ds_write2_b32 v5, v12, v13 offset0:132 offset1:148
	s_waitcnt lgkmcnt(0)
	ds_read_b128 v[20:23], v6 offset:16
	ds_read_b128 v[24:27], v6 offset:32
	ds_read_b128 v[28:31], v6 offset:48
	ds_read_b128 v[32:35], v6 offset:64
	ds_read_b128 v[36:39], v6 offset:80
	ds_read_b128 v[40:43], v6 offset:96
	ds_read_b128 v[44:47], v6 offset:112
	ds_read_b128 v[48:51], v6 offset:128
	s_waitcnt vmcnt(15)
	v_cvt_pk_f32_fp8_e32 v[232:233], v148
	v_cvt_pk_f32_fp8_sdwa v[234:235], v148 src0_sel:WORD_1
	v_pk_fma_f32 v[216:217], v[68:69], v[232:233], v[216:217] op_sel_hi:[0,1,1]
	v_pk_fma_f32 v[218:219], v[68:69], v[234:235], v[218:219] op_sel_hi:[0,1,1]
	v_cvt_pk_f32_fp8_e32 v[236:237], v149
	v_cvt_pk_f32_fp8_sdwa v[238:239], v149 src0_sel:WORD_1
	v_pk_fma_f32 v[220:221], v[68:69], v[236:237], v[220:221] op_sel_hi:[0,1,1]
	v_pk_fma_f32 v[222:223], v[68:69], v[238:239], v[222:223] op_sel_hi:[0,1,1]
	v_cvt_pk_f32_fp8_e32 v[232:233], v150
	v_cvt_pk_f32_fp8_sdwa v[234:235], v150 src0_sel:WORD_1
	v_pk_fma_f32 v[224:225], v[68:69], v[232:233], v[224:225] op_sel_hi:[0,1,1]
	v_pk_fma_f32 v[226:227], v[68:69], v[234:235], v[226:227] op_sel_hi:[0,1,1]
	v_cvt_pk_f32_fp8_e32 v[236:237], v151
	v_cvt_pk_f32_fp8_sdwa v[238:239], v151 src0_sel:WORD_1
	v_pk_fma_f32 v[228:229], v[68:69], v[236:237], v[228:229] op_sel_hi:[0,1,1]
	v_pk_fma_f32 v[230:231], v[68:69], v[238:239], v[230:231] op_sel_hi:[0,1,1]
	s_waitcnt vmcnt(14)
; DI f2_t cvt8lo(unsigned w) { return __builtin_amdgcn_cvt_pk_f32_fp8(w, false); }
; DI f2_t cvt8hi(unsigned w) { return __builtin_amdgcn_cvt_pk_f32_fp8(w, true); }
; DI void phase11(const Params& p, char* smem, int rep) {
;     ...
; #pragma unroll
;         for (int k = 0; k < 16; ++k) {
;           const f2_t a2 = {aa[k], aa[k]};
; #pragma unroll
;           for (int d = 0; d < 4; ++d) { const unsigned ww = rows[k][d]; o[2 * d] += a2 * cvt8lo(ww); o[2 * d + 1] += a2 * cvt8hi(ww); }
;         }
	v_cvt_pk_f32_fp8_e32 v[232:233], v152
	v_cvt_pk_f32_fp8_sdwa v[234:235], v152 src0_sel:WORD_1
	v_pk_fma_f32 v[216:217], v[68:69], v[232:233], v[216:217] op_sel:[1,0,0]
	v_pk_fma_f32 v[218:219], v[68:69], v[234:235], v[218:219] op_sel:[1,0,0]
	v_cvt_pk_f32_fp8_e32 v[236:237], v153
	v_cvt_pk_f32_fp8_sdwa v[238:239], v153 src0_sel:WORD_1
	v_pk_fma_f32 v[220:221], v[68:69], v[236:237], v[220:221] op_sel:[1,0,0]
	v_pk_fma_f32 v[222:223], v[68:69], v[238:239], v[222:223] op_sel:[1,0,0]
	v_cvt_pk_f32_fp8_e32 v[232:233], v154
	v_cvt_pk_f32_fp8_sdwa v[234:235], v154 src0_sel:WORD_1
	v_pk_fma_f32 v[224:225], v[68:69], v[232:233], v[224:225] op_sel:[1,0,0]
	v_pk_fma_f32 v[226:227], v[68:69], v[234:235], v[226:227] op_sel:[1,0,0]
	v_cvt_pk_f32_fp8_e32 v[236:237], v155
	v_cvt_pk_f32_fp8_sdwa v[238:239], v155 src0_sel:WORD_1
	v_pk_fma_f32 v[228:229], v[68:69], v[236:237], v[228:229] op_sel:[1,0,0]
	v_pk_fma_f32 v[230:231], v[68:69], v[238:239], v[230:231] op_sel:[1,0,0]
	s_waitcnt vmcnt(13)
	v_cvt_pk_f32_fp8_e32 v[232:233], v156
	v_cvt_pk_f32_fp8_sdwa v[234:235], v156 src0_sel:WORD_1
	v_pk_fma_f32 v[216:217], v[70:71], v[232:233], v[216:217] op_sel_hi:[0,1,1]
	v_pk_fma_f32 v[218:219], v[70:71], v[234:235], v[218:219] op_sel_hi:[0,1,1]
	v_cvt_pk_f32_fp8_e32 v[236:237], v157
	v_cvt_pk_f32_fp8_sdwa v[238:239], v157 src0_sel:WORD_1
	v_pk_fma_f32 v[220:221], v[70:71], v[236:237], v[220:221] op_sel_hi:[0,1,1]
	v_pk_fma_f32 v[222:223], v[70:71], v[238:239], v[222:223] op_sel_hi:[0,1,1]
	v_cvt_pk_f32_fp8_e32 v[232:233], v158
	v_cvt_pk_f32_fp8_sdwa v[234:235], v158 src0_sel:WORD_1
	v_pk_fma_f32 v[224:225], v[70:71], v[232:233], v[224:225] op_sel_hi:[0,1,1]
	v_pk_fma_f32 v[226:227], v[70:71], v[234:235], v[226:227] op_sel_hi:[0,1,1]
	v_cvt_pk_f32_fp8_e32 v[236:237], v159
	v_cvt_pk_f32_fp8_sdwa v[238:239], v159 src0_sel:WORD_1
	v_pk_fma_f32 v[228:229], v[70:71], v[236:237], v[228:229] op_sel_hi:[0,1,1]
	v_pk_fma_f32 v[230:231], v[70:71], v[238:239], v[230:231] op_sel_hi:[0,1,1]
	s_waitcnt vmcnt(12)
	v_cvt_pk_f32_fp8_e32 v[232:233], v160
	v_cvt_pk_f32_fp8_sdwa v[234:235], v160 src0_sel:WORD_1
	v_pk_fma_f32 v[216:217], v[70:71], v[232:233], v[216:217] op_sel:[1,0,0]
	v_pk_fma_f32 v[218:219], v[70:71], v[234:235], v[218:219] op_sel:[1,0,0]
	v_cvt_pk_f32_fp8_e32 v[236:237], v161
	v_cvt_pk_f32_fp8_sdwa v[238:239], v161 src0_sel:WORD_1
	v_pk_fma_f32 v[220:221], v[70:71], v[236:237], v[220:221] op_sel:[1,0,0]
	v_pk_fma_f32 v[222:223], v[70:71], v[238:239], v[222:223] op_sel:[1,0,0]
	v_cvt_pk_f32_fp8_e32 v[232:233], v162
	v_cvt_pk_f32_fp8_sdwa v[234:235], v162 src0_sel:WORD_1
	v_pk_fma_f32 v[224:225], v[70:71], v[232:233], v[224:225] op_sel:[1,0,0]
	v_pk_fma_f32 v[226:227], v[70:71], v[234:235], v[226:227] op_sel:[1,0,0]
	v_cvt_pk_f32_fp8_e32 v[236:237], v163
	v_cvt_pk_f32_fp8_sdwa v[238:239], v163 src0_sel:WORD_1
	v_pk_fma_f32 v[228:229], v[70:71], v[236:237], v[228:229] op_sel:[1,0,0]
	v_pk_fma_f32 v[230:231], v[70:71], v[238:239], v[230:231] op_sel:[1,0,0]
	s_waitcnt vmcnt(11)
	v_cvt_pk_f32_fp8_e32 v[232:233], v164
	v_cvt_pk_f32_fp8_sdwa v[234:235], v164 src0_sel:WORD_1
	v_pk_fma_f32 v[216:217], v[72:73], v[232:233], v[216:217] op_sel_hi:[0,1,1]
	v_pk_fma_f32 v[218:219], v[72:73], v[234:235], v[218:219] op_sel_hi:[0,1,1]
	v_cvt_pk_f32_fp8_e32 v[236:237], v165
	v_cvt_pk_f32_fp8_sdwa v[238:239], v165 src0_sel:WORD_1
	v_pk_fma_f32 v[220:221], v[72:73], v[236:237], v[220:221] op_sel_hi:[0,1,1]
	v_pk_fma_f32 v[222:223], v[72:73], v[238:239], v[222:223] op_sel_hi:[0,1,1]
	v_cvt_pk_f32_fp8_e32 v[232:233], v166
	v_cvt_pk_f32_fp8_sdwa v[234:235], v166 src0_sel:WORD_1
	v_pk_fma_f32 v[224:225], v[72:73], v[232:233], v[224:225] op_sel_hi:[0,1,1]
	v_pk_fma_f32 v[226:227], v[72:73], v[234:235], v[226:227] op_sel_hi:[0,1,1]
	v_cvt_pk_f32_fp8_e32 v[236:237], v167
	v_cvt_pk_f32_fp8_sdwa v[238:239], v167 src0_sel:WORD_1
	v_pk_fma_f32 v[228:229], v[72:73], v[236:237], v[228:229] op_sel_hi:[0,1,1]
	v_pk_fma_f32 v[230:231], v[72:73], v[238:239], v[230:231] op_sel_hi:[0,1,1]
	s_waitcnt vmcnt(10)
	v_cvt_pk_f32_fp8_e32 v[232:233], v168
	v_cvt_pk_f32_fp8_sdwa v[234:235], v168 src0_sel:WORD_1
	v_pk_fma_f32 v[216:217], v[72:73], v[232:233], v[216:217] op_sel:[1,0,0]
	v_pk_fma_f32 v[218:219], v[72:73], v[234:235], v[218:219] op_sel:[1,0,0]
	v_cvt_pk_f32_fp8_e32 v[236:237], v169
	v_cvt_pk_f32_fp8_sdwa v[238:239], v169 src0_sel:WORD_1
	v_pk_fma_f32 v[220:221], v[72:73], v[236:237], v[220:221] op_sel:[1,0,0]
	v_pk_fma_f32 v[222:223], v[72:73], v[238:239], v[222:223] op_sel:[1,0,0]
	v_cvt_pk_f32_fp8_e32 v[232:233], v170
	v_cvt_pk_f32_fp8_sdwa v[234:235], v170 src0_sel:WORD_1
	v_pk_fma_f32 v[224:225], v[72:73], v[232:233], v[224:225] op_sel:[1,0,0]
	v_pk_fma_f32 v[226:227], v[72:73], v[234:235], v[226:227] op_sel:[1,0,0]
	v_cvt_pk_f32_fp8_e32 v[236:237], v171
	v_cvt_pk_f32_fp8_sdwa v[238:239], v171 src0_sel:WORD_1
	v_pk_fma_f32 v[228:229], v[72:73], v[236:237], v[228:229] op_sel:[1,0,0]
	v_pk_fma_f32 v[230:231], v[72:73], v[238:239], v[230:231] op_sel:[1,0,0]
	s_waitcnt vmcnt(9)
	v_cvt_pk_f32_fp8_e32 v[232:233], v172
	v_cvt_pk_f32_fp8_sdwa v[234:235], v172 src0_sel:WORD_1
	v_pk_fma_f32 v[216:217], v[74:75], v[232:233], v[216:217] op_sel_hi:[0,1,1]
	v_pk_fma_f32 v[218:219], v[74:75], v[234:235], v[218:219] op_sel_hi:[0,1,1]
	v_cvt_pk_f32_fp8_e32 v[236:237], v173
	v_cvt_pk_f32_fp8_sdwa v[238:239], v173 src0_sel:WORD_1
	v_pk_fma_f32 v[220:221], v[74:75], v[236:237], v[220:221] op_sel_hi:[0,1,1]
	v_pk_fma_f32 v[222:223], v[74:75], v[238:239], v[222:223] op_sel_hi:[0,1,1]
	v_cvt_pk_f32_fp8_e32 v[232:233], v174
	v_cvt_pk_f32_fp8_sdwa v[234:235], v174 src0_sel:WORD_1
	v_pk_fma_f32 v[224:225], v[74:75], v[232:233], v[224:225] op_sel_hi:[0,1,1]
	v_pk_fma_f32 v[226:227], v[74:75], v[234:235], v[226:227] op_sel_hi:[0,1,1]
	v_cvt_pk_f32_fp8_e32 v[236:237], v175
	v_cvt_pk_f32_fp8_sdwa v[238:239], v175 src0_sel:WORD_1
	v_pk_fma_f32 v[228:229], v[74:75], v[236:237], v[228:229] op_sel_hi:[0,1,1]
	v_pk_fma_f32 v[230:231], v[74:75], v[238:239], v[230:231] op_sel_hi:[0,1,1]
	s_waitcnt vmcnt(8)
; DI f2_t cvt8lo(unsigned w) { return __builtin_amdgcn_cvt_pk_f32_fp8(w, false); }
; DI f2_t cvt8hi(unsigned w) { return __builtin_amdgcn_cvt_pk_f32_fp8(w, true); }
; DI void phase11(const Params& p, char* smem, int rep) {
;     ...
; #pragma unroll
;         for (int k = 0; k < 16; ++k) {
;           const f2_t a2 = {aa[k], aa[k]};
; #pragma unroll
;           for (int d = 0; d < 4; ++d) { const unsigned ww = rows[k][d]; o[2 * d] += a2 * cvt8lo(ww); o[2 * d + 1] += a2 * cvt8hi(ww); }
;         }
	v_cvt_pk_f32_fp8_e32 v[232:233], v176
	v_cvt_pk_f32_fp8_sdwa v[234:235], v176 src0_sel:WORD_1
	v_pk_fma_f32 v[216:217], v[74:75], v[232:233], v[216:217] op_sel:[1,0,0]
	v_pk_fma_f32 v[218:219], v[74:75], v[234:235], v[218:219] op_sel:[1,0,0]
	v_cvt_pk_f32_fp8_e32 v[236:237], v177
	v_cvt_pk_f32_fp8_sdwa v[238:239], v177 src0_sel:WORD_1
	v_pk_fma_f32 v[220:221], v[74:75], v[236:237], v[220:221] op_sel:[1,0,0]
	v_pk_fma_f32 v[222:223], v[74:75], v[238:239], v[222:223] op_sel:[1,0,0]
	v_cvt_pk_f32_fp8_e32 v[232:233], v178
	v_cvt_pk_f32_fp8_sdwa v[234:235], v178 src0_sel:WORD_1
	v_pk_fma_f32 v[224:225], v[74:75], v[232:233], v[224:225] op_sel:[1,0,0]
	v_pk_fma_f32 v[226:227], v[74:75], v[234:235], v[226:227] op_sel:[1,0,0]
	v_cvt_pk_f32_fp8_e32 v[236:237], v179
	v_cvt_pk_f32_fp8_sdwa v[238:239], v179 src0_sel:WORD_1
	v_pk_fma_f32 v[228:229], v[74:75], v[236:237], v[228:229] op_sel:[1,0,0]
	v_pk_fma_f32 v[230:231], v[74:75], v[238:239], v[230:231] op_sel:[1,0,0]
	s_waitcnt vmcnt(7)
	v_cvt_pk_f32_fp8_e32 v[232:233], v180
	v_cvt_pk_f32_fp8_sdwa v[234:235], v180 src0_sel:WORD_1
	v_pk_fma_f32 v[216:217], v[76:77], v[232:233], v[216:217] op_sel_hi:[0,1,1]
	v_pk_fma_f32 v[218:219], v[76:77], v[234:235], v[218:219] op_sel_hi:[0,1,1]
	v_cvt_pk_f32_fp8_e32 v[236:237], v181
	v_cvt_pk_f32_fp8_sdwa v[238:239], v181 src0_sel:WORD_1
	v_pk_fma_f32 v[220:221], v[76:77], v[236:237], v[220:221] op_sel_hi:[0,1,1]
	v_pk_fma_f32 v[222:223], v[76:77], v[238:239], v[222:223] op_sel_hi:[0,1,1]
	v_cvt_pk_f32_fp8_e32 v[232:233], v182
	v_cvt_pk_f32_fp8_sdwa v[234:235], v182 src0_sel:WORD_1
	v_pk_fma_f32 v[224:225], v[76:77], v[232:233], v[224:225] op_sel_hi:[0,1,1]
	v_pk_fma_f32 v[226:227], v[76:77], v[234:235], v[226:227] op_sel_hi:[0,1,1]
	v_cvt_pk_f32_fp8_e32 v[236:237], v183
	v_cvt_pk_f32_fp8_sdwa v[238:239], v183 src0_sel:WORD_1
	v_pk_fma_f32 v[228:229], v[76:77], v[236:237], v[228:229] op_sel_hi:[0,1,1]
	v_pk_fma_f32 v[230:231], v[76:77], v[238:239], v[230:231] op_sel_hi:[0,1,1]
	s_waitcnt vmcnt(6)
	v_cvt_pk_f32_fp8_e32 v[232:233], v184
	v_cvt_pk_f32_fp8_sdwa v[234:235], v184 src0_sel:WORD_1
	v_pk_fma_f32 v[216:217], v[76:77], v[232:233], v[216:217] op_sel:[1,0,0]
	v_pk_fma_f32 v[218:219], v[76:77], v[234:235], v[218:219] op_sel:[1,0,0]
	v_cvt_pk_f32_fp8_e32 v[236:237], v185
	v_cvt_pk_f32_fp8_sdwa v[238:239], v185 src0_sel:WORD_1
	v_pk_fma_f32 v[220:221], v[76:77], v[236:237], v[220:221] op_sel:[1,0,0]
	v_pk_fma_f32 v[222:223], v[76:77], v[238:239], v[222:223] op_sel:[1,0,0]
	v_cvt_pk_f32_fp8_e32 v[232:233], v186
	v_cvt_pk_f32_fp8_sdwa v[234:235], v186 src0_sel:WORD_1
	v_pk_fma_f32 v[224:225], v[76:77], v[232:233], v[224:225] op_sel:[1,0,0]
	v_pk_fma_f32 v[226:227], v[76:77], v[234:235], v[226:227] op_sel:[1,0,0]
	v_cvt_pk_f32_fp8_e32 v[236:237], v187
	v_cvt_pk_f32_fp8_sdwa v[238:239], v187 src0_sel:WORD_1
	v_pk_fma_f32 v[228:229], v[76:77], v[236:237], v[228:229] op_sel:[1,0,0]
	v_pk_fma_f32 v[230:231], v[76:77], v[238:239], v[230:231] op_sel:[1,0,0]
	s_waitcnt vmcnt(5)
	v_cvt_pk_f32_fp8_e32 v[232:233], v190
	v_cvt_pk_f32_fp8_sdwa v[234:235], v190 src0_sel:WORD_1
	v_pk_fma_f32 v[216:217], v[78:79], v[232:233], v[216:217] op_sel_hi:[0,1,1]
	v_pk_fma_f32 v[218:219], v[78:79], v[234:235], v[218:219] op_sel_hi:[0,1,1]
	v_cvt_pk_f32_fp8_e32 v[236:237], v191
	v_cvt_pk_f32_fp8_sdwa v[238:239], v191 src0_sel:WORD_1
	v_pk_fma_f32 v[220:221], v[78:79], v[236:237], v[220:221] op_sel_hi:[0,1,1]
	v_pk_fma_f32 v[222:223], v[78:79], v[238:239], v[222:223] op_sel_hi:[0,1,1]
	v_cvt_pk_f32_fp8_e32 v[232:233], v192
	v_cvt_pk_f32_fp8_sdwa v[234:235], v192 src0_sel:WORD_1
	v_pk_fma_f32 v[224:225], v[78:79], v[232:233], v[224:225] op_sel_hi:[0,1,1]
	v_pk_fma_f32 v[226:227], v[78:79], v[234:235], v[226:227] op_sel_hi:[0,1,1]
	v_cvt_pk_f32_fp8_e32 v[236:237], v193
	v_cvt_pk_f32_fp8_sdwa v[238:239], v193 src0_sel:WORD_1
	v_pk_fma_f32 v[228:229], v[78:79], v[236:237], v[228:229] op_sel_hi:[0,1,1]
	v_pk_fma_f32 v[230:231], v[78:79], v[238:239], v[230:231] op_sel_hi:[0,1,1]
	s_waitcnt vmcnt(4)
	v_cvt_pk_f32_fp8_e32 v[232:233], v194
	v_cvt_pk_f32_fp8_sdwa v[234:235], v194 src0_sel:WORD_1
	v_pk_fma_f32 v[216:217], v[78:79], v[232:233], v[216:217] op_sel:[1,0,0]
	v_pk_fma_f32 v[218:219], v[78:79], v[234:235], v[218:219] op_sel:[1,0,0]
	v_cvt_pk_f32_fp8_e32 v[236:237], v195
	v_cvt_pk_f32_fp8_sdwa v[238:239], v195 src0_sel:WORD_1
	v_pk_fma_f32 v[220:221], v[78:79], v[236:237], v[220:221] op_sel:[1,0,0]
	v_pk_fma_f32 v[222:223], v[78:79], v[238:239], v[222:223] op_sel:[1,0,0]
	v_cvt_pk_f32_fp8_e32 v[232:233], v196
	v_cvt_pk_f32_fp8_sdwa v[234:235], v196 src0_sel:WORD_1
	v_pk_fma_f32 v[224:225], v[78:79], v[232:233], v[224:225] op_sel:[1,0,0]
	v_pk_fma_f32 v[226:227], v[78:79], v[234:235], v[226:227] op_sel:[1,0,0]
	v_cvt_pk_f32_fp8_e32 v[236:237], v197
	v_cvt_pk_f32_fp8_sdwa v[238:239], v197 src0_sel:WORD_1
	v_pk_fma_f32 v[228:229], v[78:79], v[236:237], v[228:229] op_sel:[1,0,0]
	v_pk_fma_f32 v[230:231], v[78:79], v[238:239], v[230:231] op_sel:[1,0,0]
	s_waitcnt vmcnt(3)
; DI unsigned pk2(float a, float b) { f2_t v = {a, b}; bf2_t r = __builtin_convertvector(v, bf2_t); return __builtin_bit_cast(unsigned, r); }
; DI f2_t cvt8lo(unsigned w) { return __builtin_amdgcn_cvt_pk_f32_fp8(w, false); }
; DI f2_t cvt8hi(unsigned w) { return __builtin_amdgcn_cvt_pk_f32_fp8(w, true); }
; DI void phase11(const Params& p, char* smem, int rep) {
;     ...
; #pragma unroll
;         for (int k = 0; k < 16; ++k) {
;           const f2_t a2 = {aa[k], aa[k]};
; #pragma unroll
;           for (int d = 0; d < 4; ++d) { const unsigned ww = rows[k][d]; o[2 * d] += a2 * cvt8lo(ww); o[2 * d + 1] += a2 * cvt8hi(ww); }
;         }
;       }
;       float ov[16];
; #pragma unroll
;       for (int d = 0; d < 4; ++d) { ov[4 * d] = o[2 * d].x; ov[4 * d + 1] = o[2 * d].y; ov[4 * d + 2] = o[2 * d + 1].x; ov[4 * d + 3] = o[2 * d + 1].y; }
;       float q8[8], q4[4];
; #pragma unroll
;       for (int k = 0; k < 8; ++k) q8[k] = (b5 ? ov[8 + k] : ov[k]) + __shfl_xor(b5 ? ov[k] : ov[8 + k], 32);
; #pragma unroll
;       for (int k = 0; k < 4; ++k) q4[k] = (b4 ? q8[4 + k] : q8[k]) + __shfl_xor(b4 ? q8[k] : q8[4 + k], 16);
;       *(uint2*)(OUTP + (size_t)tok * D_ + s * 256 + l15 * 16 + 8 * b5 + 4 * b4) = make_uint2(pk2(q4[0], q4[1]), pk2(q4[2], q4[3]));
	v_cvt_pk_f32_fp8_e32 v[232:233], v198
	v_cvt_pk_f32_fp8_sdwa v[234:235], v198 src0_sel:WORD_1
	v_pk_fma_f32 v[216:217], v[80:81], v[232:233], v[216:217] op_sel_hi:[0,1,1]
	v_pk_fma_f32 v[218:219], v[80:81], v[234:235], v[218:219] op_sel_hi:[0,1,1]
	v_cvt_pk_f32_fp8_e32 v[236:237], v199
	v_cvt_pk_f32_fp8_sdwa v[238:239], v199 src0_sel:WORD_1
	v_pk_fma_f32 v[220:221], v[80:81], v[236:237], v[220:221] op_sel_hi:[0,1,1]
	v_pk_fma_f32 v[222:223], v[80:81], v[238:239], v[222:223] op_sel_hi:[0,1,1]
	v_cvt_pk_f32_fp8_e32 v[232:233], v200
	v_cvt_pk_f32_fp8_sdwa v[234:235], v200 src0_sel:WORD_1
	v_pk_fma_f32 v[224:225], v[80:81], v[232:233], v[224:225] op_sel_hi:[0,1,1]
	v_pk_fma_f32 v[226:227], v[80:81], v[234:235], v[226:227] op_sel_hi:[0,1,1]
	v_cvt_pk_f32_fp8_e32 v[236:237], v201
	v_cvt_pk_f32_fp8_sdwa v[238:239], v201 src0_sel:WORD_1
	v_pk_fma_f32 v[228:229], v[80:81], v[236:237], v[228:229] op_sel_hi:[0,1,1]
	v_pk_fma_f32 v[230:231], v[80:81], v[238:239], v[230:231] op_sel_hi:[0,1,1]
	s_waitcnt vmcnt(2)
	v_cvt_pk_f32_fp8_e32 v[232:233], v202
	v_cvt_pk_f32_fp8_sdwa v[234:235], v202 src0_sel:WORD_1
	v_pk_fma_f32 v[216:217], v[80:81], v[232:233], v[216:217] op_sel:[1,0,0]
	v_pk_fma_f32 v[218:219], v[80:81], v[234:235], v[218:219] op_sel:[1,0,0]
	v_cvt_pk_f32_fp8_e32 v[236:237], v203
	v_cvt_pk_f32_fp8_sdwa v[238:239], v203 src0_sel:WORD_1
	v_pk_fma_f32 v[220:221], v[80:81], v[236:237], v[220:221] op_sel:[1,0,0]
	v_pk_fma_f32 v[222:223], v[80:81], v[238:239], v[222:223] op_sel:[1,0,0]
	v_cvt_pk_f32_fp8_e32 v[232:233], v204
	v_cvt_pk_f32_fp8_sdwa v[234:235], v204 src0_sel:WORD_1
	v_pk_fma_f32 v[224:225], v[80:81], v[232:233], v[224:225] op_sel:[1,0,0]
	v_pk_fma_f32 v[226:227], v[80:81], v[234:235], v[226:227] op_sel:[1,0,0]
	v_cvt_pk_f32_fp8_e32 v[236:237], v205
	v_cvt_pk_f32_fp8_sdwa v[238:239], v205 src0_sel:WORD_1
	v_pk_fma_f32 v[228:229], v[80:81], v[236:237], v[228:229] op_sel:[1,0,0]
	v_pk_fma_f32 v[230:231], v[80:81], v[238:239], v[230:231] op_sel:[1,0,0]
	s_waitcnt vmcnt(1)
	v_cvt_pk_f32_fp8_e32 v[232:233], v206
	v_cvt_pk_f32_fp8_sdwa v[234:235], v206 src0_sel:WORD_1
	v_pk_fma_f32 v[216:217], v[82:83], v[232:233], v[216:217] op_sel_hi:[0,1,1]
	v_pk_fma_f32 v[218:219], v[82:83], v[234:235], v[218:219] op_sel_hi:[0,1,1]
	v_cvt_pk_f32_fp8_e32 v[236:237], v207
	v_cvt_pk_f32_fp8_sdwa v[238:239], v207 src0_sel:WORD_1
	v_pk_fma_f32 v[220:221], v[82:83], v[236:237], v[220:221] op_sel_hi:[0,1,1]
	v_pk_fma_f32 v[222:223], v[82:83], v[238:239], v[222:223] op_sel_hi:[0,1,1]
	v_cvt_pk_f32_fp8_e32 v[232:233], v208
	v_cvt_pk_f32_fp8_sdwa v[234:235], v208 src0_sel:WORD_1
	v_pk_fma_f32 v[224:225], v[82:83], v[232:233], v[224:225] op_sel_hi:[0,1,1]
	v_pk_fma_f32 v[226:227], v[82:83], v[234:235], v[226:227] op_sel_hi:[0,1,1]
	v_cvt_pk_f32_fp8_e32 v[236:237], v209
	v_cvt_pk_f32_fp8_sdwa v[238:239], v209 src0_sel:WORD_1
	v_pk_fma_f32 v[228:229], v[82:83], v[236:237], v[228:229] op_sel_hi:[0,1,1]
	v_pk_fma_f32 v[230:231], v[82:83], v[238:239], v[230:231] op_sel_hi:[0,1,1]
	s_waitcnt vmcnt(0)
	v_cvt_pk_f32_fp8_e32 v[232:233], v210
	v_cvt_pk_f32_fp8_sdwa v[234:235], v210 src0_sel:WORD_1
	v_pk_fma_f32 v[216:217], v[82:83], v[232:233], v[216:217] op_sel:[1,0,0]
	v_pk_fma_f32 v[218:219], v[82:83], v[234:235], v[218:219] op_sel:[1,0,0]
	v_cvt_pk_f32_fp8_e32 v[236:237], v211
	v_cvt_pk_f32_fp8_sdwa v[238:239], v211 src0_sel:WORD_1
	v_pk_fma_f32 v[220:221], v[82:83], v[236:237], v[220:221] op_sel:[1,0,0]
	v_pk_fma_f32 v[222:223], v[82:83], v[238:239], v[222:223] op_sel:[1,0,0]
	v_cvt_pk_f32_fp8_e32 v[232:233], v212
	v_cvt_pk_f32_fp8_sdwa v[234:235], v212 src0_sel:WORD_1
	v_pk_fma_f32 v[224:225], v[82:83], v[232:233], v[224:225] op_sel:[1,0,0]
	v_pk_fma_f32 v[226:227], v[82:83], v[234:235], v[226:227] op_sel:[1,0,0]
	v_cvt_pk_f32_fp8_e32 v[236:237], v213
	v_cvt_pk_f32_fp8_sdwa v[238:239], v213 src0_sel:WORD_1
	v_pk_fma_f32 v[228:229], v[82:83], v[236:237], v[228:229] op_sel:[1,0,0]
	v_pk_fma_f32 v[230:231], v[82:83], v[238:239], v[230:231] op_sel:[1,0,0]
	ds_read_b128 v[52:55], v6 offset:528
	ds_read_b128 v[56:59], v6 offset:544
	ds_read_b128 v[60:63], v6 offset:560
	ds_read_b128 v[64:67], v6 offset:576
	ds_read_b128 v[68:71], v6 offset:592
	ds_read_b128 v[72:75], v6 offset:608
	ds_read_b128 v[76:79], v6 offset:624
	ds_read_b128 v[80:83], v6 offset:640
	v_add_u32_e32 v214, s46, v4
	s_nop 0
	v_permlane32_swap_b32_e32 v216, v224
	v_permlane32_swap_b32_e32 v217, v225
	v_permlane32_swap_b32_e32 v218, v226
	v_permlane32_swap_b32_e32 v219, v227
	v_permlane32_swap_b32_e32 v220, v228
	v_permlane32_swap_b32_e32 v221, v229
	v_permlane32_swap_b32_e32 v222, v230
	v_permlane32_swap_b32_e32 v223, v231
	v_add_f32_e32 v216, v216, v224
	v_add_f32_e32 v217, v217, v225
	v_add_f32_e32 v218, v218, v226
	v_add_f32_e32 v219, v219, v227
	v_add_f32_e32 v220, v220, v228
	v_add_f32_e32 v221, v221, v229
	v_add_f32_e32 v222, v222, v230
	v_add_f32_e32 v223, v223, v231
	s_nop 1
	v_permlane16_swap_b32_e32 v216, v220
	v_permlane16_swap_b32_e32 v217, v221
	v_permlane16_swap_b32_e32 v218, v222
	v_permlane16_swap_b32_e32 v219, v223
	v_add_f32_e32 v216, v216, v220
	v_add_f32_e32 v217, v217, v221
	v_add_f32_e32 v218, v218, v222
	v_add_f32_e32 v219, v219, v223
	v_cvt_pk_bf16_f32 v232, v216, v217
	v_cvt_pk_bf16_f32 v233, v218, v219
	global_store_dwordx2 v214, v[232:233], s[14:15]
	s_add_i32 s48, s48, 1
	s_add_i32 s34, s34, 4
	s_cmp_lt_u32 s48, s49
	s_cbranch_scc0 .Lp11_chunk_done
	s_cmp_lt_u32 s34, 8192
	s_cbranch_scc1 .Lp11_body
	s_branch .Lp11_slice_next

; DI unsigned xb_xcc_id() { return (unsigned)__builtin_amdgcn_s_getreg((3 << 11) | 20) & 0xFu; }
; template <class F>
; DI void xcd_queue(unsigned* ctrs, int nchunks, char* smem, F&& f) {
;   const int x0 = (int)(xb_xcc_id() & 7u);
; #pragma unroll 1
;   for (int k = 0; k < 8; ++k) {
;     const int s = (x0 + k) & 7;
;     for (;;) { const int c = grab(ctrs + 64 * s, smem); if (c >= nchunks) break; f(s, c); }
;   }
; }
.Lp11_peek:
	global_load_dword v242, v241, s[16:17] sc1
	s_waitcnt vmcnt(0)
	s_mov_b32 s52, 1
	s_mov_b32 s18, 0
	s_branch .Lp11_slice
.Lp11_slice_next:
	s_add_i32 s18, s18, 1
	s_cmp_lt_u32 s18, 8
	s_cbranch_scc1 .Lp11_slice
	s_branch .LBB0_1265
.LBB0_1265:
	s_cmp_gt_i32 s38, 12
	s_cselect_b64 s[2:3], -1, 0
	s_cmp_lt_i32 s39, 13
	s_cselect_b64 s[4:5], -1, 0
	s_or_b64 s[2:3], s[2:3], s[4:5]
	s_and_b64 vcc, exec, s[2:3]
	s_cbranch_vccnz .LBB0_1326
	s_andn2_b64 vcc, exec, s[36:37]
	s_cbranch_vccnz .LBB0_1268
	s_cbranch_execz .LBB0_1269
	s_branch .LBB0_1323
